# peeled first K-iteration with C=0 MFMAs; per-tile accumulator zeroing removed
# speedup vs baseline: 1.0097x; 1.0097x over previous
; #define PG8_STAGE(bufoff, gbase, voff) do { _Pragma("unroll") for (int _i = 0; _i < 2; ++_i) \
;         __builtin_amdgcn_global_load_lds((const unsigned*)((const char*)(gbase) + (voff)[_i]), (PG8_LAS unsigned*)(lds + (bufoff) + ldsw + _i * 8192), 16, 0, 0); } while (0)
; #define PG8_LDA(dst, b, h) do { _Pragma("unroll") for (int m = 0; m < 4; ++m) _Pragma("unroll") for (int k = 0; k < 2; ++k) dst[m][k] = *(const PG8_LAS bf16x8*)(lds + PG8_SA(b, h) + aoff + m * 2048 + k * 1024); } while (0)
; #define PG8_LDB(dst, b, h) do { _Pragma("unroll") for (int n = 0; n < 2; ++n) _Pragma("unroll") for (int k = 0; k < 2; ++k) dst[n][k] = *(const PG8_LAS bf16x8*)(lds + PG8_SB(b, h) + boff + n * 2048 + k * 1024); } while (0)
; #define PG8_WAIT_V(n) asm volatile("s_waitcnt vmcnt(" #n ")" ::: "memory")
; #define PG8_WAIT_L(n) asm volatile("s_waitcnt lgkmcnt(" #n ")" ::: "memory")
; #define PG8_BAR __builtin_amdgcn_s_barrier()
; #define PG8_SCHED __builtin_amdgcn_sched_barrier(0)
; template <class Epi, class Sched, bool ALIGN_EPI = false, bool SP2 = false>
; __device__ __forceinline__ void gemm_phase(PG8_LAS unsigned char* lds, const Gemm g, const Sched& S, const Epi& E, const int tid) {
;     ...
;         const bool has_next = S.next(ui + 1, nxt);
;         const char* nA = has_next ? S.aptr(nxt) : cA; const char* nB = has_next ? S.bptr(nxt) : cB;
;         for (int t = 0; t < nt; t += 2) {
;             const bool last = (t == nt - 2);
;             const char* a1 = cA + (size_t)(t + 1) * kstep;
;             const char* a2 = last ? nA : cA + (size_t)(t + 2) * kstep; const char* b2 = last ? nB : cB + (size_t)(t + 2) * kstep;
;             const char* a3 = a2 + kstep; const char* b3 = b2 + kstep;
;             if (last && has_next) S.a_ready(nxt);
;             if constexpr (SP2) {
;             PG8_LDB(B0, 0, 0); PG8_LDB(B1, 0, 1); PG8_SCHED; PG8_LDA(At, 0, 0); PG8_STAGE(PG8_SA(1, 1), a1 + hstep, voffA);
;             PG8_WAIT_V(8); PG8_WAIT_L(0); PG8_BAR; PG8_MMA(0, 0, At, B0); PG8_MMA(0, 1, At, B1); PG8_BAR; PG8_SCHED;
;             PG8_LDA(At, 0, 1); PG8_STAGE(PG8_SB(0, 0), b2, voffB); PG8_STAGE(PG8_SB(0, 1), b2 + hstep, voffB); PG8_STAGE(PG8_SA(0, 0), a2, voffA);
;             PG8_WAIT_V(8); PG8_WAIT_L(0); PG8_BAR; PG8_MMA(1, 0, At, B0); PG8_MMA(1, 1, At, B1); PG8_BAR; PG8_SCHED;
.LBB0_338:
	s_ashr_i32 s29, s28, 31
	s_lshl_b64 s[18:19], s[28:29], 19
	s_add_u32 s30, s46, s18
	s_addc_u32 s31, s47, s19
	s_and_b64 s[18:19], s[2:3], exec
	s_cselect_b32 s29, s31, s41
	s_cselect_b32 s62, s30, s40
	s_ashr_i32 s27, s26, 31
	s_lshl_b64 s[18:19], s[26:27], 19
	s_add_u32 s34, s48, s18
	s_addc_u32 s35, s49, s19
	s_and_b64 s[18:19], s[2:3], exec
	s_cselect_b32 s27, s35, s39
	s_cselect_b32 s63, s34, s38
	s_add_u32 s64, s38, 0x100
	s_addc_u32 s65, s39, 0
	s_add_u32 s38, s40, 0x40080
	s_addc_u32 s39, s41, 0
	s_mov_b32 s66, -2
	ds_read_b128 v[150:153], v161
	ds_read_b128 v[172:175], v161 offset:1024
	ds_read_b128 v[176:179], v161 offset:2048
	ds_read_b128 v[180:183], v161 offset:3072
	ds_read_b128 v[184:187], v163
	ds_read_b128 v[192:195], v163 offset:1024
	ds_read_b128 v[196:199], v163 offset:2048
	ds_read_b128 v[200:203], v163 offset:3072
	s_add_u32 s15, s38, 0xfffc0080
	s_addc_u32 s18, s39, -1
	s_cmp_eq_u32 s66, 12
	s_cselect_b32 s43, s29, s18
	s_cselect_b32 s42, s62, s15
	s_cselect_b32 s41, s27, s65
	s_cselect_b32 s40, s63, s64
	v_lshl_add_u64 v[154:155], s[38:39], 0, v[144:145]
	s_add_i32 m0, s51, 0xc000
	ds_read_b128 v[204:207], v167
	ds_read_b128 v[208:211], v167 offset:1024
	ds_read_b128 v[212:215], v167 offset:2048
	ds_read_b128 v[216:219], v167 offset:3072
	ds_read_b128 v[220:223], v167 offset:4096
	ds_read_b128 v[224:227], v167 offset:5120
	ds_read_b128 v[228:231], v167 offset:6144
	ds_read_b128 v[232:235], v167 offset:7168
	global_load_lds_dwordx4 v[154:155], off
	v_lshl_add_u64 v[154:155], s[38:39], 0, v[142:143]
	s_add_i32 m0, s51, 0xe000
	s_nop 0
	global_load_lds_dwordx4 v[154:155], off
	s_waitcnt vmcnt(8)
	s_waitcnt lgkmcnt(0)
	s_barrier
	s_setprio 1
	s_waitcnt lgkmcnt(0)
	v_mfma_f32_16x16x32_bf16 v[126:129], v[150:153], v[204:207], 0
	v_mfma_f32_16x16x32_bf16 v[122:125], v[176:179], v[204:207], 0
	v_mfma_f32_16x16x32_bf16 v[110:113], v[150:153], v[212:215], 0
	v_mfma_f32_16x16x32_bf16 v[106:109], v[176:179], v[212:215], 0
	v_mfma_f32_16x16x32_bf16 v[94:97], v[150:153], v[220:223], 0
	v_mfma_f32_16x16x32_bf16 v[90:93], v[176:179], v[220:223], 0
	v_mfma_f32_16x16x32_bf16 v[78:81], v[150:153], v[228:231], 0
	v_mfma_f32_16x16x32_bf16 v[74:77], v[176:179], v[228:231], 0
	v_mfma_f32_16x16x32_bf16 v[126:129], v[172:175], v[208:211], v[126:129]
	v_mfma_f32_16x16x32_bf16 v[122:125], v[180:183], v[208:211], v[122:125]
	v_mfma_f32_16x16x32_bf16 v[110:113], v[172:175], v[216:219], v[110:113]
	v_mfma_f32_16x16x32_bf16 v[106:109], v[180:183], v[216:219], v[106:109]
	v_mfma_f32_16x16x32_bf16 v[94:97], v[172:175], v[224:227], v[94:97]
	v_mfma_f32_16x16x32_bf16 v[90:93], v[180:183], v[224:227], v[90:93]
	v_mfma_f32_16x16x32_bf16 v[78:81], v[172:175], v[232:235], v[78:81]
	v_mfma_f32_16x16x32_bf16 v[74:77], v[180:183], v[232:235], v[74:77]
	s_setprio 0
	s_setprio 1
	v_mfma_f32_16x16x32_bf16 v[118:121], v[184:187], v[204:207], 0
	v_mfma_f32_16x16x32_bf16 v[114:117], v[196:199], v[204:207], 0
	v_mfma_f32_16x16x32_bf16 v[102:105], v[184:187], v[212:215], 0
	v_mfma_f32_16x16x32_bf16 v[98:101], v[196:199], v[212:215], 0
	v_mfma_f32_16x16x32_bf16 v[86:89], v[184:187], v[220:223], 0
	v_mfma_f32_16x16x32_bf16 v[82:85], v[196:199], v[220:223], 0
	v_mfma_f32_16x16x32_bf16 v[70:73], v[184:187], v[228:231], 0
	v_mfma_f32_16x16x32_bf16 v[66:69], v[196:199], v[228:231], 0
	v_mfma_f32_16x16x32_bf16 v[118:121], v[192:195], v[208:211], v[118:121]
	v_mfma_f32_16x16x32_bf16 v[114:117], v[200:203], v[208:211], v[114:117]
	v_mfma_f32_16x16x32_bf16 v[102:105], v[192:195], v[216:219], v[102:105]
	v_mfma_f32_16x16x32_bf16 v[98:101], v[200:203], v[216:219], v[98:101]
	v_mfma_f32_16x16x32_bf16 v[86:89], v[192:195], v[224:227], v[86:89]
	v_mfma_f32_16x16x32_bf16 v[82:85], v[200:203], v[224:227], v[82:85]
	v_mfma_f32_16x16x32_bf16 v[70:73], v[192:195], v[232:235], v[70:73]
	v_mfma_f32_16x16x32_bf16 v[66:69], v[200:203], v[232:235], v[66:69]
	s_setprio 0
	s_barrier
	s_add_i32 s15, s58, s50
	v_lshl_add_u64 v[154:155], s[40:41], 0, v[132:133]
	s_mov_b32 m0, s15
	ds_read_b128 v[204:207], v167 offset:16384
	ds_read_b128 v[208:211], v167 offset:17408
	ds_read_b128 v[212:215], v167 offset:18432
	ds_read_b128 v[216:219], v167 offset:19456
	ds_read_b128 v[220:223], v167 offset:20480
	ds_read_b128 v[224:227], v167 offset:21504
	ds_read_b128 v[228:231], v167 offset:22528
	ds_read_b128 v[232:235], v167 offset:23552
	global_load_lds_dwordx4 v[154:155], off
	s_add_i32 m0, s15, 0x2000
	s_add_u32 s18, s40, 0x40000
	v_lshl_add_u64 v[158:159], s[40:41], 0, v[136:137]
	s_addc_u32 s19, s41, 0
	s_add_i32 s15, s59, s50
	global_load_lds_dwordx4 v[158:159], off
	v_lshl_add_u64 v[164:165], s[18:19], 0, v[132:133]
	s_mov_b32 m0, s15
	v_lshl_add_u64 v[168:169], s[42:43], 0, v[134:135]
	global_load_lds_dwordx4 v[164:165], off
	v_lshl_add_u64 v[164:165], s[18:19], 0, v[136:137]
	s_add_i32 m0, s15, 0x2000
	s_nop 0
	global_load_lds_dwordx4 v[164:165], off
	v_lshl_add_u64 v[164:165], s[42:43], 0, v[130:131]
	s_mov_b32 m0, s51
	s_nop 0
	global_load_lds_dwordx4 v[164:165], off
	s_mov_b32 m0, s52
	s_nop 0
	global_load_lds_dwordx4 v[168:169], off
	s_waitcnt vmcnt(8)
	s_waitcnt lgkmcnt(0)
	s_barrier
; #define PG8_STAGE(bufoff, gbase, voff) do { _Pragma("unroll") for (int _i = 0; _i < 2; ++_i) \
;         __builtin_amdgcn_global_load_lds((const unsigned*)((const char*)(gbase) + (voff)[_i]), (PG8_LAS unsigned*)(lds + (bufoff) + ldsw + _i * 8192), 16, 0, 0); } while (0)
; #define PG8_LDA(dst, b, h) do { _Pragma("unroll") for (int m = 0; m < 4; ++m) _Pragma("unroll") for (int k = 0; k < 2; ++k) dst[m][k] = *(const PG8_LAS bf16x8*)(lds + PG8_SA(b, h) + aoff + m * 2048 + k * 1024); } while (0)
; #define PG8_LDB(dst, b, h) do { _Pragma("unroll") for (int n = 0; n < 2; ++n) _Pragma("unroll") for (int k = 0; k < 2; ++k) dst[n][k] = *(const PG8_LAS bf16x8*)(lds + PG8_SB(b, h) + boff + n * 2048 + k * 1024); } while (0)
; #define PG8_MMA(ai, bj, At, Bt) do { __builtin_amdgcn_s_setprio(1); _Pragma("unroll") for (int m = 0; m < 4; ++m) _Pragma("unroll") for (int n = 0; n < 2; ++n) _Pragma("unroll") for (int k = 0; k < 2; ++k) \
;         acc[ai][bj][m][n] = __builtin_amdgcn_mfma_f32_16x16x32_bf16(Bt[n][k], At[m][k], acc[ai][bj][m][n], 0, 0, 0); __builtin_amdgcn_s_setprio(0); } while (0)
; #define PG8_WAIT_V(n) asm volatile("s_waitcnt vmcnt(" #n ")" ::: "memory")
; #define PG8_WAIT_L(n) asm volatile("s_waitcnt lgkmcnt(" #n ")" ::: "memory")
; #define PG8_BAR __builtin_amdgcn_s_barrier()
; #define PG8_SCHED __builtin_amdgcn_sched_barrier(0)
; template <class Epi, class Sched, bool ALIGN_EPI = false, bool SP2 = false>
; __device__ __forceinline__ void gemm_phase(PG8_LAS unsigned char* lds, const Gemm g, const Sched& S, const Epi& E, const int tid) {
;     ...
;             PG8_WAIT_V(8); PG8_WAIT_L(0); PG8_BAR; PG8_MMA(1, 0, At, B0); PG8_MMA(1, 1, At, B1); PG8_BAR; PG8_SCHED;
;             PG8_LDB(B0, 1, 0); PG8_LDB(B1, 1, 1); PG8_SCHED; PG8_LDA(At, 1, 0); PG8_STAGE(PG8_SA(0, 1), a2 + hstep, voffA);
;             PG8_WAIT_V(8); PG8_WAIT_L(0); PG8_BAR; PG8_MMA(0, 0, At, B0); PG8_MMA(0, 1, At, B1); PG8_BAR; PG8_SCHED;
	s_setprio 1
	s_waitcnt lgkmcnt(0)
	v_mfma_f32_16x16x32_bf16 v[62:65], v[150:153], v[204:207], 0
	v_mfma_f32_16x16x32_bf16 v[58:61], v[176:179], v[204:207], 0
	v_mfma_f32_16x16x32_bf16 v[46:49], v[150:153], v[212:215], 0
	v_mfma_f32_16x16x32_bf16 v[42:45], v[176:179], v[212:215], 0
	v_mfma_f32_16x16x32_bf16 v[30:33], v[150:153], v[220:223], 0
	v_mfma_f32_16x16x32_bf16 v[26:29], v[176:179], v[220:223], 0
	v_mfma_f32_16x16x32_bf16 v[14:17], v[150:153], v[228:231], 0
	v_mfma_f32_16x16x32_bf16 v[10:13], v[176:179], v[228:231], 0
	v_mfma_f32_16x16x32_bf16 v[62:65], v[172:175], v[208:211], v[62:65]
	v_mfma_f32_16x16x32_bf16 v[58:61], v[180:183], v[208:211], v[58:61]
	v_mfma_f32_16x16x32_bf16 v[46:49], v[172:175], v[216:219], v[46:49]
	v_mfma_f32_16x16x32_bf16 v[42:45], v[180:183], v[216:219], v[42:45]
	v_mfma_f32_16x16x32_bf16 v[30:33], v[172:175], v[224:227], v[30:33]
	v_mfma_f32_16x16x32_bf16 v[26:29], v[180:183], v[224:227], v[26:29]
	v_mfma_f32_16x16x32_bf16 v[14:17], v[172:175], v[232:235], v[14:17]
	v_mfma_f32_16x16x32_bf16 v[10:13], v[180:183], v[232:235], v[10:13]
	s_setprio 0
	s_setprio 1
	v_mfma_f32_16x16x32_bf16 v[54:57], v[184:187], v[204:207], 0
	v_mfma_f32_16x16x32_bf16 v[50:53], v[196:199], v[204:207], 0
	v_mfma_f32_16x16x32_bf16 v[38:41], v[184:187], v[212:215], 0
	v_mfma_f32_16x16x32_bf16 v[34:37], v[196:199], v[212:215], 0
	v_mfma_f32_16x16x32_bf16 v[22:25], v[184:187], v[220:223], 0
	v_mfma_f32_16x16x32_bf16 v[18:21], v[196:199], v[220:223], 0
	v_mfma_f32_16x16x32_bf16 v[6:9], v[184:187], v[228:231], 0
	v_mfma_f32_16x16x32_bf16 v[2:5], v[196:199], v[228:231], 0
	v_mfma_f32_16x16x32_bf16 v[54:57], v[192:195], v[208:211], v[54:57]
	v_mfma_f32_16x16x32_bf16 v[50:53], v[200:203], v[208:211], v[50:53]
	v_mfma_f32_16x16x32_bf16 v[38:41], v[192:195], v[216:219], v[38:41]
	v_mfma_f32_16x16x32_bf16 v[34:37], v[200:203], v[216:219], v[34:37]
	v_mfma_f32_16x16x32_bf16 v[22:25], v[192:195], v[224:227], v[22:25]
	v_mfma_f32_16x16x32_bf16 v[18:21], v[200:203], v[224:227], v[18:21]
	v_mfma_f32_16x16x32_bf16 v[6:9], v[192:195], v[232:235], v[6:9]
	v_mfma_f32_16x16x32_bf16 v[2:5], v[200:203], v[232:235], v[2:5]
	s_setprio 0
	s_barrier
	s_add_i32 s15, 0, 0x18000
	v_add_u32_e32 v156, s15, v157
	s_add_i32 s67, 0, 0x1c000
	ds_read_b128 v[150:153], v156
	ds_read_b128 v[172:175], v156 offset:1024
	ds_read_b128 v[176:179], v156 offset:2048
	ds_read_b128 v[180:183], v156 offset:3072
	v_add_u32_e32 v156, s67, v157
	ds_read_b128 v[184:187], v156
	ds_read_b128 v[192:195], v156 offset:1024
	ds_read_b128 v[196:199], v156 offset:2048
	ds_read_b128 v[200:203], v156 offset:3072
	s_add_u32 s18, s42, 0x40000
	s_addc_u32 s19, s43, 0
	s_mov_b32 m0, s53
	v_lshl_add_u64 v[188:189], s[18:19], 0, v[130:131]
	ds_read_b128 v[204:207], v167 offset:32768
	ds_read_b128 v[208:211], v167 offset:33792
	ds_read_b128 v[212:215], v167 offset:34816
	ds_read_b128 v[216:219], v167 offset:35840
	ds_read_b128 v[220:223], v167 offset:36864
	ds_read_b128 v[224:227], v167 offset:37888
	ds_read_b128 v[228:231], v167 offset:38912
	ds_read_b128 v[232:235], v167 offset:39936
	global_load_lds_dwordx4 v[188:189], off
	v_lshl_add_u64 v[188:189], s[18:19], 0, v[134:135]
	s_mov_b32 m0, s54
	s_nop 0
	global_load_lds_dwordx4 v[188:189], off
	s_waitcnt vmcnt(8)
	s_waitcnt lgkmcnt(0)
	s_barrier
	s_setprio 1
	s_waitcnt lgkmcnt(0)
	v_mfma_f32_16x16x32_bf16 v[126:129], v[150:153], v[204:207], v[126:129]
	v_mfma_f32_16x16x32_bf16 v[122:125], v[176:179], v[204:207], v[122:125]
	v_mfma_f32_16x16x32_bf16 v[110:113], v[150:153], v[212:215], v[110:113]
	v_mfma_f32_16x16x32_bf16 v[106:109], v[176:179], v[212:215], v[106:109]
	v_mfma_f32_16x16x32_bf16 v[94:97], v[150:153], v[220:223], v[94:97]
	v_mfma_f32_16x16x32_bf16 v[90:93], v[176:179], v[220:223], v[90:93]
	v_mfma_f32_16x16x32_bf16 v[78:81], v[150:153], v[228:231], v[78:81]
	v_mfma_f32_16x16x32_bf16 v[74:77], v[176:179], v[228:231], v[74:77]
	v_mfma_f32_16x16x32_bf16 v[126:129], v[172:175], v[208:211], v[126:129]
	v_mfma_f32_16x16x32_bf16 v[122:125], v[180:183], v[208:211], v[122:125]
	v_mfma_f32_16x16x32_bf16 v[110:113], v[172:175], v[216:219], v[110:113]
	v_mfma_f32_16x16x32_bf16 v[106:109], v[180:183], v[216:219], v[106:109]
	v_mfma_f32_16x16x32_bf16 v[94:97], v[172:175], v[224:227], v[94:97]
	v_mfma_f32_16x16x32_bf16 v[90:93], v[180:183], v[224:227], v[90:93]
	v_mfma_f32_16x16x32_bf16 v[78:81], v[172:175], v[232:235], v[78:81]
	v_mfma_f32_16x16x32_bf16 v[74:77], v[180:183], v[232:235], v[74:77]
	s_setprio 0
	s_setprio 1
	v_mfma_f32_16x16x32_bf16 v[118:121], v[184:187], v[204:207], v[118:121]
	v_mfma_f32_16x16x32_bf16 v[114:117], v[196:199], v[204:207], v[114:117]
	v_mfma_f32_16x16x32_bf16 v[102:105], v[184:187], v[212:215], v[102:105]
	v_mfma_f32_16x16x32_bf16 v[98:101], v[196:199], v[212:215], v[98:101]
	v_mfma_f32_16x16x32_bf16 v[86:89], v[184:187], v[220:223], v[86:89]
	v_mfma_f32_16x16x32_bf16 v[82:85], v[196:199], v[220:223], v[82:85]
	v_mfma_f32_16x16x32_bf16 v[70:73], v[184:187], v[228:231], v[70:73]
	v_mfma_f32_16x16x32_bf16 v[66:69], v[196:199], v[228:231], v[66:69]
	v_mfma_f32_16x16x32_bf16 v[118:121], v[192:195], v[208:211], v[118:121]
	v_mfma_f32_16x16x32_bf16 v[114:117], v[200:203], v[208:211], v[114:117]
	v_mfma_f32_16x16x32_bf16 v[102:105], v[192:195], v[216:219], v[102:105]
	v_mfma_f32_16x16x32_bf16 v[98:101], v[200:203], v[216:219], v[98:101]
	v_mfma_f32_16x16x32_bf16 v[86:89], v[192:195], v[224:227], v[86:89]
	v_mfma_f32_16x16x32_bf16 v[82:85], v[200:203], v[224:227], v[82:85]
	v_mfma_f32_16x16x32_bf16 v[70:73], v[192:195], v[232:235], v[70:73]
	v_mfma_f32_16x16x32_bf16 v[66:69], v[200:203], v[232:235], v[66:69]
	s_setprio 0
	s_barrier
; #define PG8_STAGE(bufoff, gbase, voff) do { _Pragma("unroll") for (int _i = 0; _i < 2; ++_i) \
;         __builtin_amdgcn_global_load_lds((const unsigned*)((const char*)(gbase) + (voff)[_i]), (PG8_LAS unsigned*)(lds + (bufoff) + ldsw + _i * 8192), 16, 0, 0); } while (0)
; #define PG8_LDA(dst, b, h) do { _Pragma("unroll") for (int m = 0; m < 4; ++m) _Pragma("unroll") for (int k = 0; k < 2; ++k) dst[m][k] = *(const PG8_LAS bf16x8*)(lds + PG8_SA(b, h) + aoff + m * 2048 + k * 1024); } while (0)
; #define PG8_MMA(ai, bj, At, Bt) do { __builtin_amdgcn_s_setprio(1); _Pragma("unroll") for (int m = 0; m < 4; ++m) _Pragma("unroll") for (int n = 0; n < 2; ++n) _Pragma("unroll") for (int k = 0; k < 2; ++k) \
;         acc[ai][bj][m][n] = __builtin_amdgcn_mfma_f32_16x16x32_bf16(Bt[n][k], At[m][k], acc[ai][bj][m][n], 0, 0, 0); __builtin_amdgcn_s_setprio(0); } while (0)
; #define PG8_WAIT_V(n) asm volatile("s_waitcnt vmcnt(" #n ")" ::: "memory")
; #define PG8_WAIT_L(n) asm volatile("s_waitcnt lgkmcnt(" #n ")" ::: "memory")
; #define PG8_BAR __builtin_amdgcn_s_barrier()
; #define PG8_SCHED __builtin_amdgcn_sched_barrier(0)
; template <class Epi, class Sched, bool ALIGN_EPI = false, bool SP2 = false>
; __device__ __forceinline__ void gemm_phase(PG8_LAS unsigned char* lds, const Gemm g, const Sched& S, const Epi& E, const int tid) {
;     ...
;         for (int t = 0; t < nt; t += 2) {
;             const bool last = (t == nt - 2);
;             const char* a1 = cA + (size_t)(t + 1) * kstep;
;             const char* a2 = last ? nA : cA + (size_t)(t + 2) * kstep; const char* b2 = last ? nB : cB + (size_t)(t + 2) * kstep;
;             const char* a3 = a2 + kstep; const char* b3 = b2 + kstep;
;     ...
;             PG8_LDA(At, 1, 1); PG8_STAGE(PG8_SB(1, 0), b3, voffB); PG8_STAGE(PG8_SB(1, 1), b3 + hstep, voffB); PG8_STAGE(PG8_SA(1, 0), a3, voffA);
;             PG8_WAIT_V(8); PG8_WAIT_L(0); PG8_BAR; PG8_MMA(1, 0, At, B0); PG8_MMA(1, 1, At, B1); PG8_BAR; PG8_SCHED;
	s_add_i32 s15, s15, s50
	v_lshl_add_u64 v[154:155], v[154:155], 0, s[8:9]
	s_mov_b32 m0, s15
	ds_read_b128 v[204:207], v167 offset:49152
	ds_read_b128 v[208:211], v167 offset:50176
	ds_read_b128 v[212:215], v167 offset:51200
	ds_read_b128 v[216:219], v167 offset:52224
	ds_read_b128 v[220:223], v167 offset:53248
	ds_read_b128 v[224:227], v167 offset:54272
	ds_read_b128 v[228:231], v167 offset:55296
	ds_read_b128 v[232:235], v167 offset:56320
	global_load_lds_dwordx4 v[154:155], off
	s_add_i32 m0, s15, 0x2000
	s_add_u32 s18, s40, 0x40080
	v_lshl_add_u64 v[154:155], v[158:159], 0, s[8:9]
	s_addc_u32 s19, s41, 0
	s_add_i32 s15, s67, s50
	global_load_lds_dwordx4 v[154:155], off
	v_lshl_add_u64 v[154:155], s[18:19], 0, v[132:133]
	s_mov_b32 m0, s15
	s_nop 0
	global_load_lds_dwordx4 v[154:155], off
	v_lshl_add_u64 v[154:155], s[18:19], 0, v[136:137]
	s_add_i32 m0, s15, 0x2000
	s_nop 0
	global_load_lds_dwordx4 v[154:155], off
	v_lshl_add_u64 v[154:155], v[164:165], 0, s[8:9]
	s_mov_b32 m0, s55
	s_nop 0
	global_load_lds_dwordx4 v[154:155], off
	v_lshl_add_u64 v[154:155], v[168:169], 0, s[8:9]
	s_mov_b32 m0, s56
	s_nop 0
	global_load_lds_dwordx4 v[154:155], off
	s_waitcnt vmcnt(8)
	s_waitcnt lgkmcnt(0)
	s_barrier
	s_setprio 1
	s_waitcnt lgkmcnt(0)
	v_mfma_f32_16x16x32_bf16 v[62:65], v[150:153], v[204:207], v[62:65]
	v_mfma_f32_16x16x32_bf16 v[58:61], v[176:179], v[204:207], v[58:61]
	v_mfma_f32_16x16x32_bf16 v[46:49], v[150:153], v[212:215], v[46:49]
	v_mfma_f32_16x16x32_bf16 v[42:45], v[176:179], v[212:215], v[42:45]
	v_mfma_f32_16x16x32_bf16 v[30:33], v[150:153], v[220:223], v[30:33]
	v_mfma_f32_16x16x32_bf16 v[26:29], v[176:179], v[220:223], v[26:29]
	v_mfma_f32_16x16x32_bf16 v[14:17], v[150:153], v[228:231], v[14:17]
	v_mfma_f32_16x16x32_bf16 v[10:13], v[176:179], v[228:231], v[10:13]
	v_mfma_f32_16x16x32_bf16 v[62:65], v[172:175], v[208:211], v[62:65]
	v_mfma_f32_16x16x32_bf16 v[58:61], v[180:183], v[208:211], v[58:61]
	v_mfma_f32_16x16x32_bf16 v[46:49], v[172:175], v[216:219], v[46:49]
	v_mfma_f32_16x16x32_bf16 v[42:45], v[180:183], v[216:219], v[42:45]
	v_mfma_f32_16x16x32_bf16 v[30:33], v[172:175], v[224:227], v[30:33]
	v_mfma_f32_16x16x32_bf16 v[26:29], v[180:183], v[224:227], v[26:29]
	v_mfma_f32_16x16x32_bf16 v[14:17], v[172:175], v[232:235], v[14:17]
	v_mfma_f32_16x16x32_bf16 v[10:13], v[180:183], v[232:235], v[10:13]
	s_setprio 0
	s_setprio 1
	v_mfma_f32_16x16x32_bf16 v[54:57], v[184:187], v[204:207], v[54:57]
	v_mfma_f32_16x16x32_bf16 v[50:53], v[196:199], v[204:207], v[50:53]
	v_mfma_f32_16x16x32_bf16 v[38:41], v[184:187], v[212:215], v[38:41]
	v_mfma_f32_16x16x32_bf16 v[34:37], v[196:199], v[212:215], v[34:37]
	v_mfma_f32_16x16x32_bf16 v[22:25], v[184:187], v[220:223], v[22:25]
	v_mfma_f32_16x16x32_bf16 v[18:21], v[196:199], v[220:223], v[18:21]
	v_mfma_f32_16x16x32_bf16 v[6:9], v[184:187], v[228:231], v[6:9]
	v_mfma_f32_16x16x32_bf16 v[2:5], v[196:199], v[228:231], v[2:5]
	v_mfma_f32_16x16x32_bf16 v[54:57], v[192:195], v[208:211], v[54:57]
	v_mfma_f32_16x16x32_bf16 v[50:53], v[200:203], v[208:211], v[50:53]
	v_mfma_f32_16x16x32_bf16 v[38:41], v[192:195], v[216:219], v[38:41]
	v_mfma_f32_16x16x32_bf16 v[34:37], v[200:203], v[216:219], v[34:37]
	v_mfma_f32_16x16x32_bf16 v[22:25], v[192:195], v[224:227], v[22:25]
	v_mfma_f32_16x16x32_bf16 v[18:21], v[200:203], v[224:227], v[18:21]
	v_mfma_f32_16x16x32_bf16 v[6:9], v[192:195], v[232:235], v[6:9]
	v_mfma_f32_16x16x32_bf16 v[2:5], v[200:203], v[232:235], v[2:5]
	s_setprio 0
	s_barrier
	s_add_i32 s66, s66, 2
	s_add_u32 s64, s64, 0x100
	s_addc_u32 s65, s65, 0
	s_add_u32 s38, s38, 0x100
	s_addc_u32 s39, s39, 0

; #define PG8_STAGE(bufoff, gbase, voff) do { _Pragma("unroll") for (int _i = 0; _i < 2; ++_i) \
;         __builtin_amdgcn_global_load_lds((const unsigned*)((const char*)(gbase) + (voff)[_i]), (PG8_LAS unsigned*)(lds + (bufoff) + ldsw + _i * 8192), 16, 0, 0); } while (0)
; #define PG8_LDA(dst, b, h) do { _Pragma("unroll") for (int m = 0; m < 4; ++m) _Pragma("unroll") for (int k = 0; k < 2; ++k) dst[m][k] = *(const PG8_LAS bf16x8*)(lds + PG8_SA(b, h) + aoff + m * 2048 + k * 1024); } while (0)
; #define PG8_LDB(dst, b, h) do { _Pragma("unroll") for (int n = 0; n < 2; ++n) _Pragma("unroll") for (int k = 0; k < 2; ++k) dst[n][k] = *(const PG8_LAS bf16x8*)(lds + PG8_SB(b, h) + boff + n * 2048 + k * 1024); } while (0)
; #define PG8_WAIT_V(n) asm volatile("s_waitcnt vmcnt(" #n ")" ::: "memory")
; #define PG8_WAIT_L(n) asm volatile("s_waitcnt lgkmcnt(" #n ")" ::: "memory")
; #define PG8_BAR __builtin_amdgcn_s_barrier()
; #define PG8_SCHED __builtin_amdgcn_sched_barrier(0)
; template <class Epi, class Sched, bool ALIGN_EPI = false, bool SP2 = false>
; __device__ __forceinline__ void gemm_phase(PG8_LAS unsigned char* lds, const Gemm g, const Sched& S, const Epi& E, const int tid) {
;     ...
;         const bool has_next = S.next(ui + 1, nxt);
;         const char* nA = has_next ? S.aptr(nxt) : cA; const char* nB = has_next ? S.bptr(nxt) : cB;
;         for (int t = 0; t < nt; t += 2) {
;             const bool last = (t == nt - 2);
;             const char* a1 = cA + (size_t)(t + 1) * kstep;
;             const char* a2 = last ? nA : cA + (size_t)(t + 2) * kstep; const char* b2 = last ? nB : cB + (size_t)(t + 2) * kstep;
;             const char* a3 = a2 + kstep; const char* b3 = b2 + kstep;
;             if (last && has_next) S.a_ready(nxt);
;             if constexpr (SP2) {
;             PG8_LDB(B0, 0, 0); PG8_LDB(B1, 0, 1); PG8_SCHED; PG8_LDA(At, 0, 0); PG8_STAGE(PG8_SA(1, 1), a1 + hstep, voffA);
;             PG8_WAIT_V(8); PG8_WAIT_L(0); PG8_BAR; PG8_MMA(0, 0, At, B0); PG8_MMA(0, 1, At, B1); PG8_BAR; PG8_SCHED;
;             PG8_LDA(At, 0, 1); PG8_STAGE(PG8_SB(0, 0), b2, voffB); PG8_STAGE(PG8_SB(0, 1), b2 + hstep, voffB); PG8_STAGE(PG8_SA(0, 0), a2, voffA);
;             PG8_WAIT_V(8); PG8_WAIT_L(0); PG8_BAR; PG8_MMA(1, 0, At, B0); PG8_MMA(1, 1, At, B1); PG8_BAR; PG8_SCHED;
.LBB0_422:
	s_add_u32 s45, s8, 0x100
	s_addc_u32 s47, s9, 0
	s_mov_b32 s77, -2
	ds_read_b128 v[130:133], v205
	ds_read_b128 v[134:137], v205 offset:1024
	ds_read_b128 v[138:141], v205 offset:2048
	ds_read_b128 v[142:145], v205 offset:3072
	ds_read_b128 v[146:149], v206
	ds_read_b128 v[150:153], v206 offset:1024
	ds_read_b128 v[154:157], v206 offset:2048
	ds_read_b128 v[158:161], v206 offset:3072
	s_add_u32 s8, s6, 0x100
	s_addc_u32 s9, s7, 0
	s_cmp_eq_u32 s77, 40
	s_cselect_b32 s43, s1, s9
	s_cselect_b32 s42, s0, s8
	s_cselect_b32 s11, s41, s47
	s_cselect_b32 s10, s40, s45
	v_lshl_add_u64 v[220:221], s[6:7], 0, v[176:177]
	s_add_i32 m0, s56, 0xc000
	ds_read_b128 v[182:185], v207
	ds_read_b128 v[186:189], v207 offset:1024
	ds_read_b128 v[192:195], v207 offset:2048
	ds_read_b128 v[196:199], v207 offset:3072
	ds_read_b128 v[200:203], v207 offset:4096
	ds_read_b128 v[208:211], v207 offset:5120
	ds_read_b128 v[212:215], v207 offset:6144
	ds_read_b128 v[216:219], v207 offset:7168
	global_load_lds_dwordx4 v[220:221], off
	v_lshl_add_u64 v[220:221], s[6:7], 0, v[174:175]
	s_add_i32 m0, s56, 0xe000
	s_nop 0
	global_load_lds_dwordx4 v[220:221], off
	s_waitcnt vmcnt(8)
	s_waitcnt lgkmcnt(0)
	s_barrier
	s_setprio 1
	s_waitcnt lgkmcnt(0)
	v_mfma_f32_16x16x32_bf16 v[126:129], v[130:133], v[182:185], 0
	v_mfma_f32_16x16x32_bf16 v[122:125], v[138:141], v[182:185], 0
	v_mfma_f32_16x16x32_bf16 v[110:113], v[130:133], v[192:195], 0
	v_mfma_f32_16x16x32_bf16 v[106:109], v[138:141], v[192:195], 0
	v_mfma_f32_16x16x32_bf16 v[94:97], v[130:133], v[200:203], 0
	v_mfma_f32_16x16x32_bf16 v[90:93], v[138:141], v[200:203], 0
	v_mfma_f32_16x16x32_bf16 v[78:81], v[130:133], v[212:215], 0
	v_mfma_f32_16x16x32_bf16 v[74:77], v[138:141], v[212:215], 0
	v_mfma_f32_16x16x32_bf16 v[126:129], v[134:137], v[186:189], v[126:129]
	v_mfma_f32_16x16x32_bf16 v[122:125], v[142:145], v[186:189], v[122:125]
	v_mfma_f32_16x16x32_bf16 v[110:113], v[134:137], v[196:199], v[110:113]
	v_mfma_f32_16x16x32_bf16 v[106:109], v[142:145], v[196:199], v[106:109]
	v_mfma_f32_16x16x32_bf16 v[94:97], v[134:137], v[208:211], v[94:97]
	v_mfma_f32_16x16x32_bf16 v[90:93], v[142:145], v[208:211], v[90:93]
	v_mfma_f32_16x16x32_bf16 v[78:81], v[134:137], v[216:219], v[78:81]
	v_mfma_f32_16x16x32_bf16 v[74:77], v[142:145], v[216:219], v[74:77]
	s_setprio 0
	s_setprio 1
	v_mfma_f32_16x16x32_bf16 v[118:121], v[146:149], v[182:185], 0
	v_mfma_f32_16x16x32_bf16 v[114:117], v[154:157], v[182:185], 0
	v_mfma_f32_16x16x32_bf16 v[102:105], v[146:149], v[192:195], 0
	v_mfma_f32_16x16x32_bf16 v[98:101], v[154:157], v[192:195], 0
	v_mfma_f32_16x16x32_bf16 v[86:89], v[146:149], v[200:203], 0
	v_mfma_f32_16x16x32_bf16 v[82:85], v[154:157], v[200:203], 0
	v_mfma_f32_16x16x32_bf16 v[70:73], v[146:149], v[212:215], 0
	v_mfma_f32_16x16x32_bf16 v[66:69], v[154:157], v[212:215], 0
	v_mfma_f32_16x16x32_bf16 v[118:121], v[150:153], v[186:189], v[118:121]
	v_mfma_f32_16x16x32_bf16 v[114:117], v[158:161], v[186:189], v[114:117]
	v_mfma_f32_16x16x32_bf16 v[102:105], v[150:153], v[196:199], v[102:105]
	v_mfma_f32_16x16x32_bf16 v[98:101], v[158:161], v[196:199], v[98:101]
	v_mfma_f32_16x16x32_bf16 v[86:89], v[150:153], v[208:211], v[86:89]
	v_mfma_f32_16x16x32_bf16 v[82:85], v[158:161], v[208:211], v[82:85]
	v_mfma_f32_16x16x32_bf16 v[70:73], v[150:153], v[216:219], v[70:73]
	v_mfma_f32_16x16x32_bf16 v[66:69], v[158:161], v[216:219], v[66:69]
	s_setprio 0
	s_barrier
	s_add_i32 s6, s66, s55
	v_lshl_add_u64 v[220:221], s[10:11], 0, v[164:165]
	s_mov_b32 m0, s6
	ds_read_b128 v[182:185], v207 offset:16384
	ds_read_b128 v[186:189], v207 offset:17408
	ds_read_b128 v[192:195], v207 offset:18432
	ds_read_b128 v[196:199], v207 offset:19456
	ds_read_b128 v[200:203], v207 offset:20480
	ds_read_b128 v[208:211], v207 offset:21504
	ds_read_b128 v[212:215], v207 offset:22528
	ds_read_b128 v[216:219], v207 offset:23552
	global_load_lds_dwordx4 v[220:221], off
	s_add_i32 m0, s6, 0x2000
	s_add_u32 s6, s10, 0xb0000
	v_lshl_add_u64 v[222:223], s[10:11], 0, v[168:169]
	s_addc_u32 s7, s11, 0
	s_add_i32 s15, s67, s55
	global_load_lds_dwordx4 v[222:223], off
	v_lshl_add_u64 v[224:225], s[6:7], 0, v[164:165]
	s_mov_b32 m0, s15
	v_lshl_add_u64 v[226:227], s[42:43], 0, v[166:167]
	global_load_lds_dwordx4 v[224:225], off
	v_lshl_add_u64 v[224:225], s[6:7], 0, v[168:169]
	s_add_i32 m0, s15, 0x2000
	s_nop 0
	global_load_lds_dwordx4 v[224:225], off
	v_lshl_add_u64 v[224:225], s[42:43], 0, v[162:163]
	s_mov_b32 m0, s56
	s_nop 0
	global_load_lds_dwordx4 v[224:225], off
	s_mov_b32 m0, s57
	s_nop 0
	global_load_lds_dwordx4 v[226:227], off
	s_waitcnt vmcnt(8)
	s_waitcnt lgkmcnt(0)
	s_barrier
; #define PG8_STAGE(bufoff, gbase, voff) do { _Pragma("unroll") for (int _i = 0; _i < 2; ++_i) \
;         __builtin_amdgcn_global_load_lds((const unsigned*)((const char*)(gbase) + (voff)[_i]), (PG8_LAS unsigned*)(lds + (bufoff) + ldsw + _i * 8192), 16, 0, 0); } while (0)
; #define PG8_LDA(dst, b, h) do { _Pragma("unroll") for (int m = 0; m < 4; ++m) _Pragma("unroll") for (int k = 0; k < 2; ++k) dst[m][k] = *(const PG8_LAS bf16x8*)(lds + PG8_SA(b, h) + aoff + m * 2048 + k * 1024); } while (0)
; #define PG8_LDB(dst, b, h) do { _Pragma("unroll") for (int n = 0; n < 2; ++n) _Pragma("unroll") for (int k = 0; k < 2; ++k) dst[n][k] = *(const PG8_LAS bf16x8*)(lds + PG8_SB(b, h) + boff + n * 2048 + k * 1024); } while (0)
; #define PG8_MMA(ai, bj, At, Bt) do { __builtin_amdgcn_s_setprio(1); _Pragma("unroll") for (int m = 0; m < 4; ++m) _Pragma("unroll") for (int n = 0; n < 2; ++n) _Pragma("unroll") for (int k = 0; k < 2; ++k) \
;         acc[ai][bj][m][n] = __builtin_amdgcn_mfma_f32_16x16x32_bf16(Bt[n][k], At[m][k], acc[ai][bj][m][n], 0, 0, 0); __builtin_amdgcn_s_setprio(0); } while (0)
; #define PG8_WAIT_V(n) asm volatile("s_waitcnt vmcnt(" #n ")" ::: "memory")
; #define PG8_WAIT_L(n) asm volatile("s_waitcnt lgkmcnt(" #n ")" ::: "memory")
; #define PG8_BAR __builtin_amdgcn_s_barrier()
; #define PG8_SCHED __builtin_amdgcn_sched_barrier(0)
; template <class Epi, class Sched, bool ALIGN_EPI = false, bool SP2 = false>
; __device__ __forceinline__ void gemm_phase(PG8_LAS unsigned char* lds, const Gemm g, const Sched& S, const Epi& E, const int tid) {
;     ...
;             PG8_WAIT_V(8); PG8_WAIT_L(0); PG8_BAR; PG8_MMA(1, 0, At, B0); PG8_MMA(1, 1, At, B1); PG8_BAR; PG8_SCHED;
;             PG8_LDB(B0, 1, 0); PG8_LDB(B1, 1, 1); PG8_SCHED; PG8_LDA(At, 1, 0); PG8_STAGE(PG8_SA(0, 1), a2 + hstep, voffA);
;             PG8_WAIT_V(8); PG8_WAIT_L(0); PG8_BAR; PG8_MMA(0, 0, At, B0); PG8_MMA(0, 1, At, B1); PG8_BAR; PG8_SCHED;
	s_setprio 1
	s_waitcnt lgkmcnt(0)
	v_mfma_f32_16x16x32_bf16 v[62:65], v[130:133], v[182:185], 0
	v_mfma_f32_16x16x32_bf16 v[58:61], v[138:141], v[182:185], 0
	v_mfma_f32_16x16x32_bf16 v[46:49], v[130:133], v[192:195], 0
	v_mfma_f32_16x16x32_bf16 v[42:45], v[138:141], v[192:195], 0
	v_mfma_f32_16x16x32_bf16 v[30:33], v[130:133], v[200:203], 0
	v_mfma_f32_16x16x32_bf16 v[26:29], v[138:141], v[200:203], 0
	v_mfma_f32_16x16x32_bf16 v[14:17], v[130:133], v[212:215], 0
	v_mfma_f32_16x16x32_bf16 v[10:13], v[138:141], v[212:215], 0
	v_mfma_f32_16x16x32_bf16 v[62:65], v[134:137], v[186:189], v[62:65]
	v_mfma_f32_16x16x32_bf16 v[58:61], v[142:145], v[186:189], v[58:61]
	v_mfma_f32_16x16x32_bf16 v[46:49], v[134:137], v[196:199], v[46:49]
	v_mfma_f32_16x16x32_bf16 v[42:45], v[142:145], v[196:199], v[42:45]
	v_mfma_f32_16x16x32_bf16 v[30:33], v[134:137], v[208:211], v[30:33]
	v_mfma_f32_16x16x32_bf16 v[26:29], v[142:145], v[208:211], v[26:29]
	v_mfma_f32_16x16x32_bf16 v[14:17], v[134:137], v[216:219], v[14:17]
	v_mfma_f32_16x16x32_bf16 v[10:13], v[142:145], v[216:219], v[10:13]
	s_setprio 0
	s_setprio 1
	v_mfma_f32_16x16x32_bf16 v[54:57], v[146:149], v[182:185], 0
	v_mfma_f32_16x16x32_bf16 v[50:53], v[154:157], v[182:185], 0
	v_mfma_f32_16x16x32_bf16 v[38:41], v[146:149], v[192:195], 0
	v_mfma_f32_16x16x32_bf16 v[34:37], v[154:157], v[192:195], 0
	v_mfma_f32_16x16x32_bf16 v[22:25], v[146:149], v[200:203], 0
	v_mfma_f32_16x16x32_bf16 v[18:21], v[154:157], v[200:203], 0
	v_mfma_f32_16x16x32_bf16 v[6:9], v[146:149], v[212:215], 0
	v_mfma_f32_16x16x32_bf16 v[2:5], v[154:157], v[212:215], 0
	v_mfma_f32_16x16x32_bf16 v[54:57], v[150:153], v[186:189], v[54:57]
	v_mfma_f32_16x16x32_bf16 v[50:53], v[158:161], v[186:189], v[50:53]
	v_mfma_f32_16x16x32_bf16 v[38:41], v[150:153], v[196:199], v[38:41]
	v_mfma_f32_16x16x32_bf16 v[34:37], v[158:161], v[196:199], v[34:37]
	v_mfma_f32_16x16x32_bf16 v[22:25], v[150:153], v[208:211], v[22:25]
	v_mfma_f32_16x16x32_bf16 v[18:21], v[158:161], v[208:211], v[18:21]
	v_mfma_f32_16x16x32_bf16 v[6:9], v[150:153], v[216:219], v[6:9]
	v_mfma_f32_16x16x32_bf16 v[2:5], v[158:161], v[216:219], v[2:5]
	s_setprio 0
	s_barrier
	s_add_i32 s15, 0, 0x18000
	s_add_i32 s18, 0, 0x1c000
	v_add_u32_e32 v142, s15, v204
	v_add_u32_e32 v158, s18, v204
	ds_read_b128 v[130:133], v142
	ds_read_b128 v[134:137], v142 offset:1024
	ds_read_b128 v[138:141], v142 offset:2048
	ds_read_b128 v[142:145], v142 offset:3072
	ds_read_b128 v[146:149], v158
	ds_read_b128 v[150:153], v158 offset:1024
	ds_read_b128 v[154:157], v158 offset:2048
	ds_read_b128 v[158:161], v158 offset:3072
	s_add_u32 s6, s42, 0xb0000
	s_addc_u32 s7, s43, 0
	s_mov_b32 m0, s58
	v_lshl_add_u64 v[228:229], s[6:7], 0, v[162:163]
	ds_read_b128 v[182:185], v207 offset:32768
	ds_read_b128 v[186:189], v207 offset:33792
	ds_read_b128 v[192:195], v207 offset:34816
	ds_read_b128 v[196:199], v207 offset:35840
	ds_read_b128 v[200:203], v207 offset:36864
	ds_read_b128 v[208:211], v207 offset:37888
	ds_read_b128 v[212:215], v207 offset:38912
	ds_read_b128 v[216:219], v207 offset:39936
	global_load_lds_dwordx4 v[228:229], off
	v_lshl_add_u64 v[228:229], s[6:7], 0, v[166:167]
	s_mov_b32 m0, s59
	s_nop 0
	global_load_lds_dwordx4 v[228:229], off
	s_waitcnt vmcnt(8)
	s_waitcnt lgkmcnt(0)
	s_barrier
	s_setprio 1
	s_waitcnt lgkmcnt(0)
	v_mfma_f32_16x16x32_bf16 v[126:129], v[130:133], v[182:185], v[126:129]
	v_mfma_f32_16x16x32_bf16 v[122:125], v[138:141], v[182:185], v[122:125]
	v_mfma_f32_16x16x32_bf16 v[110:113], v[130:133], v[192:195], v[110:113]
	v_mfma_f32_16x16x32_bf16 v[106:109], v[138:141], v[192:195], v[106:109]
	v_mfma_f32_16x16x32_bf16 v[94:97], v[130:133], v[200:203], v[94:97]
	v_mfma_f32_16x16x32_bf16 v[90:93], v[138:141], v[200:203], v[90:93]
	v_mfma_f32_16x16x32_bf16 v[78:81], v[130:133], v[212:215], v[78:81]
	v_mfma_f32_16x16x32_bf16 v[74:77], v[138:141], v[212:215], v[74:77]
	v_mfma_f32_16x16x32_bf16 v[126:129], v[134:137], v[186:189], v[126:129]
	v_mfma_f32_16x16x32_bf16 v[122:125], v[142:145], v[186:189], v[122:125]
	v_mfma_f32_16x16x32_bf16 v[110:113], v[134:137], v[196:199], v[110:113]
	v_mfma_f32_16x16x32_bf16 v[106:109], v[142:145], v[196:199], v[106:109]
	v_mfma_f32_16x16x32_bf16 v[94:97], v[134:137], v[208:211], v[94:97]
	v_mfma_f32_16x16x32_bf16 v[90:93], v[142:145], v[208:211], v[90:93]
	v_mfma_f32_16x16x32_bf16 v[78:81], v[134:137], v[216:219], v[78:81]
	v_mfma_f32_16x16x32_bf16 v[74:77], v[142:145], v[216:219], v[74:77]
	s_setprio 0
	s_setprio 1
	v_mfma_f32_16x16x32_bf16 v[118:121], v[146:149], v[182:185], v[118:121]
	v_mfma_f32_16x16x32_bf16 v[114:117], v[154:157], v[182:185], v[114:117]
	v_mfma_f32_16x16x32_bf16 v[102:105], v[146:149], v[192:195], v[102:105]
	v_mfma_f32_16x16x32_bf16 v[98:101], v[154:157], v[192:195], v[98:101]
	v_mfma_f32_16x16x32_bf16 v[86:89], v[146:149], v[200:203], v[86:89]
	v_mfma_f32_16x16x32_bf16 v[82:85], v[154:157], v[200:203], v[82:85]
	v_mfma_f32_16x16x32_bf16 v[70:73], v[146:149], v[212:215], v[70:73]
	v_mfma_f32_16x16x32_bf16 v[66:69], v[154:157], v[212:215], v[66:69]
	v_mfma_f32_16x16x32_bf16 v[118:121], v[150:153], v[186:189], v[118:121]
	v_mfma_f32_16x16x32_bf16 v[114:117], v[158:161], v[186:189], v[114:117]
	v_mfma_f32_16x16x32_bf16 v[102:105], v[150:153], v[196:199], v[102:105]
	v_mfma_f32_16x16x32_bf16 v[98:101], v[158:161], v[196:199], v[98:101]
	v_mfma_f32_16x16x32_bf16 v[86:89], v[150:153], v[208:211], v[86:89]
	v_mfma_f32_16x16x32_bf16 v[82:85], v[158:161], v[208:211], v[82:85]
	v_mfma_f32_16x16x32_bf16 v[70:73], v[150:153], v[216:219], v[70:73]
	v_mfma_f32_16x16x32_bf16 v[66:69], v[158:161], v[216:219], v[66:69]
	s_setprio 0
	s_barrier
; #define PG8_STAGE(bufoff, gbase, voff) do { _Pragma("unroll") for (int _i = 0; _i < 2; ++_i) \
;         __builtin_amdgcn_global_load_lds((const unsigned*)((const char*)(gbase) + (voff)[_i]), (PG8_LAS unsigned*)(lds + (bufoff) + ldsw + _i * 8192), 16, 0, 0); } while (0)
; #define PG8_LDA(dst, b, h) do { _Pragma("unroll") for (int m = 0; m < 4; ++m) _Pragma("unroll") for (int k = 0; k < 2; ++k) dst[m][k] = *(const PG8_LAS bf16x8*)(lds + PG8_SA(b, h) + aoff + m * 2048 + k * 1024); } while (0)
; #define PG8_MMA(ai, bj, At, Bt) do { __builtin_amdgcn_s_setprio(1); _Pragma("unroll") for (int m = 0; m < 4; ++m) _Pragma("unroll") for (int n = 0; n < 2; ++n) _Pragma("unroll") for (int k = 0; k < 2; ++k) \
;         acc[ai][bj][m][n] = __builtin_amdgcn_mfma_f32_16x16x32_bf16(Bt[n][k], At[m][k], acc[ai][bj][m][n], 0, 0, 0); __builtin_amdgcn_s_setprio(0); } while (0)
; #define PG8_WAIT_V(n) asm volatile("s_waitcnt vmcnt(" #n ")" ::: "memory")
; #define PG8_WAIT_L(n) asm volatile("s_waitcnt lgkmcnt(" #n ")" ::: "memory")
; #define PG8_BAR __builtin_amdgcn_s_barrier()
; #define PG8_SCHED __builtin_amdgcn_sched_barrier(0)
; template <class Epi, class Sched, bool ALIGN_EPI = false, bool SP2 = false>
; __device__ __forceinline__ void gemm_phase(PG8_LAS unsigned char* lds, const Gemm g, const Sched& S, const Epi& E, const int tid) {
;     ...
;         for (int t = 0; t < nt; t += 2) {
;             const bool last = (t == nt - 2);
;             const char* a1 = cA + (size_t)(t + 1) * kstep;
;             const char* a2 = last ? nA : cA + (size_t)(t + 2) * kstep; const char* b2 = last ? nB : cB + (size_t)(t + 2) * kstep;
;             const char* a3 = a2 + kstep; const char* b3 = b2 + kstep;
;     ...
;             PG8_LDA(At, 1, 1); PG8_STAGE(PG8_SB(1, 0), b3, voffB); PG8_STAGE(PG8_SB(1, 1), b3 + hstep, voffB); PG8_STAGE(PG8_SA(1, 0), a3, voffA);
;             PG8_WAIT_V(8); PG8_WAIT_L(0); PG8_BAR; PG8_MMA(1, 0, At, B0); PG8_MMA(1, 1, At, B1); PG8_BAR; PG8_SCHED;
	s_add_i32 s6, s15, s55
	v_lshl_add_u64 v[220:221], v[220:221], 0, s[36:37]
	s_mov_b32 m0, s6
	ds_read_b128 v[182:185], v207 offset:49152
	ds_read_b128 v[186:189], v207 offset:50176
	ds_read_b128 v[192:195], v207 offset:51200
	ds_read_b128 v[196:199], v207 offset:52224
	ds_read_b128 v[200:203], v207 offset:53248
	ds_read_b128 v[208:211], v207 offset:54272
	ds_read_b128 v[212:215], v207 offset:55296
	ds_read_b128 v[216:219], v207 offset:56320
	global_load_lds_dwordx4 v[220:221], off
	s_add_i32 m0, s6, 0x2000
	s_add_u32 s6, s10, 0xb0080
	v_lshl_add_u64 v[220:221], v[222:223], 0, s[36:37]
	s_addc_u32 s7, s11, 0
	s_add_i32 s10, s18, s55
	global_load_lds_dwordx4 v[220:221], off
	v_lshl_add_u64 v[220:221], s[6:7], 0, v[164:165]
	s_mov_b32 m0, s10
	s_nop 0
	global_load_lds_dwordx4 v[220:221], off
	v_lshl_add_u64 v[220:221], s[6:7], 0, v[168:169]
	s_add_i32 m0, s10, 0x2000
	s_nop 0
	global_load_lds_dwordx4 v[220:221], off
	v_lshl_add_u64 v[220:221], v[224:225], 0, s[36:37]
	s_mov_b32 m0, s61
	s_nop 0
	global_load_lds_dwordx4 v[220:221], off
	v_lshl_add_u64 v[220:221], v[226:227], 0, s[36:37]
	s_mov_b32 m0, s62
	s_nop 0
	global_load_lds_dwordx4 v[220:221], off
	s_waitcnt vmcnt(8)
	s_waitcnt lgkmcnt(0)
	s_barrier
	s_setprio 1
	s_waitcnt lgkmcnt(0)
	v_mfma_f32_16x16x32_bf16 v[62:65], v[130:133], v[182:185], v[62:65]
	v_mfma_f32_16x16x32_bf16 v[58:61], v[138:141], v[182:185], v[58:61]
	v_mfma_f32_16x16x32_bf16 v[46:49], v[130:133], v[192:195], v[46:49]
	v_mfma_f32_16x16x32_bf16 v[42:45], v[138:141], v[192:195], v[42:45]
	v_mfma_f32_16x16x32_bf16 v[30:33], v[130:133], v[200:203], v[30:33]
	v_mfma_f32_16x16x32_bf16 v[26:29], v[138:141], v[200:203], v[26:29]
	v_mfma_f32_16x16x32_bf16 v[14:17], v[130:133], v[212:215], v[14:17]
	v_mfma_f32_16x16x32_bf16 v[10:13], v[138:141], v[212:215], v[10:13]
	v_mfma_f32_16x16x32_bf16 v[62:65], v[134:137], v[186:189], v[62:65]
	v_mfma_f32_16x16x32_bf16 v[58:61], v[142:145], v[186:189], v[58:61]
	v_mfma_f32_16x16x32_bf16 v[46:49], v[134:137], v[196:199], v[46:49]
	v_mfma_f32_16x16x32_bf16 v[42:45], v[142:145], v[196:199], v[42:45]
	v_mfma_f32_16x16x32_bf16 v[30:33], v[134:137], v[208:211], v[30:33]
	v_mfma_f32_16x16x32_bf16 v[26:29], v[142:145], v[208:211], v[26:29]
	v_mfma_f32_16x16x32_bf16 v[14:17], v[134:137], v[216:219], v[14:17]
	v_mfma_f32_16x16x32_bf16 v[10:13], v[142:145], v[216:219], v[10:13]
	s_setprio 0
	s_setprio 1
	v_mfma_f32_16x16x32_bf16 v[54:57], v[146:149], v[182:185], v[54:57]
	v_mfma_f32_16x16x32_bf16 v[50:53], v[154:157], v[182:185], v[50:53]
	v_mfma_f32_16x16x32_bf16 v[38:41], v[146:149], v[192:195], v[38:41]
	v_mfma_f32_16x16x32_bf16 v[34:37], v[154:157], v[192:195], v[34:37]
	v_mfma_f32_16x16x32_bf16 v[22:25], v[146:149], v[200:203], v[22:25]
	v_mfma_f32_16x16x32_bf16 v[18:21], v[154:157], v[200:203], v[18:21]
	v_mfma_f32_16x16x32_bf16 v[6:9], v[146:149], v[212:215], v[6:9]
	v_mfma_f32_16x16x32_bf16 v[2:5], v[154:157], v[212:215], v[2:5]
	v_mfma_f32_16x16x32_bf16 v[54:57], v[150:153], v[186:189], v[54:57]
	v_mfma_f32_16x16x32_bf16 v[50:53], v[158:161], v[186:189], v[50:53]
	v_mfma_f32_16x16x32_bf16 v[38:41], v[150:153], v[196:199], v[38:41]
	v_mfma_f32_16x16x32_bf16 v[34:37], v[158:161], v[196:199], v[34:37]
	v_mfma_f32_16x16x32_bf16 v[22:25], v[150:153], v[208:211], v[22:25]
	v_mfma_f32_16x16x32_bf16 v[18:21], v[158:161], v[208:211], v[18:21]
	v_mfma_f32_16x16x32_bf16 v[6:9], v[150:153], v[216:219], v[6:9]
	v_mfma_f32_16x16x32_bf16 v[2:5], v[158:161], v[216:219], v[2:5]
	s_setprio 0
	s_barrier
	s_add_i32 s77, s77, 2
	s_add_u32 s45, s45, 0x100
	s_addc_u32 s47, s47, 0
	s_mov_b64 s[6:7], s[8:9]

; #define PG8_STAGE(bufoff, gbase, voff) do { _Pragma("unroll") for (int _i = 0; _i < 2; ++_i) \
;         __builtin_amdgcn_global_load_lds((const unsigned*)((const char*)(gbase) + (voff)[_i]), (PG8_LAS unsigned*)(lds + (bufoff) + ldsw + _i * 8192), 16, 0, 0); } while (0)
; #define PG8_LDA(dst, b, h) do { _Pragma("unroll") for (int m = 0; m < 4; ++m) _Pragma("unroll") for (int k = 0; k < 2; ++k) dst[m][k] = *(const PG8_LAS bf16x8*)(lds + PG8_SA(b, h) + aoff + m * 2048 + k * 1024); } while (0)
; #define PG8_LDB(dst, b, h) do { _Pragma("unroll") for (int n = 0; n < 2; ++n) _Pragma("unroll") for (int k = 0; k < 2; ++k) dst[n][k] = *(const PG8_LAS bf16x8*)(lds + PG8_SB(b, h) + boff + n * 2048 + k * 1024); } while (0)
; #define PG8_WAIT_V(n) asm volatile("s_waitcnt vmcnt(" #n ")" ::: "memory")
; #define PG8_WAIT_L(n) asm volatile("s_waitcnt lgkmcnt(" #n ")" ::: "memory")
; #define PG8_BAR __builtin_amdgcn_s_barrier()
; #define PG8_SCHED __builtin_amdgcn_sched_barrier(0)
; template <class Epi, class Sched, bool ALIGN_EPI = false, bool SP2 = false>
; __device__ __forceinline__ void gemm_phase(PG8_LAS unsigned char* lds, const Gemm g, const Sched& S, const Epi& E, const int tid) {
;     ...
;         const bool has_next = S.next(ui + 1, nxt);
;         const char* nA = has_next ? S.aptr(nxt) : cA; const char* nB = has_next ? S.bptr(nxt) : cB;
;         for (int t = 0; t < nt; t += 2) {
;             const bool last = (t == nt - 2);
;             const char* a1 = cA + (size_t)(t + 1) * kstep;
;             const char* a2 = last ? nA : cA + (size_t)(t + 2) * kstep; const char* b2 = last ? nB : cB + (size_t)(t + 2) * kstep;
;             const char* a3 = a2 + kstep; const char* b3 = b2 + kstep;
;             if (last && has_next) S.a_ready(nxt);
;             if constexpr (SP2) {
;             PG8_LDB(B0, 0, 0); PG8_LDB(B1, 0, 1); PG8_SCHED; PG8_LDA(At, 0, 0); PG8_STAGE(PG8_SA(1, 1), a1 + hstep, voffA);
;             PG8_WAIT_V(8); PG8_WAIT_L(0); PG8_BAR; PG8_MMA(0, 0, At, B0); PG8_MMA(0, 1, At, B1); PG8_BAR; PG8_SCHED;
;             PG8_LDA(At, 0, 1); PG8_STAGE(PG8_SB(0, 0), b2, voffB); PG8_STAGE(PG8_SB(0, 1), b2 + hstep, voffB); PG8_STAGE(PG8_SA(0, 0), a2, voffA);
;             PG8_WAIT_V(8); PG8_WAIT_L(0); PG8_BAR; PG8_MMA(1, 0, At, B0); PG8_MMA(1, 1, At, B1); PG8_BAR; PG8_SCHED;
.LBB0_732:
	s_ashr_i32 s29, s28, 31
	s_lshl_b64 s[18:19], s[28:29], 19
	s_add_u32 s30, s50, s18
	s_addc_u32 s31, s51, s19
	s_and_b64 s[18:19], s[2:3], exec
	s_cselect_b32 s29, s31, s41
	s_cselect_b32 s37, s30, s40
	s_ashr_i32 s27, s26, 31
	s_lshl_b64 s[18:19], s[26:27], 19
	s_add_u32 s34, s52, s18
	s_addc_u32 s35, s53, s19
	s_and_b64 s[18:19], s[2:3], exec
	s_cselect_b32 s27, s35, s39
	s_cselect_b32 s79, s34, s38
	s_add_u32 s80, s38, 0x100
	s_addc_u32 s81, s39, 0
	s_add_u32 s38, s40, 0x40080
	s_addc_u32 s39, s41, 0
	s_mov_b32 s82, -2
	ds_read_b128 v[130:133], v191
	ds_read_b128 v[134:137], v191 offset:1024
	ds_read_b128 v[138:141], v191 offset:2048
	ds_read_b128 v[142:145], v191 offset:3072
	ds_read_b128 v[146:149], v193
	ds_read_b128 v[150:153], v193 offset:1024
	ds_read_b128 v[154:157], v193 offset:2048
	ds_read_b128 v[158:161], v193 offset:3072
	s_add_u32 s15, s38, 0xfffc0080
	s_addc_u32 s18, s39, -1
	s_cmp_eq_u32 s82, 12
	s_cselect_b32 s43, s29, s18
	s_cselect_b32 s42, s37, s15
	s_cselect_b32 s41, s27, s81
	s_cselect_b32 s40, s79, s80
	v_lshl_add_u64 v[194:195], s[38:39], 0, v[180:181]
	s_add_i32 m0, s55, 0xc000
	ds_read_b128 v[186:189], v197
	ds_read_b128 v[198:201], v197 offset:1024
	ds_read_b128 v[206:209], v197 offset:2048
	ds_read_b128 v[212:215], v197 offset:3072
	ds_read_b128 v[216:219], v197 offset:4096
	ds_read_b128 v[220:223], v197 offset:5120
	ds_read_b128 v[224:227], v197 offset:6144
	ds_read_b128 v[228:231], v197 offset:7168
	global_load_lds_dwordx4 v[194:195], off
	v_lshl_add_u64 v[194:195], s[38:39], 0, v[178:179]
	s_add_i32 m0, s55, 0xe000
	s_nop 0
	global_load_lds_dwordx4 v[194:195], off
	s_waitcnt vmcnt(8)
	s_waitcnt lgkmcnt(0)
	s_barrier
	s_setprio 1
	s_waitcnt lgkmcnt(0)
	v_mfma_f32_16x16x32_bf16 v[126:129], v[130:133], v[186:189], 0
	v_mfma_f32_16x16x32_bf16 v[122:125], v[138:141], v[186:189], 0
	v_mfma_f32_16x16x32_bf16 v[110:113], v[130:133], v[206:209], 0
	v_mfma_f32_16x16x32_bf16 v[106:109], v[138:141], v[206:209], 0
	v_mfma_f32_16x16x32_bf16 v[94:97], v[130:133], v[216:219], 0
	v_mfma_f32_16x16x32_bf16 v[90:93], v[138:141], v[216:219], 0
	v_mfma_f32_16x16x32_bf16 v[78:81], v[130:133], v[224:227], 0
	v_mfma_f32_16x16x32_bf16 v[74:77], v[138:141], v[224:227], 0
	v_mfma_f32_16x16x32_bf16 v[126:129], v[134:137], v[198:201], v[126:129]
	v_mfma_f32_16x16x32_bf16 v[122:125], v[142:145], v[198:201], v[122:125]
	v_mfma_f32_16x16x32_bf16 v[110:113], v[134:137], v[212:215], v[110:113]
	v_mfma_f32_16x16x32_bf16 v[106:109], v[142:145], v[212:215], v[106:109]
	v_mfma_f32_16x16x32_bf16 v[94:97], v[134:137], v[220:223], v[94:97]
	v_mfma_f32_16x16x32_bf16 v[90:93], v[142:145], v[220:223], v[90:93]
	v_mfma_f32_16x16x32_bf16 v[78:81], v[134:137], v[228:231], v[78:81]
	v_mfma_f32_16x16x32_bf16 v[74:77], v[142:145], v[228:231], v[74:77]
	s_setprio 0
	s_setprio 1
	v_mfma_f32_16x16x32_bf16 v[118:121], v[146:149], v[186:189], 0
	v_mfma_f32_16x16x32_bf16 v[114:117], v[154:157], v[186:189], 0
	v_mfma_f32_16x16x32_bf16 v[102:105], v[146:149], v[206:209], 0
	v_mfma_f32_16x16x32_bf16 v[98:101], v[154:157], v[206:209], 0
	v_mfma_f32_16x16x32_bf16 v[86:89], v[146:149], v[216:219], 0
	v_mfma_f32_16x16x32_bf16 v[82:85], v[154:157], v[216:219], 0
	v_mfma_f32_16x16x32_bf16 v[70:73], v[146:149], v[224:227], 0
	v_mfma_f32_16x16x32_bf16 v[66:69], v[154:157], v[224:227], 0
	v_mfma_f32_16x16x32_bf16 v[118:121], v[150:153], v[198:201], v[118:121]
	v_mfma_f32_16x16x32_bf16 v[114:117], v[158:161], v[198:201], v[114:117]
	v_mfma_f32_16x16x32_bf16 v[102:105], v[150:153], v[212:215], v[102:105]
	v_mfma_f32_16x16x32_bf16 v[98:101], v[158:161], v[212:215], v[98:101]
	v_mfma_f32_16x16x32_bf16 v[86:89], v[150:153], v[220:223], v[86:89]
	v_mfma_f32_16x16x32_bf16 v[82:85], v[158:161], v[220:223], v[82:85]
	v_mfma_f32_16x16x32_bf16 v[70:73], v[150:153], v[228:231], v[70:73]
	v_mfma_f32_16x16x32_bf16 v[66:69], v[158:161], v[228:231], v[66:69]
	s_setprio 0
	s_barrier
	s_add_i32 s15, s66, s54
	v_lshl_add_u64 v[194:195], s[40:41], 0, v[164:165]
	s_mov_b32 m0, s15
	ds_read_b128 v[186:189], v197 offset:16384
	ds_read_b128 v[198:201], v197 offset:17408
	ds_read_b128 v[206:209], v197 offset:18432
	ds_read_b128 v[212:215], v197 offset:19456
	ds_read_b128 v[216:219], v197 offset:20480
	ds_read_b128 v[220:223], v197 offset:21504
	ds_read_b128 v[224:227], v197 offset:22528
	ds_read_b128 v[228:231], v197 offset:23552
	global_load_lds_dwordx4 v[194:195], off
	s_add_i32 m0, s15, 0x2000
	s_add_u32 s18, s40, 0x40000
	v_lshl_add_u64 v[232:233], s[40:41], 0, v[168:169]
	s_addc_u32 s19, s41, 0
	s_add_i32 s15, s67, s54
	global_load_lds_dwordx4 v[232:233], off
	v_lshl_add_u64 v[234:235], s[18:19], 0, v[164:165]
	s_mov_b32 m0, s15
	v_lshl_add_u64 v[236:237], s[42:43], 0, v[166:167]
	global_load_lds_dwordx4 v[234:235], off
	v_lshl_add_u64 v[234:235], s[18:19], 0, v[168:169]
	s_add_i32 m0, s15, 0x2000
	s_nop 0
	global_load_lds_dwordx4 v[234:235], off
	v_lshl_add_u64 v[234:235], s[42:43], 0, v[162:163]
	s_mov_b32 m0, s55
	s_nop 0
	global_load_lds_dwordx4 v[234:235], off
	s_mov_b32 m0, s56
	s_nop 0
	global_load_lds_dwordx4 v[236:237], off
	s_waitcnt vmcnt(8)
	s_waitcnt lgkmcnt(0)
	s_barrier
; #define PG8_STAGE(bufoff, gbase, voff) do { _Pragma("unroll") for (int _i = 0; _i < 2; ++_i) \
;         __builtin_amdgcn_global_load_lds((const unsigned*)((const char*)(gbase) + (voff)[_i]), (PG8_LAS unsigned*)(lds + (bufoff) + ldsw + _i * 8192), 16, 0, 0); } while (0)
; #define PG8_LDA(dst, b, h) do { _Pragma("unroll") for (int m = 0; m < 4; ++m) _Pragma("unroll") for (int k = 0; k < 2; ++k) dst[m][k] = *(const PG8_LAS bf16x8*)(lds + PG8_SA(b, h) + aoff + m * 2048 + k * 1024); } while (0)
; #define PG8_LDB(dst, b, h) do { _Pragma("unroll") for (int n = 0; n < 2; ++n) _Pragma("unroll") for (int k = 0; k < 2; ++k) dst[n][k] = *(const PG8_LAS bf16x8*)(lds + PG8_SB(b, h) + boff + n * 2048 + k * 1024); } while (0)
; #define PG8_MMA(ai, bj, At, Bt) do { __builtin_amdgcn_s_setprio(1); _Pragma("unroll") for (int m = 0; m < 4; ++m) _Pragma("unroll") for (int n = 0; n < 2; ++n) _Pragma("unroll") for (int k = 0; k < 2; ++k) \
;         acc[ai][bj][m][n] = __builtin_amdgcn_mfma_f32_16x16x32_bf16(Bt[n][k], At[m][k], acc[ai][bj][m][n], 0, 0, 0); __builtin_amdgcn_s_setprio(0); } while (0)
; #define PG8_WAIT_V(n) asm volatile("s_waitcnt vmcnt(" #n ")" ::: "memory")
; #define PG8_WAIT_L(n) asm volatile("s_waitcnt lgkmcnt(" #n ")" ::: "memory")
; #define PG8_BAR __builtin_amdgcn_s_barrier()
; #define PG8_SCHED __builtin_amdgcn_sched_barrier(0)
; template <class Epi, class Sched, bool ALIGN_EPI = false, bool SP2 = false>
; __device__ __forceinline__ void gemm_phase(PG8_LAS unsigned char* lds, const Gemm g, const Sched& S, const Epi& E, const int tid) {
;     ...
;             PG8_WAIT_V(8); PG8_WAIT_L(0); PG8_BAR; PG8_MMA(1, 0, At, B0); PG8_MMA(1, 1, At, B1); PG8_BAR; PG8_SCHED;
;             PG8_LDB(B0, 1, 0); PG8_LDB(B1, 1, 1); PG8_SCHED; PG8_LDA(At, 1, 0); PG8_STAGE(PG8_SA(0, 1), a2 + hstep, voffA);
;             PG8_WAIT_V(8); PG8_WAIT_L(0); PG8_BAR; PG8_MMA(0, 0, At, B0); PG8_MMA(0, 1, At, B1); PG8_BAR; PG8_SCHED;
	s_setprio 1
	s_waitcnt lgkmcnt(0)
	v_mfma_f32_16x16x32_bf16 v[62:65], v[130:133], v[186:189], 0
	v_mfma_f32_16x16x32_bf16 v[58:61], v[138:141], v[186:189], 0
	v_mfma_f32_16x16x32_bf16 v[46:49], v[130:133], v[206:209], 0
	v_mfma_f32_16x16x32_bf16 v[42:45], v[138:141], v[206:209], 0
	v_mfma_f32_16x16x32_bf16 v[30:33], v[130:133], v[216:219], 0
	v_mfma_f32_16x16x32_bf16 v[26:29], v[138:141], v[216:219], 0
	v_mfma_f32_16x16x32_bf16 v[14:17], v[130:133], v[224:227], 0
	v_mfma_f32_16x16x32_bf16 v[10:13], v[138:141], v[224:227], 0
	v_mfma_f32_16x16x32_bf16 v[62:65], v[134:137], v[198:201], v[62:65]
	v_mfma_f32_16x16x32_bf16 v[58:61], v[142:145], v[198:201], v[58:61]
	v_mfma_f32_16x16x32_bf16 v[46:49], v[134:137], v[212:215], v[46:49]
	v_mfma_f32_16x16x32_bf16 v[42:45], v[142:145], v[212:215], v[42:45]
	v_mfma_f32_16x16x32_bf16 v[30:33], v[134:137], v[220:223], v[30:33]
	v_mfma_f32_16x16x32_bf16 v[26:29], v[142:145], v[220:223], v[26:29]
	v_mfma_f32_16x16x32_bf16 v[14:17], v[134:137], v[228:231], v[14:17]
	v_mfma_f32_16x16x32_bf16 v[10:13], v[142:145], v[228:231], v[10:13]
	s_setprio 0
	s_setprio 1
	v_mfma_f32_16x16x32_bf16 v[54:57], v[146:149], v[186:189], 0
	v_mfma_f32_16x16x32_bf16 v[50:53], v[154:157], v[186:189], 0
	v_mfma_f32_16x16x32_bf16 v[38:41], v[146:149], v[206:209], 0
	v_mfma_f32_16x16x32_bf16 v[34:37], v[154:157], v[206:209], 0
	v_mfma_f32_16x16x32_bf16 v[22:25], v[146:149], v[216:219], 0
	v_mfma_f32_16x16x32_bf16 v[18:21], v[154:157], v[216:219], 0
	v_mfma_f32_16x16x32_bf16 v[6:9], v[146:149], v[224:227], 0
	v_mfma_f32_16x16x32_bf16 v[2:5], v[154:157], v[224:227], 0
	v_mfma_f32_16x16x32_bf16 v[54:57], v[150:153], v[198:201], v[54:57]
	v_mfma_f32_16x16x32_bf16 v[50:53], v[158:161], v[198:201], v[50:53]
	v_mfma_f32_16x16x32_bf16 v[38:41], v[150:153], v[212:215], v[38:41]
	v_mfma_f32_16x16x32_bf16 v[34:37], v[158:161], v[212:215], v[34:37]
	v_mfma_f32_16x16x32_bf16 v[22:25], v[150:153], v[220:223], v[22:25]
	v_mfma_f32_16x16x32_bf16 v[18:21], v[158:161], v[220:223], v[18:21]
	v_mfma_f32_16x16x32_bf16 v[6:9], v[150:153], v[228:231], v[6:9]
	v_mfma_f32_16x16x32_bf16 v[2:5], v[158:161], v[228:231], v[2:5]
	s_setprio 0
	s_barrier
	s_add_i32 s15, 0, 0x18000
	s_add_i32 s83, 0, 0x1c000
	v_add_u32_e32 v142, s15, v173
	v_add_u32_e32 v158, s83, v173
	ds_read_b128 v[130:133], v142
	ds_read_b128 v[134:137], v142 offset:1024
	ds_read_b128 v[138:141], v142 offset:2048
	ds_read_b128 v[142:145], v142 offset:3072
	ds_read_b128 v[146:149], v158
	ds_read_b128 v[150:153], v158 offset:1024
	ds_read_b128 v[154:157], v158 offset:2048
	ds_read_b128 v[158:161], v158 offset:3072
	s_add_u32 s18, s42, 0x40000
	s_addc_u32 s19, s43, 0
	s_mov_b32 m0, s57
	v_lshl_add_u64 v[238:239], s[18:19], 0, v[162:163]
	ds_read_b128 v[186:189], v197 offset:32768
	ds_read_b128 v[198:201], v197 offset:33792
	ds_read_b128 v[206:209], v197 offset:34816
	ds_read_b128 v[212:215], v197 offset:35840
	ds_read_b128 v[216:219], v197 offset:36864
	ds_read_b128 v[220:223], v197 offset:37888
	ds_read_b128 v[224:227], v197 offset:38912
	ds_read_b128 v[228:231], v197 offset:39936
	global_load_lds_dwordx4 v[238:239], off
	v_lshl_add_u64 v[238:239], s[18:19], 0, v[166:167]
	s_mov_b32 m0, s58
	s_nop 0
	global_load_lds_dwordx4 v[238:239], off
	s_waitcnt vmcnt(8)
	s_waitcnt lgkmcnt(0)
	s_barrier
	s_setprio 1
	s_waitcnt lgkmcnt(0)
	v_mfma_f32_16x16x32_bf16 v[126:129], v[130:133], v[186:189], v[126:129]
	v_mfma_f32_16x16x32_bf16 v[122:125], v[138:141], v[186:189], v[122:125]
	v_mfma_f32_16x16x32_bf16 v[110:113], v[130:133], v[206:209], v[110:113]
	v_mfma_f32_16x16x32_bf16 v[106:109], v[138:141], v[206:209], v[106:109]
	v_mfma_f32_16x16x32_bf16 v[94:97], v[130:133], v[216:219], v[94:97]
	v_mfma_f32_16x16x32_bf16 v[90:93], v[138:141], v[216:219], v[90:93]
	v_mfma_f32_16x16x32_bf16 v[78:81], v[130:133], v[224:227], v[78:81]
	v_mfma_f32_16x16x32_bf16 v[74:77], v[138:141], v[224:227], v[74:77]
	v_mfma_f32_16x16x32_bf16 v[126:129], v[134:137], v[198:201], v[126:129]
	v_mfma_f32_16x16x32_bf16 v[122:125], v[142:145], v[198:201], v[122:125]
	v_mfma_f32_16x16x32_bf16 v[110:113], v[134:137], v[212:215], v[110:113]
	v_mfma_f32_16x16x32_bf16 v[106:109], v[142:145], v[212:215], v[106:109]
	v_mfma_f32_16x16x32_bf16 v[94:97], v[134:137], v[220:223], v[94:97]
	v_mfma_f32_16x16x32_bf16 v[90:93], v[142:145], v[220:223], v[90:93]
	v_mfma_f32_16x16x32_bf16 v[78:81], v[134:137], v[228:231], v[78:81]
	v_mfma_f32_16x16x32_bf16 v[74:77], v[142:145], v[228:231], v[74:77]
	s_setprio 0
	s_setprio 1
	v_mfma_f32_16x16x32_bf16 v[118:121], v[146:149], v[186:189], v[118:121]
	v_mfma_f32_16x16x32_bf16 v[114:117], v[154:157], v[186:189], v[114:117]
	v_mfma_f32_16x16x32_bf16 v[102:105], v[146:149], v[206:209], v[102:105]
	v_mfma_f32_16x16x32_bf16 v[98:101], v[154:157], v[206:209], v[98:101]
	v_mfma_f32_16x16x32_bf16 v[86:89], v[146:149], v[216:219], v[86:89]
	v_mfma_f32_16x16x32_bf16 v[82:85], v[154:157], v[216:219], v[82:85]
	v_mfma_f32_16x16x32_bf16 v[70:73], v[146:149], v[224:227], v[70:73]
	v_mfma_f32_16x16x32_bf16 v[66:69], v[154:157], v[224:227], v[66:69]
	v_mfma_f32_16x16x32_bf16 v[118:121], v[150:153], v[198:201], v[118:121]
	v_mfma_f32_16x16x32_bf16 v[114:117], v[158:161], v[198:201], v[114:117]
	v_mfma_f32_16x16x32_bf16 v[102:105], v[150:153], v[212:215], v[102:105]
	v_mfma_f32_16x16x32_bf16 v[98:101], v[158:161], v[212:215], v[98:101]
	v_mfma_f32_16x16x32_bf16 v[86:89], v[150:153], v[220:223], v[86:89]
	v_mfma_f32_16x16x32_bf16 v[82:85], v[158:161], v[220:223], v[82:85]
	v_mfma_f32_16x16x32_bf16 v[70:73], v[150:153], v[228:231], v[70:73]
	v_mfma_f32_16x16x32_bf16 v[66:69], v[158:161], v[228:231], v[66:69]
	s_setprio 0
	s_barrier
; #define PG8_STAGE(bufoff, gbase, voff) do { _Pragma("unroll") for (int _i = 0; _i < 2; ++_i) \
;         __builtin_amdgcn_global_load_lds((const unsigned*)((const char*)(gbase) + (voff)[_i]), (PG8_LAS unsigned*)(lds + (bufoff) + ldsw + _i * 8192), 16, 0, 0); } while (0)
; #define PG8_LDA(dst, b, h) do { _Pragma("unroll") for (int m = 0; m < 4; ++m) _Pragma("unroll") for (int k = 0; k < 2; ++k) dst[m][k] = *(const PG8_LAS bf16x8*)(lds + PG8_SA(b, h) + aoff + m * 2048 + k * 1024); } while (0)
; #define PG8_MMA(ai, bj, At, Bt) do { __builtin_amdgcn_s_setprio(1); _Pragma("unroll") for (int m = 0; m < 4; ++m) _Pragma("unroll") for (int n = 0; n < 2; ++n) _Pragma("unroll") for (int k = 0; k < 2; ++k) \
;         acc[ai][bj][m][n] = __builtin_amdgcn_mfma_f32_16x16x32_bf16(Bt[n][k], At[m][k], acc[ai][bj][m][n], 0, 0, 0); __builtin_amdgcn_s_setprio(0); } while (0)
; #define PG8_WAIT_V(n) asm volatile("s_waitcnt vmcnt(" #n ")" ::: "memory")
; #define PG8_WAIT_L(n) asm volatile("s_waitcnt lgkmcnt(" #n ")" ::: "memory")
; #define PG8_BAR __builtin_amdgcn_s_barrier()
; #define PG8_SCHED __builtin_amdgcn_sched_barrier(0)
; template <class Epi, class Sched, bool ALIGN_EPI = false, bool SP2 = false>
; __device__ __forceinline__ void gemm_phase(PG8_LAS unsigned char* lds, const Gemm g, const Sched& S, const Epi& E, const int tid) {
;     ...
;         for (int t = 0; t < nt; t += 2) {
;             const bool last = (t == nt - 2);
;             const char* a1 = cA + (size_t)(t + 1) * kstep;
;             const char* a2 = last ? nA : cA + (size_t)(t + 2) * kstep; const char* b2 = last ? nB : cB + (size_t)(t + 2) * kstep;
;             const char* a3 = a2 + kstep; const char* b3 = b2 + kstep;
;     ...
;             PG8_LDA(At, 1, 1); PG8_STAGE(PG8_SB(1, 0), b3, voffB); PG8_STAGE(PG8_SB(1, 1), b3 + hstep, voffB); PG8_STAGE(PG8_SA(1, 0), a3, voffA);
;             PG8_WAIT_V(8); PG8_WAIT_L(0); PG8_BAR; PG8_MMA(1, 0, At, B0); PG8_MMA(1, 1, At, B1); PG8_BAR; PG8_SCHED;
	s_add_i32 s15, s15, s54
	v_lshl_add_u64 v[194:195], v[194:195], 0, s[10:11]
	s_mov_b32 m0, s15
	ds_read_b128 v[186:189], v197 offset:49152
	ds_read_b128 v[198:201], v197 offset:50176
	ds_read_b128 v[206:209], v197 offset:51200
	ds_read_b128 v[212:215], v197 offset:52224
	ds_read_b128 v[216:219], v197 offset:53248
	ds_read_b128 v[220:223], v197 offset:54272
	ds_read_b128 v[224:227], v197 offset:55296
	ds_read_b128 v[228:231], v197 offset:56320
	global_load_lds_dwordx4 v[194:195], off
	s_add_i32 m0, s15, 0x2000
	s_add_u32 s18, s40, 0x40080
	v_lshl_add_u64 v[194:195], v[232:233], 0, s[10:11]
	s_addc_u32 s19, s41, 0
	s_add_i32 s15, s83, s54
	global_load_lds_dwordx4 v[194:195], off
	v_lshl_add_u64 v[194:195], s[18:19], 0, v[164:165]
	s_mov_b32 m0, s15
	s_nop 0
	global_load_lds_dwordx4 v[194:195], off
	v_lshl_add_u64 v[194:195], s[18:19], 0, v[168:169]
	s_add_i32 m0, s15, 0x2000
	s_nop 0
	global_load_lds_dwordx4 v[194:195], off
	v_lshl_add_u64 v[194:195], v[234:235], 0, s[10:11]
	s_mov_b32 m0, s61
	s_nop 0
	global_load_lds_dwordx4 v[194:195], off
	v_lshl_add_u64 v[194:195], v[236:237], 0, s[10:11]
	s_mov_b32 m0, s62
	s_nop 0
	global_load_lds_dwordx4 v[194:195], off
	s_waitcnt vmcnt(8)
	s_waitcnt lgkmcnt(0)
	s_barrier
	s_setprio 1
	s_waitcnt lgkmcnt(0)
	v_mfma_f32_16x16x32_bf16 v[62:65], v[130:133], v[186:189], v[62:65]
	v_mfma_f32_16x16x32_bf16 v[58:61], v[138:141], v[186:189], v[58:61]
	v_mfma_f32_16x16x32_bf16 v[46:49], v[130:133], v[206:209], v[46:49]
	v_mfma_f32_16x16x32_bf16 v[42:45], v[138:141], v[206:209], v[42:45]
	v_mfma_f32_16x16x32_bf16 v[30:33], v[130:133], v[216:219], v[30:33]
	v_mfma_f32_16x16x32_bf16 v[26:29], v[138:141], v[216:219], v[26:29]
	v_mfma_f32_16x16x32_bf16 v[14:17], v[130:133], v[224:227], v[14:17]
	v_mfma_f32_16x16x32_bf16 v[10:13], v[138:141], v[224:227], v[10:13]
	v_mfma_f32_16x16x32_bf16 v[62:65], v[134:137], v[198:201], v[62:65]
	v_mfma_f32_16x16x32_bf16 v[58:61], v[142:145], v[198:201], v[58:61]
	v_mfma_f32_16x16x32_bf16 v[46:49], v[134:137], v[212:215], v[46:49]
	v_mfma_f32_16x16x32_bf16 v[42:45], v[142:145], v[212:215], v[42:45]
	v_mfma_f32_16x16x32_bf16 v[30:33], v[134:137], v[220:223], v[30:33]
	v_mfma_f32_16x16x32_bf16 v[26:29], v[142:145], v[220:223], v[26:29]
	v_mfma_f32_16x16x32_bf16 v[14:17], v[134:137], v[228:231], v[14:17]
	v_mfma_f32_16x16x32_bf16 v[10:13], v[142:145], v[228:231], v[10:13]
	s_setprio 0
	s_setprio 1
	v_mfma_f32_16x16x32_bf16 v[54:57], v[146:149], v[186:189], v[54:57]
	v_mfma_f32_16x16x32_bf16 v[50:53], v[154:157], v[186:189], v[50:53]
	v_mfma_f32_16x16x32_bf16 v[38:41], v[146:149], v[206:209], v[38:41]
	v_mfma_f32_16x16x32_bf16 v[34:37], v[154:157], v[206:209], v[34:37]
	v_mfma_f32_16x16x32_bf16 v[22:25], v[146:149], v[216:219], v[22:25]
	v_mfma_f32_16x16x32_bf16 v[18:21], v[154:157], v[216:219], v[18:21]
	v_mfma_f32_16x16x32_bf16 v[6:9], v[146:149], v[224:227], v[6:9]
	v_mfma_f32_16x16x32_bf16 v[2:5], v[154:157], v[224:227], v[2:5]
	v_mfma_f32_16x16x32_bf16 v[54:57], v[150:153], v[198:201], v[54:57]
	v_mfma_f32_16x16x32_bf16 v[50:53], v[158:161], v[198:201], v[50:53]
	v_mfma_f32_16x16x32_bf16 v[38:41], v[150:153], v[212:215], v[38:41]
	v_mfma_f32_16x16x32_bf16 v[34:37], v[158:161], v[212:215], v[34:37]
	v_mfma_f32_16x16x32_bf16 v[22:25], v[150:153], v[220:223], v[22:25]
	v_mfma_f32_16x16x32_bf16 v[18:21], v[158:161], v[220:223], v[18:21]
	v_mfma_f32_16x16x32_bf16 v[6:9], v[150:153], v[228:231], v[6:9]
	v_mfma_f32_16x16x32_bf16 v[2:5], v[158:161], v[228:231], v[2:5]
	s_setprio 0
	s_barrier
	s_add_i32 s82, s82, 2
	s_add_u32 s80, s80, 0x100
	s_addc_u32 s81, s81, 0
	s_add_u32 s38, s38, 0x100
	s_addc_u32 s39, s39, 0

; #define PG8_STAGE(bufoff, gbase, voff) do { _Pragma("unroll") for (int _i = 0; _i < 2; ++_i) \
;         __builtin_amdgcn_global_load_lds((const unsigned*)((const char*)(gbase) + (voff)[_i]), (PG8_LAS unsigned*)(lds + (bufoff) + ldsw + _i * 8192), 16, 0, 0); } while (0)
; #define PG8_LDA(dst, b, h) do { _Pragma("unroll") for (int m = 0; m < 4; ++m) _Pragma("unroll") for (int k = 0; k < 2; ++k) dst[m][k] = *(const PG8_LAS bf16x8*)(lds + PG8_SA(b, h) + aoff + m * 2048 + k * 1024); } while (0)
; #define PG8_LDB(dst, b, h) do { _Pragma("unroll") for (int n = 0; n < 2; ++n) _Pragma("unroll") for (int k = 0; k < 2; ++k) dst[n][k] = *(const PG8_LAS bf16x8*)(lds + PG8_SB(b, h) + boff + n * 2048 + k * 1024); } while (0)
; #define PG8_WAIT_V(n) asm volatile("s_waitcnt vmcnt(" #n ")" ::: "memory")
; #define PG8_WAIT_L(n) asm volatile("s_waitcnt lgkmcnt(" #n ")" ::: "memory")
; #define PG8_BAR __builtin_amdgcn_s_barrier()
; #define PG8_SCHED __builtin_amdgcn_sched_barrier(0)
; template <class Epi, class Sched, bool ALIGN_EPI = false, bool SP2 = false>
; __device__ __forceinline__ void gemm_phase(PG8_LAS unsigned char* lds, const Gemm g, const Sched& S, const Epi& E, const int tid) {
;     ...
;         const bool has_next = S.next(ui + 1, nxt);
;         const char* nA = has_next ? S.aptr(nxt) : cA; const char* nB = has_next ? S.bptr(nxt) : cB;
;         for (int t = 0; t < nt; t += 2) {
;             const bool last = (t == nt - 2);
;             const char* a1 = cA + (size_t)(t + 1) * kstep;
;             const char* a2 = last ? nA : cA + (size_t)(t + 2) * kstep; const char* b2 = last ? nB : cB + (size_t)(t + 2) * kstep;
;             const char* a3 = a2 + kstep; const char* b3 = b2 + kstep;
;             if (last && has_next) S.a_ready(nxt);
;             if constexpr (SP2) {
;             PG8_LDB(B0, 0, 0); PG8_LDB(B1, 0, 1); PG8_SCHED; PG8_LDA(At, 0, 0); PG8_STAGE(PG8_SA(1, 1), a1 + hstep, voffA);
;             PG8_WAIT_V(8); PG8_WAIT_L(0); PG8_BAR; PG8_MMA(0, 0, At, B0); PG8_MMA(0, 1, At, B1); PG8_BAR; PG8_SCHED;
;             PG8_LDA(At, 0, 1); PG8_STAGE(PG8_SB(0, 0), b2, voffB); PG8_STAGE(PG8_SB(0, 1), b2 + hstep, voffB); PG8_STAGE(PG8_SA(0, 0), a2, voffA);
;             PG8_WAIT_V(8); PG8_WAIT_L(0); PG8_BAR; PG8_MMA(1, 0, At, B0); PG8_MMA(1, 1, At, B1); PG8_BAR; PG8_SCHED;
.LBB0_1121:
	s_add_u32 s5, s56, 0x100
	s_addc_u32 s49, s57, 0
	s_add_u32 s56, s58, 0x40080
	s_addc_u32 s57, s59, 0
	s_mov_b32 s51, -2
	ds_read_b128 v[130:133], v139
	ds_read_b128 v[134:137], v139 offset:1024
	ds_read_b128 v[162:165], v139 offset:2048
	ds_read_b128 v[166:169], v139 offset:3072
	ds_read_b128 v[176:179], v173
	ds_read_b128 v[180:183], v173 offset:1024
	ds_read_b128 v[184:187], v173 offset:2048
	ds_read_b128 v[192:195], v173 offset:3072
	s_add_u32 s15, s56, 0xfffc0080
	s_addc_u32 s18, s57, -1
	s_cmp_eq_u32 s51, 12
	s_cselect_b32 s61, s1, s18
	s_cselect_b32 s60, s0, s15
	s_cselect_b32 s59, s53, s49
	s_cselect_b32 s58, s52, s5
	v_lshl_add_u64 v[170:171], s[56:57], 0, v[156:157]
	s_add_i32 m0, s67, 0xc000
	ds_read_b128 v[196:199], v174
	ds_read_b128 v[200:203], v174 offset:1024
	ds_read_b128 v[204:207], v174 offset:2048
	ds_read_b128 v[208:211], v174 offset:3072
	ds_read_b128 v[212:215], v174 offset:4096
	ds_read_b128 v[216:219], v174 offset:5120
	ds_read_b128 v[220:223], v174 offset:6144
	ds_read_b128 v[224:227], v174 offset:7168
	global_load_lds_dwordx4 v[170:171], off
	v_lshl_add_u64 v[170:171], s[56:57], 0, v[154:155]
	s_add_i32 m0, s67, 0xe000
	s_nop 0
	global_load_lds_dwordx4 v[170:171], off
	s_waitcnt vmcnt(8)
	s_waitcnt lgkmcnt(0)
	s_barrier
	s_setprio 1
	s_waitcnt lgkmcnt(0)
	v_mfma_f32_16x16x32_bf16 v[126:129], v[130:133], v[196:199], 0
	v_mfma_f32_16x16x32_bf16 v[122:125], v[162:165], v[196:199], 0
	v_mfma_f32_16x16x32_bf16 v[110:113], v[130:133], v[204:207], 0
	v_mfma_f32_16x16x32_bf16 v[106:109], v[162:165], v[204:207], 0
	v_mfma_f32_16x16x32_bf16 v[94:97], v[130:133], v[212:215], 0
	v_mfma_f32_16x16x32_bf16 v[90:93], v[162:165], v[212:215], 0
	v_mfma_f32_16x16x32_bf16 v[78:81], v[130:133], v[220:223], 0
	v_mfma_f32_16x16x32_bf16 v[74:77], v[162:165], v[220:223], 0
	v_mfma_f32_16x16x32_bf16 v[126:129], v[134:137], v[200:203], v[126:129]
	v_mfma_f32_16x16x32_bf16 v[122:125], v[166:169], v[200:203], v[122:125]
	v_mfma_f32_16x16x32_bf16 v[110:113], v[134:137], v[208:211], v[110:113]
	v_mfma_f32_16x16x32_bf16 v[106:109], v[166:169], v[208:211], v[106:109]
	v_mfma_f32_16x16x32_bf16 v[94:97], v[134:137], v[216:219], v[94:97]
	v_mfma_f32_16x16x32_bf16 v[90:93], v[166:169], v[216:219], v[90:93]
	v_mfma_f32_16x16x32_bf16 v[78:81], v[134:137], v[224:227], v[78:81]
	v_mfma_f32_16x16x32_bf16 v[74:77], v[166:169], v[224:227], v[74:77]
	s_setprio 0
	s_setprio 1
	v_mfma_f32_16x16x32_bf16 v[118:121], v[176:179], v[196:199], 0
	v_mfma_f32_16x16x32_bf16 v[114:117], v[184:187], v[196:199], 0
	v_mfma_f32_16x16x32_bf16 v[102:105], v[176:179], v[204:207], 0
	v_mfma_f32_16x16x32_bf16 v[98:101], v[184:187], v[204:207], 0
	v_mfma_f32_16x16x32_bf16 v[86:89], v[176:179], v[212:215], 0
	v_mfma_f32_16x16x32_bf16 v[82:85], v[184:187], v[212:215], 0
	v_mfma_f32_16x16x32_bf16 v[70:73], v[176:179], v[220:223], 0
	v_mfma_f32_16x16x32_bf16 v[66:69], v[184:187], v[220:223], 0
	v_mfma_f32_16x16x32_bf16 v[118:121], v[180:183], v[200:203], v[118:121]
	v_mfma_f32_16x16x32_bf16 v[114:117], v[192:195], v[200:203], v[114:117]
	v_mfma_f32_16x16x32_bf16 v[102:105], v[180:183], v[208:211], v[102:105]
	v_mfma_f32_16x16x32_bf16 v[98:101], v[192:195], v[208:211], v[98:101]
	v_mfma_f32_16x16x32_bf16 v[86:89], v[180:183], v[216:219], v[86:89]
	v_mfma_f32_16x16x32_bf16 v[82:85], v[192:195], v[216:219], v[82:85]
	v_mfma_f32_16x16x32_bf16 v[70:73], v[180:183], v[224:227], v[70:73]
	v_mfma_f32_16x16x32_bf16 v[66:69], v[192:195], v[224:227], v[66:69]
	s_setprio 0
	s_barrier
	s_add_i32 s15, s86, s66
	v_lshl_add_u64 v[170:171], s[58:59], 0, v[142:143]
	s_mov_b32 m0, s15
	ds_read_b128 v[196:199], v174 offset:16384
	ds_read_b128 v[200:203], v174 offset:17408
	ds_read_b128 v[204:207], v174 offset:18432
	ds_read_b128 v[208:211], v174 offset:19456
	ds_read_b128 v[212:215], v174 offset:20480
	ds_read_b128 v[216:219], v174 offset:21504
	ds_read_b128 v[220:223], v174 offset:22528
	ds_read_b128 v[224:227], v174 offset:23552
	global_load_lds_dwordx4 v[170:171], off
	s_add_i32 m0, s15, 0x2000
	s_add_u32 s18, s58, 0x40000
	v_lshl_add_u64 v[188:189], s[58:59], 0, v[146:147]
	s_addc_u32 s19, s59, 0
	s_add_i32 s15, s87, s66
	global_load_lds_dwordx4 v[188:189], off
	v_lshl_add_u64 v[228:229], s[18:19], 0, v[142:143]
	s_mov_b32 m0, s15
	v_lshl_add_u64 v[230:231], s[60:61], 0, v[144:145]
	global_load_lds_dwordx4 v[228:229], off
	v_lshl_add_u64 v[228:229], s[18:19], 0, v[146:147]
	s_add_i32 m0, s15, 0x2000
	s_nop 0
	global_load_lds_dwordx4 v[228:229], off
	v_lshl_add_u64 v[228:229], s[60:61], 0, v[140:141]
	s_mov_b32 m0, s67
	s_nop 0
	global_load_lds_dwordx4 v[228:229], off
	s_mov_b32 m0, s68
	s_nop 0
	global_load_lds_dwordx4 v[230:231], off
	s_waitcnt vmcnt(8)
	s_waitcnt lgkmcnt(0)
	s_barrier
; #define PG8_STAGE(bufoff, gbase, voff) do { _Pragma("unroll") for (int _i = 0; _i < 2; ++_i) \
;         __builtin_amdgcn_global_load_lds((const unsigned*)((const char*)(gbase) + (voff)[_i]), (PG8_LAS unsigned*)(lds + (bufoff) + ldsw + _i * 8192), 16, 0, 0); } while (0)
; #define PG8_LDA(dst, b, h) do { _Pragma("unroll") for (int m = 0; m < 4; ++m) _Pragma("unroll") for (int k = 0; k < 2; ++k) dst[m][k] = *(const PG8_LAS bf16x8*)(lds + PG8_SA(b, h) + aoff + m * 2048 + k * 1024); } while (0)
; #define PG8_LDB(dst, b, h) do { _Pragma("unroll") for (int n = 0; n < 2; ++n) _Pragma("unroll") for (int k = 0; k < 2; ++k) dst[n][k] = *(const PG8_LAS bf16x8*)(lds + PG8_SB(b, h) + boff + n * 2048 + k * 1024); } while (0)
; #define PG8_MMA(ai, bj, At, Bt) do { __builtin_amdgcn_s_setprio(1); _Pragma("unroll") for (int m = 0; m < 4; ++m) _Pragma("unroll") for (int n = 0; n < 2; ++n) _Pragma("unroll") for (int k = 0; k < 2; ++k) \
;         acc[ai][bj][m][n] = __builtin_amdgcn_mfma_f32_16x16x32_bf16(Bt[n][k], At[m][k], acc[ai][bj][m][n], 0, 0, 0); __builtin_amdgcn_s_setprio(0); } while (0)
; #define PG8_WAIT_V(n) asm volatile("s_waitcnt vmcnt(" #n ")" ::: "memory")
; #define PG8_WAIT_L(n) asm volatile("s_waitcnt lgkmcnt(" #n ")" ::: "memory")
; #define PG8_BAR __builtin_amdgcn_s_barrier()
; #define PG8_SCHED __builtin_amdgcn_sched_barrier(0)
; template <class Epi, class Sched, bool ALIGN_EPI = false, bool SP2 = false>
; __device__ __forceinline__ void gemm_phase(PG8_LAS unsigned char* lds, const Gemm g, const Sched& S, const Epi& E, const int tid) {
;     ...
;             PG8_WAIT_V(8); PG8_WAIT_L(0); PG8_BAR; PG8_MMA(1, 0, At, B0); PG8_MMA(1, 1, At, B1); PG8_BAR; PG8_SCHED;
;             PG8_LDB(B0, 1, 0); PG8_LDB(B1, 1, 1); PG8_SCHED; PG8_LDA(At, 1, 0); PG8_STAGE(PG8_SA(0, 1), a2 + hstep, voffA);
;             PG8_WAIT_V(8); PG8_WAIT_L(0); PG8_BAR; PG8_MMA(0, 0, At, B0); PG8_MMA(0, 1, At, B1); PG8_BAR; PG8_SCHED;
	s_setprio 1
	s_waitcnt lgkmcnt(0)
	v_mfma_f32_16x16x32_bf16 v[62:65], v[130:133], v[196:199], 0
	v_mfma_f32_16x16x32_bf16 v[58:61], v[162:165], v[196:199], 0
	v_mfma_f32_16x16x32_bf16 v[46:49], v[130:133], v[204:207], 0
	v_mfma_f32_16x16x32_bf16 v[42:45], v[162:165], v[204:207], 0
	v_mfma_f32_16x16x32_bf16 v[30:33], v[130:133], v[212:215], 0
	v_mfma_f32_16x16x32_bf16 v[26:29], v[162:165], v[212:215], 0
	v_mfma_f32_16x16x32_bf16 v[14:17], v[130:133], v[220:223], 0
	v_mfma_f32_16x16x32_bf16 v[10:13], v[162:165], v[220:223], 0
	v_mfma_f32_16x16x32_bf16 v[62:65], v[134:137], v[200:203], v[62:65]
	v_mfma_f32_16x16x32_bf16 v[58:61], v[166:169], v[200:203], v[58:61]
	v_mfma_f32_16x16x32_bf16 v[46:49], v[134:137], v[208:211], v[46:49]
	v_mfma_f32_16x16x32_bf16 v[42:45], v[166:169], v[208:211], v[42:45]
	v_mfma_f32_16x16x32_bf16 v[30:33], v[134:137], v[216:219], v[30:33]
	v_mfma_f32_16x16x32_bf16 v[26:29], v[166:169], v[216:219], v[26:29]
	v_mfma_f32_16x16x32_bf16 v[14:17], v[134:137], v[224:227], v[14:17]
	v_mfma_f32_16x16x32_bf16 v[10:13], v[166:169], v[224:227], v[10:13]
	s_setprio 0
	s_setprio 1
	v_mfma_f32_16x16x32_bf16 v[54:57], v[176:179], v[196:199], 0
	v_mfma_f32_16x16x32_bf16 v[50:53], v[184:187], v[196:199], 0
	v_mfma_f32_16x16x32_bf16 v[38:41], v[176:179], v[204:207], 0
	v_mfma_f32_16x16x32_bf16 v[34:37], v[184:187], v[204:207], 0
	v_mfma_f32_16x16x32_bf16 v[22:25], v[176:179], v[212:215], 0
	v_mfma_f32_16x16x32_bf16 v[18:21], v[184:187], v[212:215], 0
	v_mfma_f32_16x16x32_bf16 v[6:9], v[176:179], v[220:223], 0
	v_mfma_f32_16x16x32_bf16 v[2:5], v[184:187], v[220:223], 0
	v_mfma_f32_16x16x32_bf16 v[54:57], v[180:183], v[200:203], v[54:57]
	v_mfma_f32_16x16x32_bf16 v[50:53], v[192:195], v[200:203], v[50:53]
	v_mfma_f32_16x16x32_bf16 v[38:41], v[180:183], v[208:211], v[38:41]
	v_mfma_f32_16x16x32_bf16 v[34:37], v[192:195], v[208:211], v[34:37]
	v_mfma_f32_16x16x32_bf16 v[22:25], v[180:183], v[216:219], v[22:25]
	v_mfma_f32_16x16x32_bf16 v[18:21], v[192:195], v[216:219], v[18:21]
	v_mfma_f32_16x16x32_bf16 v[6:9], v[180:183], v[224:227], v[6:9]
	v_mfma_f32_16x16x32_bf16 v[2:5], v[192:195], v[224:227], v[2:5]
	s_setprio 0
	s_barrier
	s_add_i32 s15, 0, 0x18000
	s_add_i32 s62, 0, 0x1c000
	v_add_u32_e32 v166, s15, v172
	v_add_u32_e32 v191, s62, v172
	ds_read_b128 v[130:133], v166
	ds_read_b128 v[134:137], v166 offset:1024
	ds_read_b128 v[162:165], v166 offset:2048
	ds_read_b128 v[166:169], v166 offset:3072
	ds_read_b128 v[176:179], v191
	ds_read_b128 v[180:183], v191 offset:1024
	ds_read_b128 v[184:187], v191 offset:2048
	ds_read_b128 v[192:195], v191 offset:3072
	s_add_u32 s18, s60, 0x40000
	s_addc_u32 s19, s61, 0
	s_mov_b32 m0, s69
	v_lshl_add_u64 v[232:233], s[18:19], 0, v[140:141]
	ds_read_b128 v[196:199], v174 offset:32768
	ds_read_b128 v[200:203], v174 offset:33792
	ds_read_b128 v[204:207], v174 offset:34816
	ds_read_b128 v[208:211], v174 offset:35840
	ds_read_b128 v[212:215], v174 offset:36864
	ds_read_b128 v[216:219], v174 offset:37888
	ds_read_b128 v[220:223], v174 offset:38912
	ds_read_b128 v[224:227], v174 offset:39936
	global_load_lds_dwordx4 v[232:233], off
	v_lshl_add_u64 v[232:233], s[18:19], 0, v[144:145]
	s_mov_b32 m0, s71
	s_nop 0
	global_load_lds_dwordx4 v[232:233], off
	s_waitcnt vmcnt(8)
	s_waitcnt lgkmcnt(0)
	s_barrier
	s_setprio 1
	s_waitcnt lgkmcnt(0)
	v_mfma_f32_16x16x32_bf16 v[126:129], v[130:133], v[196:199], v[126:129]
	v_mfma_f32_16x16x32_bf16 v[122:125], v[162:165], v[196:199], v[122:125]
	v_mfma_f32_16x16x32_bf16 v[110:113], v[130:133], v[204:207], v[110:113]
	v_mfma_f32_16x16x32_bf16 v[106:109], v[162:165], v[204:207], v[106:109]
	v_mfma_f32_16x16x32_bf16 v[94:97], v[130:133], v[212:215], v[94:97]
	v_mfma_f32_16x16x32_bf16 v[90:93], v[162:165], v[212:215], v[90:93]
	v_mfma_f32_16x16x32_bf16 v[78:81], v[130:133], v[220:223], v[78:81]
	v_mfma_f32_16x16x32_bf16 v[74:77], v[162:165], v[220:223], v[74:77]
	v_mfma_f32_16x16x32_bf16 v[126:129], v[134:137], v[200:203], v[126:129]
	v_mfma_f32_16x16x32_bf16 v[122:125], v[166:169], v[200:203], v[122:125]
	v_mfma_f32_16x16x32_bf16 v[110:113], v[134:137], v[208:211], v[110:113]
	v_mfma_f32_16x16x32_bf16 v[106:109], v[166:169], v[208:211], v[106:109]
	v_mfma_f32_16x16x32_bf16 v[94:97], v[134:137], v[216:219], v[94:97]
	v_mfma_f32_16x16x32_bf16 v[90:93], v[166:169], v[216:219], v[90:93]
	v_mfma_f32_16x16x32_bf16 v[78:81], v[134:137], v[224:227], v[78:81]
	v_mfma_f32_16x16x32_bf16 v[74:77], v[166:169], v[224:227], v[74:77]
	s_setprio 0
	s_setprio 1
	v_mfma_f32_16x16x32_bf16 v[118:121], v[176:179], v[196:199], v[118:121]
	v_mfma_f32_16x16x32_bf16 v[114:117], v[184:187], v[196:199], v[114:117]
	v_mfma_f32_16x16x32_bf16 v[102:105], v[176:179], v[204:207], v[102:105]
	v_mfma_f32_16x16x32_bf16 v[98:101], v[184:187], v[204:207], v[98:101]
	v_mfma_f32_16x16x32_bf16 v[86:89], v[176:179], v[212:215], v[86:89]
	v_mfma_f32_16x16x32_bf16 v[82:85], v[184:187], v[212:215], v[82:85]
	v_mfma_f32_16x16x32_bf16 v[70:73], v[176:179], v[220:223], v[70:73]
	v_mfma_f32_16x16x32_bf16 v[66:69], v[184:187], v[220:223], v[66:69]
	v_mfma_f32_16x16x32_bf16 v[118:121], v[180:183], v[200:203], v[118:121]
	v_mfma_f32_16x16x32_bf16 v[114:117], v[192:195], v[200:203], v[114:117]
	v_mfma_f32_16x16x32_bf16 v[102:105], v[180:183], v[208:211], v[102:105]
	v_mfma_f32_16x16x32_bf16 v[98:101], v[192:195], v[208:211], v[98:101]
	v_mfma_f32_16x16x32_bf16 v[86:89], v[180:183], v[216:219], v[86:89]
	v_mfma_f32_16x16x32_bf16 v[82:85], v[192:195], v[216:219], v[82:85]
	v_mfma_f32_16x16x32_bf16 v[70:73], v[180:183], v[224:227], v[70:73]
	v_mfma_f32_16x16x32_bf16 v[66:69], v[192:195], v[224:227], v[66:69]
	s_setprio 0
	s_barrier
; #define PG8_STAGE(bufoff, gbase, voff) do { _Pragma("unroll") for (int _i = 0; _i < 2; ++_i) \
;         __builtin_amdgcn_global_load_lds((const unsigned*)((const char*)(gbase) + (voff)[_i]), (PG8_LAS unsigned*)(lds + (bufoff) + ldsw + _i * 8192), 16, 0, 0); } while (0)
; #define PG8_LDA(dst, b, h) do { _Pragma("unroll") for (int m = 0; m < 4; ++m) _Pragma("unroll") for (int k = 0; k < 2; ++k) dst[m][k] = *(const PG8_LAS bf16x8*)(lds + PG8_SA(b, h) + aoff + m * 2048 + k * 1024); } while (0)
; #define PG8_MMA(ai, bj, At, Bt) do { __builtin_amdgcn_s_setprio(1); _Pragma("unroll") for (int m = 0; m < 4; ++m) _Pragma("unroll") for (int n = 0; n < 2; ++n) _Pragma("unroll") for (int k = 0; k < 2; ++k) \
;         acc[ai][bj][m][n] = __builtin_amdgcn_mfma_f32_16x16x32_bf16(Bt[n][k], At[m][k], acc[ai][bj][m][n], 0, 0, 0); __builtin_amdgcn_s_setprio(0); } while (0)
; #define PG8_WAIT_V(n) asm volatile("s_waitcnt vmcnt(" #n ")" ::: "memory")
; #define PG8_WAIT_L(n) asm volatile("s_waitcnt lgkmcnt(" #n ")" ::: "memory")
; #define PG8_BAR __builtin_amdgcn_s_barrier()
; #define PG8_SCHED __builtin_amdgcn_sched_barrier(0)
; template <class Epi, class Sched, bool ALIGN_EPI = false, bool SP2 = false>
; __device__ __forceinline__ void gemm_phase(PG8_LAS unsigned char* lds, const Gemm g, const Sched& S, const Epi& E, const int tid) {
;     ...
;         for (int t = 0; t < nt; t += 2) {
;             const bool last = (t == nt - 2);
;             const char* a1 = cA + (size_t)(t + 1) * kstep;
;             const char* a2 = last ? nA : cA + (size_t)(t + 2) * kstep; const char* b2 = last ? nB : cB + (size_t)(t + 2) * kstep;
;             const char* a3 = a2 + kstep; const char* b3 = b2 + kstep;
;     ...
;             PG8_LDA(At, 1, 1); PG8_STAGE(PG8_SB(1, 0), b3, voffB); PG8_STAGE(PG8_SB(1, 1), b3 + hstep, voffB); PG8_STAGE(PG8_SA(1, 0), a3, voffA);
;             PG8_WAIT_V(8); PG8_WAIT_L(0); PG8_BAR; PG8_MMA(1, 0, At, B0); PG8_MMA(1, 1, At, B1); PG8_BAR; PG8_SCHED;
	s_add_i32 s15, s15, s66
	v_lshl_add_u64 v[170:171], v[170:171], 0, s[44:45]
	s_mov_b32 m0, s15
	ds_read_b128 v[196:199], v174 offset:49152
	ds_read_b128 v[200:203], v174 offset:50176
	ds_read_b128 v[204:207], v174 offset:51200
	ds_read_b128 v[208:211], v174 offset:52224
	ds_read_b128 v[212:215], v174 offset:53248
	ds_read_b128 v[216:219], v174 offset:54272
	ds_read_b128 v[220:223], v174 offset:55296
	ds_read_b128 v[224:227], v174 offset:56320
	global_load_lds_dwordx4 v[170:171], off
	s_add_i32 m0, s15, 0x2000
	s_add_u32 s18, s58, 0x40080
	v_lshl_add_u64 v[170:171], v[188:189], 0, s[44:45]
	s_addc_u32 s19, s59, 0
	s_add_i32 s15, s62, s66
	global_load_lds_dwordx4 v[170:171], off
	v_lshl_add_u64 v[170:171], s[18:19], 0, v[142:143]
	s_mov_b32 m0, s15
	s_nop 0
	global_load_lds_dwordx4 v[170:171], off
	v_lshl_add_u64 v[170:171], s[18:19], 0, v[146:147]
	s_add_i32 m0, s15, 0x2000
	s_nop 0
	global_load_lds_dwordx4 v[170:171], off
	v_lshl_add_u64 v[170:171], v[228:229], 0, s[44:45]
	s_mov_b32 m0, s77
	s_nop 0
	global_load_lds_dwordx4 v[170:171], off
	v_lshl_add_u64 v[170:171], v[230:231], 0, s[44:45]
	s_mov_b32 m0, s78
	s_nop 0
	global_load_lds_dwordx4 v[170:171], off
	s_waitcnt vmcnt(8)
	s_waitcnt lgkmcnt(0)
	s_barrier
	s_setprio 1
	s_waitcnt lgkmcnt(0)
	v_mfma_f32_16x16x32_bf16 v[62:65], v[130:133], v[196:199], v[62:65]
	v_mfma_f32_16x16x32_bf16 v[58:61], v[162:165], v[196:199], v[58:61]
	v_mfma_f32_16x16x32_bf16 v[46:49], v[130:133], v[204:207], v[46:49]
	v_mfma_f32_16x16x32_bf16 v[42:45], v[162:165], v[204:207], v[42:45]
	v_mfma_f32_16x16x32_bf16 v[30:33], v[130:133], v[212:215], v[30:33]
	v_mfma_f32_16x16x32_bf16 v[26:29], v[162:165], v[212:215], v[26:29]
	v_mfma_f32_16x16x32_bf16 v[14:17], v[130:133], v[220:223], v[14:17]
	v_mfma_f32_16x16x32_bf16 v[10:13], v[162:165], v[220:223], v[10:13]
	v_mfma_f32_16x16x32_bf16 v[62:65], v[134:137], v[200:203], v[62:65]
	v_mfma_f32_16x16x32_bf16 v[58:61], v[166:169], v[200:203], v[58:61]
	v_mfma_f32_16x16x32_bf16 v[46:49], v[134:137], v[208:211], v[46:49]
	v_mfma_f32_16x16x32_bf16 v[42:45], v[166:169], v[208:211], v[42:45]
	v_mfma_f32_16x16x32_bf16 v[30:33], v[134:137], v[216:219], v[30:33]
	v_mfma_f32_16x16x32_bf16 v[26:29], v[166:169], v[216:219], v[26:29]
	v_mfma_f32_16x16x32_bf16 v[14:17], v[134:137], v[224:227], v[14:17]
	v_mfma_f32_16x16x32_bf16 v[10:13], v[166:169], v[224:227], v[10:13]
	s_setprio 0
	s_setprio 1
	v_mfma_f32_16x16x32_bf16 v[54:57], v[176:179], v[196:199], v[54:57]
	v_mfma_f32_16x16x32_bf16 v[50:53], v[184:187], v[196:199], v[50:53]
	v_mfma_f32_16x16x32_bf16 v[38:41], v[176:179], v[204:207], v[38:41]
	v_mfma_f32_16x16x32_bf16 v[34:37], v[184:187], v[204:207], v[34:37]
	v_mfma_f32_16x16x32_bf16 v[22:25], v[176:179], v[212:215], v[22:25]
	v_mfma_f32_16x16x32_bf16 v[18:21], v[184:187], v[212:215], v[18:21]
	v_mfma_f32_16x16x32_bf16 v[6:9], v[176:179], v[220:223], v[6:9]
	v_mfma_f32_16x16x32_bf16 v[2:5], v[184:187], v[220:223], v[2:5]
	v_mfma_f32_16x16x32_bf16 v[54:57], v[180:183], v[200:203], v[54:57]
	v_mfma_f32_16x16x32_bf16 v[50:53], v[192:195], v[200:203], v[50:53]
	v_mfma_f32_16x16x32_bf16 v[38:41], v[180:183], v[208:211], v[38:41]
	v_mfma_f32_16x16x32_bf16 v[34:37], v[192:195], v[208:211], v[34:37]
	v_mfma_f32_16x16x32_bf16 v[22:25], v[180:183], v[216:219], v[22:25]
	v_mfma_f32_16x16x32_bf16 v[18:21], v[192:195], v[216:219], v[18:21]
	v_mfma_f32_16x16x32_bf16 v[6:9], v[180:183], v[224:227], v[6:9]
	v_mfma_f32_16x16x32_bf16 v[2:5], v[192:195], v[224:227], v[2:5]
	s_setprio 0
	s_barrier
	s_add_i32 s51, s51, 2
	s_add_u32 s5, s5, 0x100
	s_addc_u32 s49, s49, 0
	s_add_u32 s56, s56, 0x100
	s_addc_u32 s57, s57, 0

; #define PG8_STAGE(bufoff, gbase, voff) do { _Pragma("unroll") for (int _i = 0; _i < 2; ++_i) \
;         __builtin_amdgcn_global_load_lds((const unsigned*)((const char*)(gbase) + (voff)[_i]), (PG8_LAS unsigned*)(lds + (bufoff) + ldsw + _i * 8192), 16, 0, 0); } while (0)
; #define PG8_LDA(dst, b, h) do { _Pragma("unroll") for (int m = 0; m < 4; ++m) _Pragma("unroll") for (int k = 0; k < 2; ++k) dst[m][k] = *(const PG8_LAS bf16x8*)(lds + PG8_SA(b, h) + aoff + m * 2048 + k * 1024); } while (0)
; #define PG8_LDB(dst, b, h) do { _Pragma("unroll") for (int n = 0; n < 2; ++n) _Pragma("unroll") for (int k = 0; k < 2; ++k) dst[n][k] = *(const PG8_LAS bf16x8*)(lds + PG8_SB(b, h) + boff + n * 2048 + k * 1024); } while (0)
; #define PG8_WAIT_V(n) asm volatile("s_waitcnt vmcnt(" #n ")" ::: "memory")
; #define PG8_WAIT_L(n) asm volatile("s_waitcnt lgkmcnt(" #n ")" ::: "memory")
; #define PG8_BAR __builtin_amdgcn_s_barrier()
; #define PG8_SCHED __builtin_amdgcn_sched_barrier(0)
; template <class Epi, class Sched, bool ALIGN_EPI = false, bool SP2 = false>
; __device__ __forceinline__ void gemm_phase(PG8_LAS unsigned char* lds, const Gemm g, const Sched& S, const Epi& E, const int tid) {
;     ...
;         const bool has_next = S.next(ui + 1, nxt);
;         const char* nA = has_next ? S.aptr(nxt) : cA; const char* nB = has_next ? S.bptr(nxt) : cB;
;         for (int t = 0; t < nt; t += 2) {
;             const bool last = (t == nt - 2);
;             const char* a1 = cA + (size_t)(t + 1) * kstep;
;             const char* a2 = last ? nA : cA + (size_t)(t + 2) * kstep; const char* b2 = last ? nB : cB + (size_t)(t + 2) * kstep;
;             const char* a3 = a2 + kstep; const char* b3 = b2 + kstep;
;             if (last && has_next) S.a_ready(nxt);
;             if constexpr (SP2) {
;             PG8_LDB(B0, 0, 0); PG8_LDB(B1, 0, 1); PG8_SCHED; PG8_LDA(At, 0, 0); PG8_STAGE(PG8_SA(1, 1), a1 + hstep, voffA);
;             PG8_WAIT_V(8); PG8_WAIT_L(0); PG8_BAR; PG8_MMA(0, 0, At, B0); PG8_MMA(0, 1, At, B1); PG8_BAR; PG8_SCHED;
;             PG8_LDA(At, 0, 1); PG8_STAGE(PG8_SB(0, 0), b2, voffB); PG8_STAGE(PG8_SB(0, 1), b2 + hstep, voffB); PG8_STAGE(PG8_SA(0, 0), a2, voffA);
;             PG8_WAIT_V(8); PG8_WAIT_L(0); PG8_BAR; PG8_MMA(1, 0, At, B0); PG8_MMA(1, 1, At, B1); PG8_BAR; PG8_SCHED;
.LBB0_1373:
	s_ashr_i32 s39, s38, 31
	s_lshl_b64 s[18:19], s[38:39], 19
	s_add_u32 s40, s52, s18
	s_addc_u32 s41, s53, s19
	s_and_b64 s[18:19], s[4:5], exec
	s_cselect_b32 s7, s41, s11
	s_cselect_b32 s39, s40, s10
	s_ashr_i32 s37, s36, 31
	s_lshl_b64 s[18:19], s[36:37], 19
	s_add_u32 s42, s54, s18
	s_addc_u32 s43, s55, s19
	s_and_b64 s[18:19], s[4:5], exec
	s_cselect_b32 s37, s43, s9
	s_cselect_b32 s45, s42, s8
	s_add_u32 s48, s8, 0x100
	s_addc_u32 s49, s9, 0
	s_add_u32 s8, s10, 0x40080
	s_addc_u32 s9, s11, 0
	s_mov_b32 s76, -2
	ds_read_b128 v[130:133], v204
	ds_read_b128 v[134:137], v204 offset:1024
	ds_read_b128 v[138:141], v204 offset:2048
	ds_read_b128 v[142:145], v204 offset:3072
	ds_read_b128 v[146:149], v205
	ds_read_b128 v[150:153], v205 offset:1024
	ds_read_b128 v[154:157], v205 offset:2048
	ds_read_b128 v[158:161], v205 offset:3072
	s_add_u32 s10, s8, 0xfffc0080
	s_addc_u32 s11, s9, -1
	s_cmp_eq_u32 s76, 12
	s_cselect_b32 s47, s7, s11
	s_cselect_b32 s46, s39, s10
	s_cselect_b32 s11, s37, s49
	s_cselect_b32 s10, s45, s48
	v_lshl_add_u64 v[220:221], s[8:9], 0, v[176:177]
	s_add_i32 m0, s57, 0xc000
	ds_read_b128 v[182:185], v206
	ds_read_b128 v[186:189], v206 offset:1024
	ds_read_b128 v[192:195], v206 offset:2048
	ds_read_b128 v[196:199], v206 offset:3072
	ds_read_b128 v[200:203], v206 offset:4096
	ds_read_b128 v[208:211], v206 offset:5120
	ds_read_b128 v[212:215], v206 offset:6144
	ds_read_b128 v[216:219], v206 offset:7168
	global_load_lds_dwordx4 v[220:221], off
	v_lshl_add_u64 v[220:221], s[8:9], 0, v[174:175]
	s_add_i32 m0, s57, 0xe000
	s_nop 0
	global_load_lds_dwordx4 v[220:221], off
	s_waitcnt vmcnt(8)
	s_waitcnt lgkmcnt(0)
	s_barrier
	s_setprio 1
	s_waitcnt lgkmcnt(0)
	v_mfma_f32_16x16x32_bf16 v[126:129], v[130:133], v[182:185], 0
	v_mfma_f32_16x16x32_bf16 v[122:125], v[138:141], v[182:185], 0
	v_mfma_f32_16x16x32_bf16 v[110:113], v[130:133], v[192:195], 0
	v_mfma_f32_16x16x32_bf16 v[106:109], v[138:141], v[192:195], 0
	v_mfma_f32_16x16x32_bf16 v[94:97], v[130:133], v[200:203], 0
	v_mfma_f32_16x16x32_bf16 v[90:93], v[138:141], v[200:203], 0
	v_mfma_f32_16x16x32_bf16 v[78:81], v[130:133], v[212:215], 0
	v_mfma_f32_16x16x32_bf16 v[74:77], v[138:141], v[212:215], 0
	v_mfma_f32_16x16x32_bf16 v[126:129], v[134:137], v[186:189], v[126:129]
	v_mfma_f32_16x16x32_bf16 v[122:125], v[142:145], v[186:189], v[122:125]
	v_mfma_f32_16x16x32_bf16 v[110:113], v[134:137], v[196:199], v[110:113]
	v_mfma_f32_16x16x32_bf16 v[106:109], v[142:145], v[196:199], v[106:109]
	v_mfma_f32_16x16x32_bf16 v[94:97], v[134:137], v[208:211], v[94:97]
	v_mfma_f32_16x16x32_bf16 v[90:93], v[142:145], v[208:211], v[90:93]
	v_mfma_f32_16x16x32_bf16 v[78:81], v[134:137], v[216:219], v[78:81]
	v_mfma_f32_16x16x32_bf16 v[74:77], v[142:145], v[216:219], v[74:77]
	s_setprio 0
	s_setprio 1
	v_mfma_f32_16x16x32_bf16 v[118:121], v[146:149], v[182:185], 0
	v_mfma_f32_16x16x32_bf16 v[114:117], v[154:157], v[182:185], 0
	v_mfma_f32_16x16x32_bf16 v[102:105], v[146:149], v[192:195], 0
	v_mfma_f32_16x16x32_bf16 v[98:101], v[154:157], v[192:195], 0
	v_mfma_f32_16x16x32_bf16 v[86:89], v[146:149], v[200:203], 0
	v_mfma_f32_16x16x32_bf16 v[82:85], v[154:157], v[200:203], 0
	v_mfma_f32_16x16x32_bf16 v[70:73], v[146:149], v[212:215], 0
	v_mfma_f32_16x16x32_bf16 v[66:69], v[154:157], v[212:215], 0
	v_mfma_f32_16x16x32_bf16 v[118:121], v[150:153], v[186:189], v[118:121]
	v_mfma_f32_16x16x32_bf16 v[114:117], v[158:161], v[186:189], v[114:117]
	v_mfma_f32_16x16x32_bf16 v[102:105], v[150:153], v[196:199], v[102:105]
	v_mfma_f32_16x16x32_bf16 v[98:101], v[158:161], v[196:199], v[98:101]
	v_mfma_f32_16x16x32_bf16 v[86:89], v[150:153], v[208:211], v[86:89]
	v_mfma_f32_16x16x32_bf16 v[82:85], v[158:161], v[208:211], v[82:85]
	v_mfma_f32_16x16x32_bf16 v[70:73], v[150:153], v[216:219], v[70:73]
	v_mfma_f32_16x16x32_bf16 v[66:69], v[158:161], v[216:219], v[66:69]
	s_setprio 0
	s_barrier
	s_add_i32 s15, s67, s56
	v_lshl_add_u64 v[220:221], s[10:11], 0, v[164:165]
	s_mov_b32 m0, s15
	ds_read_b128 v[182:185], v206 offset:16384
	ds_read_b128 v[186:189], v206 offset:17408
	ds_read_b128 v[192:195], v206 offset:18432
	ds_read_b128 v[196:199], v206 offset:19456
	ds_read_b128 v[200:203], v206 offset:20480
	ds_read_b128 v[208:211], v206 offset:21504
	ds_read_b128 v[212:215], v206 offset:22528
	ds_read_b128 v[216:219], v206 offset:23552
	global_load_lds_dwordx4 v[220:221], off
	s_add_i32 m0, s15, 0x2000
	s_add_u32 s18, s10, 0x40000
	v_lshl_add_u64 v[222:223], s[10:11], 0, v[168:169]
	s_addc_u32 s19, s11, 0
	s_add_i32 s15, s68, s56
	global_load_lds_dwordx4 v[222:223], off
	v_lshl_add_u64 v[224:225], s[18:19], 0, v[164:165]
	s_mov_b32 m0, s15
	v_lshl_add_u64 v[226:227], s[46:47], 0, v[166:167]
	global_load_lds_dwordx4 v[224:225], off
	v_lshl_add_u64 v[224:225], s[18:19], 0, v[168:169]
	s_add_i32 m0, s15, 0x2000
	s_nop 0
	global_load_lds_dwordx4 v[224:225], off
	v_lshl_add_u64 v[224:225], s[46:47], 0, v[162:163]
	s_mov_b32 m0, s57
	s_nop 0
	global_load_lds_dwordx4 v[224:225], off
	s_mov_b32 m0, s58
	s_nop 0
	global_load_lds_dwordx4 v[226:227], off
	s_waitcnt vmcnt(8)
	s_waitcnt lgkmcnt(0)
	s_barrier
; #define PG8_STAGE(bufoff, gbase, voff) do { _Pragma("unroll") for (int _i = 0; _i < 2; ++_i) \
;         __builtin_amdgcn_global_load_lds((const unsigned*)((const char*)(gbase) + (voff)[_i]), (PG8_LAS unsigned*)(lds + (bufoff) + ldsw + _i * 8192), 16, 0, 0); } while (0)
; #define PG8_LDA(dst, b, h) do { _Pragma("unroll") for (int m = 0; m < 4; ++m) _Pragma("unroll") for (int k = 0; k < 2; ++k) dst[m][k] = *(const PG8_LAS bf16x8*)(lds + PG8_SA(b, h) + aoff + m * 2048 + k * 1024); } while (0)
; #define PG8_LDB(dst, b, h) do { _Pragma("unroll") for (int n = 0; n < 2; ++n) _Pragma("unroll") for (int k = 0; k < 2; ++k) dst[n][k] = *(const PG8_LAS bf16x8*)(lds + PG8_SB(b, h) + boff + n * 2048 + k * 1024); } while (0)
; #define PG8_MMA(ai, bj, At, Bt) do { __builtin_amdgcn_s_setprio(1); _Pragma("unroll") for (int m = 0; m < 4; ++m) _Pragma("unroll") for (int n = 0; n < 2; ++n) _Pragma("unroll") for (int k = 0; k < 2; ++k) \
;         acc[ai][bj][m][n] = __builtin_amdgcn_mfma_f32_16x16x32_bf16(Bt[n][k], At[m][k], acc[ai][bj][m][n], 0, 0, 0); __builtin_amdgcn_s_setprio(0); } while (0)
; #define PG8_WAIT_V(n) asm volatile("s_waitcnt vmcnt(" #n ")" ::: "memory")
; #define PG8_WAIT_L(n) asm volatile("s_waitcnt lgkmcnt(" #n ")" ::: "memory")
; #define PG8_BAR __builtin_amdgcn_s_barrier()
; #define PG8_SCHED __builtin_amdgcn_sched_barrier(0)
; template <class Epi, class Sched, bool ALIGN_EPI = false, bool SP2 = false>
; __device__ __forceinline__ void gemm_phase(PG8_LAS unsigned char* lds, const Gemm g, const Sched& S, const Epi& E, const int tid) {
;     ...
;             PG8_WAIT_V(8); PG8_WAIT_L(0); PG8_BAR; PG8_MMA(1, 0, At, B0); PG8_MMA(1, 1, At, B1); PG8_BAR; PG8_SCHED;
;             PG8_LDB(B0, 1, 0); PG8_LDB(B1, 1, 1); PG8_SCHED; PG8_LDA(At, 1, 0); PG8_STAGE(PG8_SA(0, 1), a2 + hstep, voffA);
;             PG8_WAIT_V(8); PG8_WAIT_L(0); PG8_BAR; PG8_MMA(0, 0, At, B0); PG8_MMA(0, 1, At, B1); PG8_BAR; PG8_SCHED;
	s_setprio 1
	s_waitcnt lgkmcnt(0)
	v_mfma_f32_16x16x32_bf16 v[62:65], v[130:133], v[182:185], 0
	v_mfma_f32_16x16x32_bf16 v[58:61], v[138:141], v[182:185], 0
	v_mfma_f32_16x16x32_bf16 v[46:49], v[130:133], v[192:195], 0
	v_mfma_f32_16x16x32_bf16 v[42:45], v[138:141], v[192:195], 0
	v_mfma_f32_16x16x32_bf16 v[30:33], v[130:133], v[200:203], 0
	v_mfma_f32_16x16x32_bf16 v[26:29], v[138:141], v[200:203], 0
	v_mfma_f32_16x16x32_bf16 v[14:17], v[130:133], v[212:215], 0
	v_mfma_f32_16x16x32_bf16 v[10:13], v[138:141], v[212:215], 0
	v_mfma_f32_16x16x32_bf16 v[62:65], v[134:137], v[186:189], v[62:65]
	v_mfma_f32_16x16x32_bf16 v[58:61], v[142:145], v[186:189], v[58:61]
	v_mfma_f32_16x16x32_bf16 v[46:49], v[134:137], v[196:199], v[46:49]
	v_mfma_f32_16x16x32_bf16 v[42:45], v[142:145], v[196:199], v[42:45]
	v_mfma_f32_16x16x32_bf16 v[30:33], v[134:137], v[208:211], v[30:33]
	v_mfma_f32_16x16x32_bf16 v[26:29], v[142:145], v[208:211], v[26:29]
	v_mfma_f32_16x16x32_bf16 v[14:17], v[134:137], v[216:219], v[14:17]
	v_mfma_f32_16x16x32_bf16 v[10:13], v[142:145], v[216:219], v[10:13]
	s_setprio 0
	s_setprio 1
	v_mfma_f32_16x16x32_bf16 v[54:57], v[146:149], v[182:185], 0
	v_mfma_f32_16x16x32_bf16 v[50:53], v[154:157], v[182:185], 0
	v_mfma_f32_16x16x32_bf16 v[38:41], v[146:149], v[192:195], 0
	v_mfma_f32_16x16x32_bf16 v[34:37], v[154:157], v[192:195], 0
	v_mfma_f32_16x16x32_bf16 v[22:25], v[146:149], v[200:203], 0
	v_mfma_f32_16x16x32_bf16 v[18:21], v[154:157], v[200:203], 0
	v_mfma_f32_16x16x32_bf16 v[6:9], v[146:149], v[212:215], 0
	v_mfma_f32_16x16x32_bf16 v[2:5], v[154:157], v[212:215], 0
	v_mfma_f32_16x16x32_bf16 v[54:57], v[150:153], v[186:189], v[54:57]
	v_mfma_f32_16x16x32_bf16 v[50:53], v[158:161], v[186:189], v[50:53]
	v_mfma_f32_16x16x32_bf16 v[38:41], v[150:153], v[196:199], v[38:41]
	v_mfma_f32_16x16x32_bf16 v[34:37], v[158:161], v[196:199], v[34:37]
	v_mfma_f32_16x16x32_bf16 v[22:25], v[150:153], v[208:211], v[22:25]
	v_mfma_f32_16x16x32_bf16 v[18:21], v[158:161], v[208:211], v[18:21]
	v_mfma_f32_16x16x32_bf16 v[6:9], v[150:153], v[216:219], v[6:9]
	v_mfma_f32_16x16x32_bf16 v[2:5], v[158:161], v[216:219], v[2:5]
	s_setprio 0
	s_barrier
	s_add_i32 s15, 0, 0x18000
	s_add_i32 s77, 0, 0x1c000
	v_add_u32_e32 v142, s15, v191
	v_add_u32_e32 v158, s77, v191
	ds_read_b128 v[130:133], v142
	ds_read_b128 v[134:137], v142 offset:1024
	ds_read_b128 v[138:141], v142 offset:2048
	ds_read_b128 v[142:145], v142 offset:3072
	ds_read_b128 v[146:149], v158
	ds_read_b128 v[150:153], v158 offset:1024
	ds_read_b128 v[154:157], v158 offset:2048
	ds_read_b128 v[158:161], v158 offset:3072
	s_add_u32 s18, s46, 0x40000
	s_addc_u32 s19, s47, 0
	s_mov_b32 m0, s59
	v_lshl_add_u64 v[228:229], s[18:19], 0, v[162:163]
	ds_read_b128 v[182:185], v206 offset:32768
	ds_read_b128 v[186:189], v206 offset:33792
	ds_read_b128 v[192:195], v206 offset:34816
	ds_read_b128 v[196:199], v206 offset:35840
	ds_read_b128 v[200:203], v206 offset:36864
	ds_read_b128 v[208:211], v206 offset:37888
	ds_read_b128 v[212:215], v206 offset:38912
	ds_read_b128 v[216:219], v206 offset:39936
	global_load_lds_dwordx4 v[228:229], off
	v_lshl_add_u64 v[228:229], s[18:19], 0, v[166:167]
	s_mov_b32 m0, s60
	s_nop 0
	global_load_lds_dwordx4 v[228:229], off
	s_waitcnt vmcnt(8)
	s_waitcnt lgkmcnt(0)
	s_barrier
	s_setprio 1
	s_waitcnt lgkmcnt(0)
	v_mfma_f32_16x16x32_bf16 v[126:129], v[130:133], v[182:185], v[126:129]
	v_mfma_f32_16x16x32_bf16 v[122:125], v[138:141], v[182:185], v[122:125]
	v_mfma_f32_16x16x32_bf16 v[110:113], v[130:133], v[192:195], v[110:113]
	v_mfma_f32_16x16x32_bf16 v[106:109], v[138:141], v[192:195], v[106:109]
	v_mfma_f32_16x16x32_bf16 v[94:97], v[130:133], v[200:203], v[94:97]
	v_mfma_f32_16x16x32_bf16 v[90:93], v[138:141], v[200:203], v[90:93]
	v_mfma_f32_16x16x32_bf16 v[78:81], v[130:133], v[212:215], v[78:81]
	v_mfma_f32_16x16x32_bf16 v[74:77], v[138:141], v[212:215], v[74:77]
	v_mfma_f32_16x16x32_bf16 v[126:129], v[134:137], v[186:189], v[126:129]
	v_mfma_f32_16x16x32_bf16 v[122:125], v[142:145], v[186:189], v[122:125]
	v_mfma_f32_16x16x32_bf16 v[110:113], v[134:137], v[196:199], v[110:113]
	v_mfma_f32_16x16x32_bf16 v[106:109], v[142:145], v[196:199], v[106:109]
	v_mfma_f32_16x16x32_bf16 v[94:97], v[134:137], v[208:211], v[94:97]
	v_mfma_f32_16x16x32_bf16 v[90:93], v[142:145], v[208:211], v[90:93]
	v_mfma_f32_16x16x32_bf16 v[78:81], v[134:137], v[216:219], v[78:81]
	v_mfma_f32_16x16x32_bf16 v[74:77], v[142:145], v[216:219], v[74:77]
	s_setprio 0
	s_setprio 1
	v_mfma_f32_16x16x32_bf16 v[118:121], v[146:149], v[182:185], v[118:121]
	v_mfma_f32_16x16x32_bf16 v[114:117], v[154:157], v[182:185], v[114:117]
	v_mfma_f32_16x16x32_bf16 v[102:105], v[146:149], v[192:195], v[102:105]
	v_mfma_f32_16x16x32_bf16 v[98:101], v[154:157], v[192:195], v[98:101]
	v_mfma_f32_16x16x32_bf16 v[86:89], v[146:149], v[200:203], v[86:89]
	v_mfma_f32_16x16x32_bf16 v[82:85], v[154:157], v[200:203], v[82:85]
	v_mfma_f32_16x16x32_bf16 v[70:73], v[146:149], v[212:215], v[70:73]
	v_mfma_f32_16x16x32_bf16 v[66:69], v[154:157], v[212:215], v[66:69]
	v_mfma_f32_16x16x32_bf16 v[118:121], v[150:153], v[186:189], v[118:121]
	v_mfma_f32_16x16x32_bf16 v[114:117], v[158:161], v[186:189], v[114:117]
	v_mfma_f32_16x16x32_bf16 v[102:105], v[150:153], v[196:199], v[102:105]
	v_mfma_f32_16x16x32_bf16 v[98:101], v[158:161], v[196:199], v[98:101]
	v_mfma_f32_16x16x32_bf16 v[86:89], v[150:153], v[208:211], v[86:89]
	v_mfma_f32_16x16x32_bf16 v[82:85], v[158:161], v[208:211], v[82:85]
	v_mfma_f32_16x16x32_bf16 v[70:73], v[150:153], v[216:219], v[70:73]
	v_mfma_f32_16x16x32_bf16 v[66:69], v[158:161], v[216:219], v[66:69]
	s_setprio 0
	s_barrier
; #define PG8_STAGE(bufoff, gbase, voff) do { _Pragma("unroll") for (int _i = 0; _i < 2; ++_i) \
;         __builtin_amdgcn_global_load_lds((const unsigned*)((const char*)(gbase) + (voff)[_i]), (PG8_LAS unsigned*)(lds + (bufoff) + ldsw + _i * 8192), 16, 0, 0); } while (0)
; #define PG8_LDA(dst, b, h) do { _Pragma("unroll") for (int m = 0; m < 4; ++m) _Pragma("unroll") for (int k = 0; k < 2; ++k) dst[m][k] = *(const PG8_LAS bf16x8*)(lds + PG8_SA(b, h) + aoff + m * 2048 + k * 1024); } while (0)
; #define PG8_MMA(ai, bj, At, Bt) do { __builtin_amdgcn_s_setprio(1); _Pragma("unroll") for (int m = 0; m < 4; ++m) _Pragma("unroll") for (int n = 0; n < 2; ++n) _Pragma("unroll") for (int k = 0; k < 2; ++k) \
;         acc[ai][bj][m][n] = __builtin_amdgcn_mfma_f32_16x16x32_bf16(Bt[n][k], At[m][k], acc[ai][bj][m][n], 0, 0, 0); __builtin_amdgcn_s_setprio(0); } while (0)
; #define PG8_WAIT_V(n) asm volatile("s_waitcnt vmcnt(" #n ")" ::: "memory")
; #define PG8_WAIT_L(n) asm volatile("s_waitcnt lgkmcnt(" #n ")" ::: "memory")
; #define PG8_BAR __builtin_amdgcn_s_barrier()
; #define PG8_SCHED __builtin_amdgcn_sched_barrier(0)
; template <class Epi, class Sched, bool ALIGN_EPI = false, bool SP2 = false>
; __device__ __forceinline__ void gemm_phase(PG8_LAS unsigned char* lds, const Gemm g, const Sched& S, const Epi& E, const int tid) {
;     ...
;         for (int t = 0; t < nt; t += 2) {
;             const bool last = (t == nt - 2);
;             const char* a1 = cA + (size_t)(t + 1) * kstep;
;             const char* a2 = last ? nA : cA + (size_t)(t + 2) * kstep; const char* b2 = last ? nB : cB + (size_t)(t + 2) * kstep;
;             const char* a3 = a2 + kstep; const char* b3 = b2 + kstep;
;     ...
;             PG8_LDA(At, 1, 1); PG8_STAGE(PG8_SB(1, 0), b3, voffB); PG8_STAGE(PG8_SB(1, 1), b3 + hstep, voffB); PG8_STAGE(PG8_SA(1, 0), a3, voffA);
;             PG8_WAIT_V(8); PG8_WAIT_L(0); PG8_BAR; PG8_MMA(1, 0, At, B0); PG8_MMA(1, 1, At, B1); PG8_BAR; PG8_SCHED;
	s_add_i32 s15, s15, s56
	v_lshl_add_u64 v[220:221], v[220:221], 0, s[30:31]
	s_mov_b32 m0, s15
	ds_read_b128 v[182:185], v206 offset:49152
	ds_read_b128 v[186:189], v206 offset:50176
	ds_read_b128 v[192:195], v206 offset:51200
	ds_read_b128 v[196:199], v206 offset:52224
	ds_read_b128 v[200:203], v206 offset:53248
	ds_read_b128 v[208:211], v206 offset:54272
	ds_read_b128 v[212:215], v206 offset:55296
	ds_read_b128 v[216:219], v206 offset:56320
	global_load_lds_dwordx4 v[220:221], off
	s_add_i32 m0, s15, 0x2000
	s_add_u32 s10, s10, 0x40080
	v_lshl_add_u64 v[220:221], v[222:223], 0, s[30:31]
	s_addc_u32 s11, s11, 0
	s_add_i32 s15, s77, s56
	global_load_lds_dwordx4 v[220:221], off
	v_lshl_add_u64 v[220:221], s[10:11], 0, v[164:165]
	s_mov_b32 m0, s15
	s_nop 0
	global_load_lds_dwordx4 v[220:221], off
	v_lshl_add_u64 v[220:221], s[10:11], 0, v[168:169]
	s_add_i32 m0, s15, 0x2000
	s_nop 0
	global_load_lds_dwordx4 v[220:221], off
	v_lshl_add_u64 v[220:221], v[224:225], 0, s[30:31]
	s_mov_b32 m0, s62
	s_nop 0
	global_load_lds_dwordx4 v[220:221], off
	v_lshl_add_u64 v[220:221], v[226:227], 0, s[30:31]
	s_mov_b32 m0, s63
	s_nop 0
	global_load_lds_dwordx4 v[220:221], off
	s_waitcnt vmcnt(8)
	s_waitcnt lgkmcnt(0)
	s_barrier
	s_setprio 1
	s_waitcnt lgkmcnt(0)
	v_mfma_f32_16x16x32_bf16 v[62:65], v[130:133], v[182:185], v[62:65]
	v_mfma_f32_16x16x32_bf16 v[58:61], v[138:141], v[182:185], v[58:61]
	v_mfma_f32_16x16x32_bf16 v[46:49], v[130:133], v[192:195], v[46:49]
	v_mfma_f32_16x16x32_bf16 v[42:45], v[138:141], v[192:195], v[42:45]
	v_mfma_f32_16x16x32_bf16 v[30:33], v[130:133], v[200:203], v[30:33]
	v_mfma_f32_16x16x32_bf16 v[26:29], v[138:141], v[200:203], v[26:29]
	v_mfma_f32_16x16x32_bf16 v[14:17], v[130:133], v[212:215], v[14:17]
	v_mfma_f32_16x16x32_bf16 v[10:13], v[138:141], v[212:215], v[10:13]
	v_mfma_f32_16x16x32_bf16 v[62:65], v[134:137], v[186:189], v[62:65]
	v_mfma_f32_16x16x32_bf16 v[58:61], v[142:145], v[186:189], v[58:61]
	v_mfma_f32_16x16x32_bf16 v[46:49], v[134:137], v[196:199], v[46:49]
	v_mfma_f32_16x16x32_bf16 v[42:45], v[142:145], v[196:199], v[42:45]
	v_mfma_f32_16x16x32_bf16 v[30:33], v[134:137], v[208:211], v[30:33]
	v_mfma_f32_16x16x32_bf16 v[26:29], v[142:145], v[208:211], v[26:29]
	v_mfma_f32_16x16x32_bf16 v[14:17], v[134:137], v[216:219], v[14:17]
	v_mfma_f32_16x16x32_bf16 v[10:13], v[142:145], v[216:219], v[10:13]
	s_setprio 0
	s_setprio 1
	v_mfma_f32_16x16x32_bf16 v[54:57], v[146:149], v[182:185], v[54:57]
	v_mfma_f32_16x16x32_bf16 v[50:53], v[154:157], v[182:185], v[50:53]
	v_mfma_f32_16x16x32_bf16 v[38:41], v[146:149], v[192:195], v[38:41]
	v_mfma_f32_16x16x32_bf16 v[34:37], v[154:157], v[192:195], v[34:37]
	v_mfma_f32_16x16x32_bf16 v[22:25], v[146:149], v[200:203], v[22:25]
	v_mfma_f32_16x16x32_bf16 v[18:21], v[154:157], v[200:203], v[18:21]
	v_mfma_f32_16x16x32_bf16 v[6:9], v[146:149], v[212:215], v[6:9]
	v_mfma_f32_16x16x32_bf16 v[2:5], v[154:157], v[212:215], v[2:5]
	v_mfma_f32_16x16x32_bf16 v[54:57], v[150:153], v[186:189], v[54:57]
	v_mfma_f32_16x16x32_bf16 v[50:53], v[158:161], v[186:189], v[50:53]
	v_mfma_f32_16x16x32_bf16 v[38:41], v[150:153], v[196:199], v[38:41]
	v_mfma_f32_16x16x32_bf16 v[34:37], v[158:161], v[196:199], v[34:37]
	v_mfma_f32_16x16x32_bf16 v[22:25], v[150:153], v[208:211], v[22:25]
	v_mfma_f32_16x16x32_bf16 v[18:21], v[158:161], v[208:211], v[18:21]
	v_mfma_f32_16x16x32_bf16 v[6:9], v[150:153], v[216:219], v[6:9]
	v_mfma_f32_16x16x32_bf16 v[2:5], v[158:161], v[216:219], v[2:5]
	s_setprio 0
	s_barrier
	s_add_i32 s76, s76, 2
	s_add_u32 s48, s48, 0x100
	s_addc_u32 s49, s49, 0
	s_add_u32 s8, s8, 0x100
	s_addc_u32 s9, s9, 0

; #define PG8_STAGE(bufoff, gbase, voff) do { _Pragma("unroll") for (int _i = 0; _i < 2; ++_i) \
;         __builtin_amdgcn_global_load_lds((const unsigned*)((const char*)(gbase) + (voff)[_i]), (PG8_LAS unsigned*)(lds + (bufoff) + ldsw + _i * 8192), 16, 0, 0); } while (0)
; #define PG8_LDA(dst, b, h) do { _Pragma("unroll") for (int m = 0; m < 4; ++m) _Pragma("unroll") for (int k = 0; k < 2; ++k) dst[m][k] = *(const PG8_LAS bf16x8*)(lds + PG8_SA(b, h) + aoff + m * 2048 + k * 1024); } while (0)
; #define PG8_LDB(dst, b, h) do { _Pragma("unroll") for (int n = 0; n < 2; ++n) _Pragma("unroll") for (int k = 0; k < 2; ++k) dst[n][k] = *(const PG8_LAS bf16x8*)(lds + PG8_SB(b, h) + boff + n * 2048 + k * 1024); } while (0)
; #define PG8_WAIT_V(n) asm volatile("s_waitcnt vmcnt(" #n ")" ::: "memory")
; #define PG8_WAIT_L(n) asm volatile("s_waitcnt lgkmcnt(" #n ")" ::: "memory")
; #define PG8_BAR __builtin_amdgcn_s_barrier()
; #define PG8_SCHED __builtin_amdgcn_sched_barrier(0)
; template <class Epi, class Sched, bool ALIGN_EPI = false, bool SP2 = false>
; __device__ __forceinline__ void gemm_phase(PG8_LAS unsigned char* lds, const Gemm g, const Sched& S, const Epi& E, const int tid) {
;     ...
;         const bool has_next = S.next(ui + 1, nxt);
;         const char* nA = has_next ? S.aptr(nxt) : cA; const char* nB = has_next ? S.bptr(nxt) : cB;
;         for (int t = 0; t < nt; t += 2) {
;             const bool last = (t == nt - 2);
;             const char* a1 = cA + (size_t)(t + 1) * kstep;
;             const char* a2 = last ? nA : cA + (size_t)(t + 2) * kstep; const char* b2 = last ? nB : cB + (size_t)(t + 2) * kstep;
;             const char* a3 = a2 + kstep; const char* b3 = b2 + kstep;
;             if (last && has_next) S.a_ready(nxt);
;             if constexpr (SP2) {
;             PG8_LDB(B0, 0, 0); PG8_LDB(B1, 0, 1); PG8_SCHED; PG8_LDA(At, 0, 0); PG8_STAGE(PG8_SA(1, 1), a1 + hstep, voffA);
;             PG8_WAIT_V(8); PG8_WAIT_L(0); PG8_BAR; PG8_MMA(0, 0, At, B0); PG8_MMA(0, 1, At, B1); PG8_BAR; PG8_SCHED;
;             PG8_LDA(At, 0, 1); PG8_STAGE(PG8_SB(0, 0), b2, voffB); PG8_STAGE(PG8_SB(0, 1), b2 + hstep, voffB); PG8_STAGE(PG8_SA(0, 0), a2, voffA);
;             PG8_WAIT_V(8); PG8_WAIT_L(0); PG8_BAR; PG8_MMA(1, 0, At, B0); PG8_MMA(1, 1, At, B1); PG8_BAR; PG8_SCHED;
.LBB0_5219:
	s_add_u32 s43, s8, 0x100
	s_addc_u32 s45, s9, 0
	s_mov_b32 s74, -2
	ds_read_b128 v[130:133], v204
	ds_read_b128 v[134:137], v204 offset:1024
	ds_read_b128 v[138:141], v204 offset:2048
	ds_read_b128 v[142:145], v204 offset:3072
	ds_read_b128 v[146:149], v205
	ds_read_b128 v[150:153], v205 offset:1024
	ds_read_b128 v[154:157], v205 offset:2048
	ds_read_b128 v[158:161], v205 offset:3072
	s_add_u32 s8, s6, 0x100
	s_addc_u32 s9, s7, 0
	s_cmp_eq_u32 s74, 40
	s_cselect_b32 s41, s1, s9
	s_cselect_b32 s40, s0, s8
	s_cselect_b32 s11, s39, s45
	s_cselect_b32 s10, s38, s43
	v_lshl_add_u64 v[220:221], s[6:7], 0, v[176:177]
	s_add_i32 m0, s53, 0xc000
	ds_read_b128 v[182:185], v206
	ds_read_b128 v[186:189], v206 offset:1024
	ds_read_b128 v[192:195], v206 offset:2048
	ds_read_b128 v[196:199], v206 offset:3072
	ds_read_b128 v[200:203], v206 offset:4096
	ds_read_b128 v[208:211], v206 offset:5120
	ds_read_b128 v[212:215], v206 offset:6144
	ds_read_b128 v[216:219], v206 offset:7168
	global_load_lds_dwordx4 v[220:221], off
	v_lshl_add_u64 v[220:221], s[6:7], 0, v[174:175]
	s_add_i32 m0, s53, 0xe000
	s_nop 0
	global_load_lds_dwordx4 v[220:221], off
	s_waitcnt vmcnt(8)
	s_waitcnt lgkmcnt(0)
	s_barrier
	s_setprio 1
	s_waitcnt lgkmcnt(0)
	v_mfma_f32_16x16x32_bf16 v[126:129], v[130:133], v[182:185], 0
	v_mfma_f32_16x16x32_bf16 v[122:125], v[138:141], v[182:185], 0
	v_mfma_f32_16x16x32_bf16 v[110:113], v[130:133], v[192:195], 0
	v_mfma_f32_16x16x32_bf16 v[106:109], v[138:141], v[192:195], 0
	v_mfma_f32_16x16x32_bf16 v[94:97], v[130:133], v[200:203], 0
	v_mfma_f32_16x16x32_bf16 v[90:93], v[138:141], v[200:203], 0
	v_mfma_f32_16x16x32_bf16 v[78:81], v[130:133], v[212:215], 0
	v_mfma_f32_16x16x32_bf16 v[74:77], v[138:141], v[212:215], 0
	v_mfma_f32_16x16x32_bf16 v[126:129], v[134:137], v[186:189], v[126:129]
	v_mfma_f32_16x16x32_bf16 v[122:125], v[142:145], v[186:189], v[122:125]
	v_mfma_f32_16x16x32_bf16 v[110:113], v[134:137], v[196:199], v[110:113]
	v_mfma_f32_16x16x32_bf16 v[106:109], v[142:145], v[196:199], v[106:109]
	v_mfma_f32_16x16x32_bf16 v[94:97], v[134:137], v[208:211], v[94:97]
	v_mfma_f32_16x16x32_bf16 v[90:93], v[142:145], v[208:211], v[90:93]
	v_mfma_f32_16x16x32_bf16 v[78:81], v[134:137], v[216:219], v[78:81]
	v_mfma_f32_16x16x32_bf16 v[74:77], v[142:145], v[216:219], v[74:77]
	s_setprio 0
	s_setprio 1
	v_mfma_f32_16x16x32_bf16 v[118:121], v[146:149], v[182:185], 0
	v_mfma_f32_16x16x32_bf16 v[114:117], v[154:157], v[182:185], 0
	v_mfma_f32_16x16x32_bf16 v[102:105], v[146:149], v[192:195], 0
	v_mfma_f32_16x16x32_bf16 v[98:101], v[154:157], v[192:195], 0
	v_mfma_f32_16x16x32_bf16 v[86:89], v[146:149], v[200:203], 0
	v_mfma_f32_16x16x32_bf16 v[82:85], v[154:157], v[200:203], 0
	v_mfma_f32_16x16x32_bf16 v[70:73], v[146:149], v[212:215], 0
	v_mfma_f32_16x16x32_bf16 v[66:69], v[154:157], v[212:215], 0
	v_mfma_f32_16x16x32_bf16 v[118:121], v[150:153], v[186:189], v[118:121]
	v_mfma_f32_16x16x32_bf16 v[114:117], v[158:161], v[186:189], v[114:117]
	v_mfma_f32_16x16x32_bf16 v[102:105], v[150:153], v[196:199], v[102:105]
	v_mfma_f32_16x16x32_bf16 v[98:101], v[158:161], v[196:199], v[98:101]
	v_mfma_f32_16x16x32_bf16 v[86:89], v[150:153], v[208:211], v[86:89]
	v_mfma_f32_16x16x32_bf16 v[82:85], v[158:161], v[208:211], v[82:85]
	v_mfma_f32_16x16x32_bf16 v[70:73], v[150:153], v[216:219], v[70:73]
	v_mfma_f32_16x16x32_bf16 v[66:69], v[158:161], v[216:219], v[66:69]
	s_setprio 0
	s_barrier
	s_add_i32 s6, s63, s52
	v_lshl_add_u64 v[220:221], s[10:11], 0, v[164:165]
	s_mov_b32 m0, s6
	ds_read_b128 v[182:185], v206 offset:16384
	ds_read_b128 v[186:189], v206 offset:17408
	ds_read_b128 v[192:195], v206 offset:18432
	ds_read_b128 v[196:199], v206 offset:19456
	ds_read_b128 v[200:203], v206 offset:20480
	ds_read_b128 v[208:211], v206 offset:21504
	ds_read_b128 v[212:215], v206 offset:22528
	ds_read_b128 v[216:219], v206 offset:23552
	global_load_lds_dwordx4 v[220:221], off
	s_add_i32 m0, s6, 0x2000
	s_add_u32 s6, s10, 0xb0000
	v_lshl_add_u64 v[222:223], s[10:11], 0, v[168:169]
	s_addc_u32 s7, s11, 0
	s_add_i32 s15, s64, s52
	global_load_lds_dwordx4 v[222:223], off
	v_lshl_add_u64 v[224:225], s[6:7], 0, v[164:165]
	s_mov_b32 m0, s15
	v_lshl_add_u64 v[226:227], s[40:41], 0, v[166:167]
	global_load_lds_dwordx4 v[224:225], off
	v_lshl_add_u64 v[224:225], s[6:7], 0, v[168:169]
	s_add_i32 m0, s15, 0x2000
	s_nop 0
	global_load_lds_dwordx4 v[224:225], off
	v_lshl_add_u64 v[224:225], s[40:41], 0, v[162:163]
	s_mov_b32 m0, s53
	s_nop 0
	global_load_lds_dwordx4 v[224:225], off
	s_mov_b32 m0, s54
	s_nop 0
	global_load_lds_dwordx4 v[226:227], off
	s_waitcnt vmcnt(8)
	s_waitcnt lgkmcnt(0)
	s_barrier
; #define PG8_STAGE(bufoff, gbase, voff) do { _Pragma("unroll") for (int _i = 0; _i < 2; ++_i) \
;         __builtin_amdgcn_global_load_lds((const unsigned*)((const char*)(gbase) + (voff)[_i]), (PG8_LAS unsigned*)(lds + (bufoff) + ldsw + _i * 8192), 16, 0, 0); } while (0)
; #define PG8_LDA(dst, b, h) do { _Pragma("unroll") for (int m = 0; m < 4; ++m) _Pragma("unroll") for (int k = 0; k < 2; ++k) dst[m][k] = *(const PG8_LAS bf16x8*)(lds + PG8_SA(b, h) + aoff + m * 2048 + k * 1024); } while (0)
; #define PG8_LDB(dst, b, h) do { _Pragma("unroll") for (int n = 0; n < 2; ++n) _Pragma("unroll") for (int k = 0; k < 2; ++k) dst[n][k] = *(const PG8_LAS bf16x8*)(lds + PG8_SB(b, h) + boff + n * 2048 + k * 1024); } while (0)
; #define PG8_MMA(ai, bj, At, Bt) do { __builtin_amdgcn_s_setprio(1); _Pragma("unroll") for (int m = 0; m < 4; ++m) _Pragma("unroll") for (int n = 0; n < 2; ++n) _Pragma("unroll") for (int k = 0; k < 2; ++k) \
;         acc[ai][bj][m][n] = __builtin_amdgcn_mfma_f32_16x16x32_bf16(Bt[n][k], At[m][k], acc[ai][bj][m][n], 0, 0, 0); __builtin_amdgcn_s_setprio(0); } while (0)
; #define PG8_WAIT_V(n) asm volatile("s_waitcnt vmcnt(" #n ")" ::: "memory")
; #define PG8_WAIT_L(n) asm volatile("s_waitcnt lgkmcnt(" #n ")" ::: "memory")
; #define PG8_BAR __builtin_amdgcn_s_barrier()
; #define PG8_SCHED __builtin_amdgcn_sched_barrier(0)
; template <class Epi, class Sched, bool ALIGN_EPI = false, bool SP2 = false>
; __device__ __forceinline__ void gemm_phase(PG8_LAS unsigned char* lds, const Gemm g, const Sched& S, const Epi& E, const int tid) {
;     ...
;             PG8_WAIT_V(8); PG8_WAIT_L(0); PG8_BAR; PG8_MMA(1, 0, At, B0); PG8_MMA(1, 1, At, B1); PG8_BAR; PG8_SCHED;
;             PG8_LDB(B0, 1, 0); PG8_LDB(B1, 1, 1); PG8_SCHED; PG8_LDA(At, 1, 0); PG8_STAGE(PG8_SA(0, 1), a2 + hstep, voffA);
;             PG8_WAIT_V(8); PG8_WAIT_L(0); PG8_BAR; PG8_MMA(0, 0, At, B0); PG8_MMA(0, 1, At, B1); PG8_BAR; PG8_SCHED;
	s_setprio 1
	s_waitcnt lgkmcnt(0)
	v_mfma_f32_16x16x32_bf16 v[62:65], v[130:133], v[182:185], 0
	v_mfma_f32_16x16x32_bf16 v[58:61], v[138:141], v[182:185], 0
	v_mfma_f32_16x16x32_bf16 v[46:49], v[130:133], v[192:195], 0
	v_mfma_f32_16x16x32_bf16 v[42:45], v[138:141], v[192:195], 0
	v_mfma_f32_16x16x32_bf16 v[30:33], v[130:133], v[200:203], 0
	v_mfma_f32_16x16x32_bf16 v[26:29], v[138:141], v[200:203], 0
	v_mfma_f32_16x16x32_bf16 v[14:17], v[130:133], v[212:215], 0
	v_mfma_f32_16x16x32_bf16 v[10:13], v[138:141], v[212:215], 0
	v_mfma_f32_16x16x32_bf16 v[62:65], v[134:137], v[186:189], v[62:65]
	v_mfma_f32_16x16x32_bf16 v[58:61], v[142:145], v[186:189], v[58:61]
	v_mfma_f32_16x16x32_bf16 v[46:49], v[134:137], v[196:199], v[46:49]
	v_mfma_f32_16x16x32_bf16 v[42:45], v[142:145], v[196:199], v[42:45]
	v_mfma_f32_16x16x32_bf16 v[30:33], v[134:137], v[208:211], v[30:33]
	v_mfma_f32_16x16x32_bf16 v[26:29], v[142:145], v[208:211], v[26:29]
	v_mfma_f32_16x16x32_bf16 v[14:17], v[134:137], v[216:219], v[14:17]
	v_mfma_f32_16x16x32_bf16 v[10:13], v[142:145], v[216:219], v[10:13]
	s_setprio 0
	s_setprio 1
	v_mfma_f32_16x16x32_bf16 v[54:57], v[146:149], v[182:185], 0
	v_mfma_f32_16x16x32_bf16 v[50:53], v[154:157], v[182:185], 0
	v_mfma_f32_16x16x32_bf16 v[38:41], v[146:149], v[192:195], 0
	v_mfma_f32_16x16x32_bf16 v[34:37], v[154:157], v[192:195], 0
	v_mfma_f32_16x16x32_bf16 v[22:25], v[146:149], v[200:203], 0
	v_mfma_f32_16x16x32_bf16 v[18:21], v[154:157], v[200:203], 0
	v_mfma_f32_16x16x32_bf16 v[6:9], v[146:149], v[212:215], 0
	v_mfma_f32_16x16x32_bf16 v[2:5], v[154:157], v[212:215], 0
	v_mfma_f32_16x16x32_bf16 v[54:57], v[150:153], v[186:189], v[54:57]
	v_mfma_f32_16x16x32_bf16 v[50:53], v[158:161], v[186:189], v[50:53]
	v_mfma_f32_16x16x32_bf16 v[38:41], v[150:153], v[196:199], v[38:41]
	v_mfma_f32_16x16x32_bf16 v[34:37], v[158:161], v[196:199], v[34:37]
	v_mfma_f32_16x16x32_bf16 v[22:25], v[150:153], v[208:211], v[22:25]
	v_mfma_f32_16x16x32_bf16 v[18:21], v[158:161], v[208:211], v[18:21]
	v_mfma_f32_16x16x32_bf16 v[6:9], v[150:153], v[216:219], v[6:9]
	v_mfma_f32_16x16x32_bf16 v[2:5], v[158:161], v[216:219], v[2:5]
	s_setprio 0
	s_barrier
	s_add_i32 s15, 0, 0x18000
	s_add_i32 s18, 0, 0x1c000
	v_add_u32_e32 v142, s15, v191
	v_add_u32_e32 v158, s18, v191
	ds_read_b128 v[130:133], v142
	ds_read_b128 v[134:137], v142 offset:1024
	ds_read_b128 v[138:141], v142 offset:2048
	ds_read_b128 v[142:145], v142 offset:3072
	ds_read_b128 v[146:149], v158
	ds_read_b128 v[150:153], v158 offset:1024
	ds_read_b128 v[154:157], v158 offset:2048
	ds_read_b128 v[158:161], v158 offset:3072
	s_add_u32 s6, s40, 0xb0000
	s_addc_u32 s7, s41, 0
	s_mov_b32 m0, s55
	v_lshl_add_u64 v[228:229], s[6:7], 0, v[162:163]
	ds_read_b128 v[182:185], v206 offset:32768
	ds_read_b128 v[186:189], v206 offset:33792
	ds_read_b128 v[192:195], v206 offset:34816
	ds_read_b128 v[196:199], v206 offset:35840
	ds_read_b128 v[200:203], v206 offset:36864
	ds_read_b128 v[208:211], v206 offset:37888
	ds_read_b128 v[212:215], v206 offset:38912
	ds_read_b128 v[216:219], v206 offset:39936
	global_load_lds_dwordx4 v[228:229], off
	v_lshl_add_u64 v[228:229], s[6:7], 0, v[166:167]
	s_mov_b32 m0, s56
	s_nop 0
	global_load_lds_dwordx4 v[228:229], off
	s_waitcnt vmcnt(8)
	s_waitcnt lgkmcnt(0)
	s_barrier
	s_setprio 1
	s_waitcnt lgkmcnt(0)
	v_mfma_f32_16x16x32_bf16 v[126:129], v[130:133], v[182:185], v[126:129]
	v_mfma_f32_16x16x32_bf16 v[122:125], v[138:141], v[182:185], v[122:125]
	v_mfma_f32_16x16x32_bf16 v[110:113], v[130:133], v[192:195], v[110:113]
	v_mfma_f32_16x16x32_bf16 v[106:109], v[138:141], v[192:195], v[106:109]
	v_mfma_f32_16x16x32_bf16 v[94:97], v[130:133], v[200:203], v[94:97]
	v_mfma_f32_16x16x32_bf16 v[90:93], v[138:141], v[200:203], v[90:93]
	v_mfma_f32_16x16x32_bf16 v[78:81], v[130:133], v[212:215], v[78:81]
	v_mfma_f32_16x16x32_bf16 v[74:77], v[138:141], v[212:215], v[74:77]
	v_mfma_f32_16x16x32_bf16 v[126:129], v[134:137], v[186:189], v[126:129]
	v_mfma_f32_16x16x32_bf16 v[122:125], v[142:145], v[186:189], v[122:125]
	v_mfma_f32_16x16x32_bf16 v[110:113], v[134:137], v[196:199], v[110:113]
	v_mfma_f32_16x16x32_bf16 v[106:109], v[142:145], v[196:199], v[106:109]
	v_mfma_f32_16x16x32_bf16 v[94:97], v[134:137], v[208:211], v[94:97]
	v_mfma_f32_16x16x32_bf16 v[90:93], v[142:145], v[208:211], v[90:93]
	v_mfma_f32_16x16x32_bf16 v[78:81], v[134:137], v[216:219], v[78:81]
	v_mfma_f32_16x16x32_bf16 v[74:77], v[142:145], v[216:219], v[74:77]
	s_setprio 0
	s_setprio 1
	v_mfma_f32_16x16x32_bf16 v[118:121], v[146:149], v[182:185], v[118:121]
	v_mfma_f32_16x16x32_bf16 v[114:117], v[154:157], v[182:185], v[114:117]
	v_mfma_f32_16x16x32_bf16 v[102:105], v[146:149], v[192:195], v[102:105]
	v_mfma_f32_16x16x32_bf16 v[98:101], v[154:157], v[192:195], v[98:101]
	v_mfma_f32_16x16x32_bf16 v[86:89], v[146:149], v[200:203], v[86:89]
	v_mfma_f32_16x16x32_bf16 v[82:85], v[154:157], v[200:203], v[82:85]
	v_mfma_f32_16x16x32_bf16 v[70:73], v[146:149], v[212:215], v[70:73]
	v_mfma_f32_16x16x32_bf16 v[66:69], v[154:157], v[212:215], v[66:69]
	v_mfma_f32_16x16x32_bf16 v[118:121], v[150:153], v[186:189], v[118:121]
	v_mfma_f32_16x16x32_bf16 v[114:117], v[158:161], v[186:189], v[114:117]
	v_mfma_f32_16x16x32_bf16 v[102:105], v[150:153], v[196:199], v[102:105]
	v_mfma_f32_16x16x32_bf16 v[98:101], v[158:161], v[196:199], v[98:101]
	v_mfma_f32_16x16x32_bf16 v[86:89], v[150:153], v[208:211], v[86:89]
	v_mfma_f32_16x16x32_bf16 v[82:85], v[158:161], v[208:211], v[82:85]
	v_mfma_f32_16x16x32_bf16 v[70:73], v[150:153], v[216:219], v[70:73]
	v_mfma_f32_16x16x32_bf16 v[66:69], v[158:161], v[216:219], v[66:69]
	s_setprio 0
	s_barrier
; #define PG8_STAGE(bufoff, gbase, voff) do { _Pragma("unroll") for (int _i = 0; _i < 2; ++_i) \
;         __builtin_amdgcn_global_load_lds((const unsigned*)((const char*)(gbase) + (voff)[_i]), (PG8_LAS unsigned*)(lds + (bufoff) + ldsw + _i * 8192), 16, 0, 0); } while (0)
; #define PG8_LDA(dst, b, h) do { _Pragma("unroll") for (int m = 0; m < 4; ++m) _Pragma("unroll") for (int k = 0; k < 2; ++k) dst[m][k] = *(const PG8_LAS bf16x8*)(lds + PG8_SA(b, h) + aoff + m * 2048 + k * 1024); } while (0)
; #define PG8_MMA(ai, bj, At, Bt) do { __builtin_amdgcn_s_setprio(1); _Pragma("unroll") for (int m = 0; m < 4; ++m) _Pragma("unroll") for (int n = 0; n < 2; ++n) _Pragma("unroll") for (int k = 0; k < 2; ++k) \
;         acc[ai][bj][m][n] = __builtin_amdgcn_mfma_f32_16x16x32_bf16(Bt[n][k], At[m][k], acc[ai][bj][m][n], 0, 0, 0); __builtin_amdgcn_s_setprio(0); } while (0)
; #define PG8_WAIT_V(n) asm volatile("s_waitcnt vmcnt(" #n ")" ::: "memory")
; #define PG8_WAIT_L(n) asm volatile("s_waitcnt lgkmcnt(" #n ")" ::: "memory")
; #define PG8_BAR __builtin_amdgcn_s_barrier()
; #define PG8_SCHED __builtin_amdgcn_sched_barrier(0)
; template <class Epi, class Sched, bool ALIGN_EPI = false, bool SP2 = false>
; __device__ __forceinline__ void gemm_phase(PG8_LAS unsigned char* lds, const Gemm g, const Sched& S, const Epi& E, const int tid) {
;     ...
;         for (int t = 0; t < nt; t += 2) {
;             const bool last = (t == nt - 2);
;             const char* a1 = cA + (size_t)(t + 1) * kstep;
;             const char* a2 = last ? nA : cA + (size_t)(t + 2) * kstep; const char* b2 = last ? nB : cB + (size_t)(t + 2) * kstep;
;             const char* a3 = a2 + kstep; const char* b3 = b2 + kstep;
;     ...
;             PG8_LDA(At, 1, 1); PG8_STAGE(PG8_SB(1, 0), b3, voffB); PG8_STAGE(PG8_SB(1, 1), b3 + hstep, voffB); PG8_STAGE(PG8_SA(1, 0), a3, voffA);
;             PG8_WAIT_V(8); PG8_WAIT_L(0); PG8_BAR; PG8_MMA(1, 0, At, B0); PG8_MMA(1, 1, At, B1); PG8_BAR; PG8_SCHED;
	s_add_i32 s6, s15, s52
	v_lshl_add_u64 v[220:221], v[220:221], 0, s[34:35]
	s_mov_b32 m0, s6
	ds_read_b128 v[182:185], v206 offset:49152
	ds_read_b128 v[186:189], v206 offset:50176
	ds_read_b128 v[192:195], v206 offset:51200
	ds_read_b128 v[196:199], v206 offset:52224
	ds_read_b128 v[200:203], v206 offset:53248
	ds_read_b128 v[208:211], v206 offset:54272
	ds_read_b128 v[212:215], v206 offset:55296
	ds_read_b128 v[216:219], v206 offset:56320
	global_load_lds_dwordx4 v[220:221], off
	s_add_i32 m0, s6, 0x2000
	s_add_u32 s6, s10, 0xb0080
	v_lshl_add_u64 v[220:221], v[222:223], 0, s[34:35]
	s_addc_u32 s7, s11, 0
	s_add_i32 s10, s18, s52
	global_load_lds_dwordx4 v[220:221], off
	v_lshl_add_u64 v[220:221], s[6:7], 0, v[164:165]
	s_mov_b32 m0, s10
	s_nop 0
	global_load_lds_dwordx4 v[220:221], off
	v_lshl_add_u64 v[220:221], s[6:7], 0, v[168:169]
	s_add_i32 m0, s10, 0x2000
	s_nop 0
	global_load_lds_dwordx4 v[220:221], off
	v_lshl_add_u64 v[220:221], v[224:225], 0, s[34:35]
	s_mov_b32 m0, s58
	s_nop 0
	global_load_lds_dwordx4 v[220:221], off
	v_lshl_add_u64 v[220:221], v[226:227], 0, s[34:35]
	s_mov_b32 m0, s59
	s_nop 0
	global_load_lds_dwordx4 v[220:221], off
	s_waitcnt vmcnt(8)
	s_waitcnt lgkmcnt(0)
	s_barrier
	s_setprio 1
	s_waitcnt lgkmcnt(0)
	v_mfma_f32_16x16x32_bf16 v[62:65], v[130:133], v[182:185], v[62:65]
	v_mfma_f32_16x16x32_bf16 v[58:61], v[138:141], v[182:185], v[58:61]
	v_mfma_f32_16x16x32_bf16 v[46:49], v[130:133], v[192:195], v[46:49]
	v_mfma_f32_16x16x32_bf16 v[42:45], v[138:141], v[192:195], v[42:45]
	v_mfma_f32_16x16x32_bf16 v[30:33], v[130:133], v[200:203], v[30:33]
	v_mfma_f32_16x16x32_bf16 v[26:29], v[138:141], v[200:203], v[26:29]
	v_mfma_f32_16x16x32_bf16 v[14:17], v[130:133], v[212:215], v[14:17]
	v_mfma_f32_16x16x32_bf16 v[10:13], v[138:141], v[212:215], v[10:13]
	v_mfma_f32_16x16x32_bf16 v[62:65], v[134:137], v[186:189], v[62:65]
	v_mfma_f32_16x16x32_bf16 v[58:61], v[142:145], v[186:189], v[58:61]
	v_mfma_f32_16x16x32_bf16 v[46:49], v[134:137], v[196:199], v[46:49]
	v_mfma_f32_16x16x32_bf16 v[42:45], v[142:145], v[196:199], v[42:45]
	v_mfma_f32_16x16x32_bf16 v[30:33], v[134:137], v[208:211], v[30:33]
	v_mfma_f32_16x16x32_bf16 v[26:29], v[142:145], v[208:211], v[26:29]
	v_mfma_f32_16x16x32_bf16 v[14:17], v[134:137], v[216:219], v[14:17]
	v_mfma_f32_16x16x32_bf16 v[10:13], v[142:145], v[216:219], v[10:13]
	s_setprio 0
	s_setprio 1
	v_mfma_f32_16x16x32_bf16 v[54:57], v[146:149], v[182:185], v[54:57]
	v_mfma_f32_16x16x32_bf16 v[50:53], v[154:157], v[182:185], v[50:53]
	v_mfma_f32_16x16x32_bf16 v[38:41], v[146:149], v[192:195], v[38:41]
	v_mfma_f32_16x16x32_bf16 v[34:37], v[154:157], v[192:195], v[34:37]
	v_mfma_f32_16x16x32_bf16 v[22:25], v[146:149], v[200:203], v[22:25]
	v_mfma_f32_16x16x32_bf16 v[18:21], v[154:157], v[200:203], v[18:21]
	v_mfma_f32_16x16x32_bf16 v[6:9], v[146:149], v[212:215], v[6:9]
	v_mfma_f32_16x16x32_bf16 v[2:5], v[154:157], v[212:215], v[2:5]
	v_mfma_f32_16x16x32_bf16 v[54:57], v[150:153], v[186:189], v[54:57]
	v_mfma_f32_16x16x32_bf16 v[50:53], v[158:161], v[186:189], v[50:53]
	v_mfma_f32_16x16x32_bf16 v[38:41], v[150:153], v[196:199], v[38:41]
	v_mfma_f32_16x16x32_bf16 v[34:37], v[158:161], v[196:199], v[34:37]
	v_mfma_f32_16x16x32_bf16 v[22:25], v[150:153], v[208:211], v[22:25]
	v_mfma_f32_16x16x32_bf16 v[18:21], v[158:161], v[208:211], v[18:21]
	v_mfma_f32_16x16x32_bf16 v[6:9], v[150:153], v[216:219], v[6:9]
	v_mfma_f32_16x16x32_bf16 v[2:5], v[158:161], v[216:219], v[2:5]
	s_setprio 0
	s_barrier
	s_add_i32 s74, s74, 2
	s_add_u32 s43, s43, 0x100
	s_addc_u32 s45, s45, 0
	s_mov_b64 s[6:7], s[8:9]

; #define PG8_STAGE(bufoff, gbase, voff) do { _Pragma("unroll") for (int _i = 0; _i < 2; ++_i) \
;         __builtin_amdgcn_global_load_lds((const unsigned*)((const char*)(gbase) + (voff)[_i]), (PG8_LAS unsigned*)(lds + (bufoff) + ldsw + _i * 8192), 16, 0, 0); } while (0)
; #define PG8_LDA(dst, b, h) do { _Pragma("unroll") for (int m = 0; m < 4; ++m) _Pragma("unroll") for (int k = 0; k < 2; ++k) dst[m][k] = *(const PG8_LAS bf16x8*)(lds + PG8_SA(b, h) + aoff + m * 2048 + k * 1024); } while (0)
; #define PG8_LDB(dst, b, h) do { _Pragma("unroll") for (int n = 0; n < 2; ++n) _Pragma("unroll") for (int k = 0; k < 2; ++k) dst[n][k] = *(const PG8_LAS bf16x8*)(lds + PG8_SB(b, h) + boff + n * 2048 + k * 1024); } while (0)
; #define PG8_WAIT_V(n) asm volatile("s_waitcnt vmcnt(" #n ")" ::: "memory")
; #define PG8_WAIT_L(n) asm volatile("s_waitcnt lgkmcnt(" #n ")" ::: "memory")
; #define PG8_BAR __builtin_amdgcn_s_barrier()
; #define PG8_SCHED __builtin_amdgcn_sched_barrier(0)
; template <class Epi, class Sched, bool ALIGN_EPI = false, bool SP2 = false>
; __device__ __forceinline__ void gemm_phase(PG8_LAS unsigned char* lds, const Gemm g, const Sched& S, const Epi& E, const int tid) {
;     ...
;         const bool has_next = S.next(ui + 1, nxt);
;         const char* nA = has_next ? S.aptr(nxt) : cA; const char* nB = has_next ? S.bptr(nxt) : cB;
;         for (int t = 0; t < nt; t += 2) {
;             const bool last = (t == nt - 2);
;             const char* a1 = cA + (size_t)(t + 1) * kstep;
;             const char* a2 = last ? nA : cA + (size_t)(t + 2) * kstep; const char* b2 = last ? nB : cB + (size_t)(t + 2) * kstep;
;             const char* a3 = a2 + kstep; const char* b3 = b2 + kstep;
;             if (last && has_next) S.a_ready(nxt);
;             if constexpr (SP2) {
;             PG8_LDB(B0, 0, 0); PG8_LDB(B1, 0, 1); PG8_SCHED; PG8_LDA(At, 0, 0); PG8_STAGE(PG8_SA(1, 1), a1 + hstep, voffA);
;             PG8_WAIT_V(8); PG8_WAIT_L(0); PG8_BAR; PG8_MMA(0, 0, At, B0); PG8_MMA(0, 1, At, B1); PG8_BAR; PG8_SCHED;
;             PG8_LDA(At, 0, 1); PG8_STAGE(PG8_SB(0, 0), b2, voffB); PG8_STAGE(PG8_SB(0, 1), b2 + hstep, voffB); PG8_STAGE(PG8_SA(0, 0), a2, voffA);
;             PG8_WAIT_V(8); PG8_WAIT_L(0); PG8_BAR; PG8_MMA(1, 0, At, B0); PG8_MMA(1, 1, At, B1); PG8_BAR; PG8_SCHED;
.LBB0_5776:
	s_add_u32 s5, s54, 0x100
	s_addc_u32 s47, s55, 0
	s_add_u32 s54, s56, 0x40080
	s_addc_u32 s55, s57, 0
	s_mov_b32 s49, -2
	ds_read_b128 v[130:133], v171
	ds_read_b128 v[134:137], v171 offset:1024
	ds_read_b128 v[160:163], v171 offset:2048
	ds_read_b128 v[164:167], v171 offset:3072
	ds_read_b128 v[176:179], v172
	ds_read_b128 v[180:183], v172 offset:1024
	ds_read_b128 v[184:187], v172 offset:2048
	ds_read_b128 v[192:195], v172 offset:3072
	s_add_u32 s15, s54, 0xfffc0080
	s_addc_u32 s18, s55, -1
	s_cmp_eq_u32 s49, 12
	s_cselect_b32 s59, s1, s18
	s_cselect_b32 s58, s0, s15
	s_cselect_b32 s57, s51, s47
	s_cselect_b32 s56, s50, s5
	v_lshl_add_u64 v[168:169], s[54:55], 0, v[154:155]
	s_add_i32 m0, s64, 0xc000
	ds_read_b128 v[196:199], v173
	ds_read_b128 v[200:203], v173 offset:1024
	ds_read_b128 v[204:207], v173 offset:2048
	ds_read_b128 v[208:211], v173 offset:3072
	ds_read_b128 v[212:215], v173 offset:4096
	ds_read_b128 v[216:219], v173 offset:5120
	ds_read_b128 v[220:223], v173 offset:6144
	ds_read_b128 v[224:227], v173 offset:7168
	global_load_lds_dwordx4 v[168:169], off
	v_lshl_add_u64 v[168:169], s[54:55], 0, v[152:153]
	s_add_i32 m0, s64, 0xe000
	s_nop 0
	global_load_lds_dwordx4 v[168:169], off
	s_waitcnt vmcnt(8)
	s_waitcnt lgkmcnt(0)
	s_barrier
	s_setprio 1
	s_waitcnt lgkmcnt(0)
	v_mfma_f32_16x16x32_bf16 v[126:129], v[130:133], v[196:199], 0
	v_mfma_f32_16x16x32_bf16 v[122:125], v[160:163], v[196:199], 0
	v_mfma_f32_16x16x32_bf16 v[110:113], v[130:133], v[204:207], 0
	v_mfma_f32_16x16x32_bf16 v[106:109], v[160:163], v[204:207], 0
	v_mfma_f32_16x16x32_bf16 v[94:97], v[130:133], v[212:215], 0
	v_mfma_f32_16x16x32_bf16 v[90:93], v[160:163], v[212:215], 0
	v_mfma_f32_16x16x32_bf16 v[78:81], v[130:133], v[220:223], 0
	v_mfma_f32_16x16x32_bf16 v[74:77], v[160:163], v[220:223], 0
	v_mfma_f32_16x16x32_bf16 v[126:129], v[134:137], v[200:203], v[126:129]
	v_mfma_f32_16x16x32_bf16 v[122:125], v[164:167], v[200:203], v[122:125]
	v_mfma_f32_16x16x32_bf16 v[110:113], v[134:137], v[208:211], v[110:113]
	v_mfma_f32_16x16x32_bf16 v[106:109], v[164:167], v[208:211], v[106:109]
	v_mfma_f32_16x16x32_bf16 v[94:97], v[134:137], v[216:219], v[94:97]
	v_mfma_f32_16x16x32_bf16 v[90:93], v[164:167], v[216:219], v[90:93]
	v_mfma_f32_16x16x32_bf16 v[78:81], v[134:137], v[224:227], v[78:81]
	v_mfma_f32_16x16x32_bf16 v[74:77], v[164:167], v[224:227], v[74:77]
	s_setprio 0
	s_setprio 1
	v_mfma_f32_16x16x32_bf16 v[118:121], v[176:179], v[196:199], 0
	v_mfma_f32_16x16x32_bf16 v[114:117], v[184:187], v[196:199], 0
	v_mfma_f32_16x16x32_bf16 v[102:105], v[176:179], v[204:207], 0
	v_mfma_f32_16x16x32_bf16 v[98:101], v[184:187], v[204:207], 0
	v_mfma_f32_16x16x32_bf16 v[86:89], v[176:179], v[212:215], 0
	v_mfma_f32_16x16x32_bf16 v[82:85], v[184:187], v[212:215], 0
	v_mfma_f32_16x16x32_bf16 v[70:73], v[176:179], v[220:223], 0
	v_mfma_f32_16x16x32_bf16 v[66:69], v[184:187], v[220:223], 0
	v_mfma_f32_16x16x32_bf16 v[118:121], v[180:183], v[200:203], v[118:121]
	v_mfma_f32_16x16x32_bf16 v[114:117], v[192:195], v[200:203], v[114:117]
	v_mfma_f32_16x16x32_bf16 v[102:105], v[180:183], v[208:211], v[102:105]
	v_mfma_f32_16x16x32_bf16 v[98:101], v[192:195], v[208:211], v[98:101]
	v_mfma_f32_16x16x32_bf16 v[86:89], v[180:183], v[216:219], v[86:89]
	v_mfma_f32_16x16x32_bf16 v[82:85], v[192:195], v[216:219], v[82:85]
	v_mfma_f32_16x16x32_bf16 v[70:73], v[180:183], v[224:227], v[70:73]
	v_mfma_f32_16x16x32_bf16 v[66:69], v[192:195], v[224:227], v[66:69]
	s_setprio 0
	s_barrier
	s_add_i32 s15, s83, s63
	v_lshl_add_u64 v[168:169], s[56:57], 0, v[140:141]
	s_mov_b32 m0, s15
	ds_read_b128 v[196:199], v173 offset:16384
	ds_read_b128 v[200:203], v173 offset:17408
	ds_read_b128 v[204:207], v173 offset:18432
	ds_read_b128 v[208:211], v173 offset:19456
	ds_read_b128 v[212:215], v173 offset:20480
	ds_read_b128 v[216:219], v173 offset:21504
	ds_read_b128 v[220:223], v173 offset:22528
	ds_read_b128 v[224:227], v173 offset:23552
	global_load_lds_dwordx4 v[168:169], off
	s_add_i32 m0, s15, 0x2000
	s_add_u32 s18, s56, 0x40000
	v_lshl_add_u64 v[188:189], s[56:57], 0, v[144:145]
	s_addc_u32 s19, s57, 0
	s_add_i32 s15, s84, s63
	global_load_lds_dwordx4 v[188:189], off
	v_lshl_add_u64 v[228:229], s[18:19], 0, v[140:141]
	s_mov_b32 m0, s15
	v_lshl_add_u64 v[230:231], s[58:59], 0, v[142:143]
	global_load_lds_dwordx4 v[228:229], off
	v_lshl_add_u64 v[228:229], s[18:19], 0, v[144:145]
	s_add_i32 m0, s15, 0x2000
	s_nop 0
	global_load_lds_dwordx4 v[228:229], off
	v_lshl_add_u64 v[228:229], s[58:59], 0, v[138:139]
	s_mov_b32 m0, s64
	s_nop 0
	global_load_lds_dwordx4 v[228:229], off
	s_mov_b32 m0, s65
	s_nop 0
	global_load_lds_dwordx4 v[230:231], off
	s_waitcnt vmcnt(8)
	s_waitcnt lgkmcnt(0)
	s_barrier
; #define PG8_STAGE(bufoff, gbase, voff) do { _Pragma("unroll") for (int _i = 0; _i < 2; ++_i) \
;         __builtin_amdgcn_global_load_lds((const unsigned*)((const char*)(gbase) + (voff)[_i]), (PG8_LAS unsigned*)(lds + (bufoff) + ldsw + _i * 8192), 16, 0, 0); } while (0)
; #define PG8_LDA(dst, b, h) do { _Pragma("unroll") for (int m = 0; m < 4; ++m) _Pragma("unroll") for (int k = 0; k < 2; ++k) dst[m][k] = *(const PG8_LAS bf16x8*)(lds + PG8_SA(b, h) + aoff + m * 2048 + k * 1024); } while (0)
; #define PG8_LDB(dst, b, h) do { _Pragma("unroll") for (int n = 0; n < 2; ++n) _Pragma("unroll") for (int k = 0; k < 2; ++k) dst[n][k] = *(const PG8_LAS bf16x8*)(lds + PG8_SB(b, h) + boff + n * 2048 + k * 1024); } while (0)
; #define PG8_MMA(ai, bj, At, Bt) do { __builtin_amdgcn_s_setprio(1); _Pragma("unroll") for (int m = 0; m < 4; ++m) _Pragma("unroll") for (int n = 0; n < 2; ++n) _Pragma("unroll") for (int k = 0; k < 2; ++k) \
;         acc[ai][bj][m][n] = __builtin_amdgcn_mfma_f32_16x16x32_bf16(Bt[n][k], At[m][k], acc[ai][bj][m][n], 0, 0, 0); __builtin_amdgcn_s_setprio(0); } while (0)
; #define PG8_WAIT_V(n) asm volatile("s_waitcnt vmcnt(" #n ")" ::: "memory")
; #define PG8_WAIT_L(n) asm volatile("s_waitcnt lgkmcnt(" #n ")" ::: "memory")
; #define PG8_BAR __builtin_amdgcn_s_barrier()
; #define PG8_SCHED __builtin_amdgcn_sched_barrier(0)
; template <class Epi, class Sched, bool ALIGN_EPI = false, bool SP2 = false>
; __device__ __forceinline__ void gemm_phase(PG8_LAS unsigned char* lds, const Gemm g, const Sched& S, const Epi& E, const int tid) {
;     ...
;             PG8_WAIT_V(8); PG8_WAIT_L(0); PG8_BAR; PG8_MMA(1, 0, At, B0); PG8_MMA(1, 1, At, B1); PG8_BAR; PG8_SCHED;
;             PG8_LDB(B0, 1, 0); PG8_LDB(B1, 1, 1); PG8_SCHED; PG8_LDA(At, 1, 0); PG8_STAGE(PG8_SA(0, 1), a2 + hstep, voffA);
;             PG8_WAIT_V(8); PG8_WAIT_L(0); PG8_BAR; PG8_MMA(0, 0, At, B0); PG8_MMA(0, 1, At, B1); PG8_BAR; PG8_SCHED;
	s_setprio 1
	s_waitcnt lgkmcnt(0)
	v_mfma_f32_16x16x32_bf16 v[62:65], v[130:133], v[196:199], 0
	v_mfma_f32_16x16x32_bf16 v[58:61], v[160:163], v[196:199], 0
	v_mfma_f32_16x16x32_bf16 v[46:49], v[130:133], v[204:207], 0
	v_mfma_f32_16x16x32_bf16 v[42:45], v[160:163], v[204:207], 0
	v_mfma_f32_16x16x32_bf16 v[30:33], v[130:133], v[212:215], 0
	v_mfma_f32_16x16x32_bf16 v[26:29], v[160:163], v[212:215], 0
	v_mfma_f32_16x16x32_bf16 v[14:17], v[130:133], v[220:223], 0
	v_mfma_f32_16x16x32_bf16 v[10:13], v[160:163], v[220:223], 0
	v_mfma_f32_16x16x32_bf16 v[62:65], v[134:137], v[200:203], v[62:65]
	v_mfma_f32_16x16x32_bf16 v[58:61], v[164:167], v[200:203], v[58:61]
	v_mfma_f32_16x16x32_bf16 v[46:49], v[134:137], v[208:211], v[46:49]
	v_mfma_f32_16x16x32_bf16 v[42:45], v[164:167], v[208:211], v[42:45]
	v_mfma_f32_16x16x32_bf16 v[30:33], v[134:137], v[216:219], v[30:33]
	v_mfma_f32_16x16x32_bf16 v[26:29], v[164:167], v[216:219], v[26:29]
	v_mfma_f32_16x16x32_bf16 v[14:17], v[134:137], v[224:227], v[14:17]
	v_mfma_f32_16x16x32_bf16 v[10:13], v[164:167], v[224:227], v[10:13]
	s_setprio 0
	s_setprio 1
	v_mfma_f32_16x16x32_bf16 v[54:57], v[176:179], v[196:199], 0
	v_mfma_f32_16x16x32_bf16 v[50:53], v[184:187], v[196:199], 0
	v_mfma_f32_16x16x32_bf16 v[38:41], v[176:179], v[204:207], 0
	v_mfma_f32_16x16x32_bf16 v[34:37], v[184:187], v[204:207], 0
	v_mfma_f32_16x16x32_bf16 v[22:25], v[176:179], v[212:215], 0
	v_mfma_f32_16x16x32_bf16 v[18:21], v[184:187], v[212:215], 0
	v_mfma_f32_16x16x32_bf16 v[6:9], v[176:179], v[220:223], 0
	v_mfma_f32_16x16x32_bf16 v[2:5], v[184:187], v[220:223], 0
	v_mfma_f32_16x16x32_bf16 v[54:57], v[180:183], v[200:203], v[54:57]
	v_mfma_f32_16x16x32_bf16 v[50:53], v[192:195], v[200:203], v[50:53]
	v_mfma_f32_16x16x32_bf16 v[38:41], v[180:183], v[208:211], v[38:41]
	v_mfma_f32_16x16x32_bf16 v[34:37], v[192:195], v[208:211], v[34:37]
	v_mfma_f32_16x16x32_bf16 v[22:25], v[180:183], v[216:219], v[22:25]
	v_mfma_f32_16x16x32_bf16 v[18:21], v[192:195], v[216:219], v[18:21]
	v_mfma_f32_16x16x32_bf16 v[6:9], v[180:183], v[224:227], v[6:9]
	v_mfma_f32_16x16x32_bf16 v[2:5], v[192:195], v[224:227], v[2:5]
	s_setprio 0
	s_barrier
	s_add_i32 s15, 0, 0x18000
	s_add_i32 s60, 0, 0x1c000
	v_add_u32_e32 v164, s15, v170
	v_add_u32_e32 v175, s60, v170
	ds_read_b128 v[130:133], v164
	ds_read_b128 v[134:137], v164 offset:1024
	ds_read_b128 v[160:163], v164 offset:2048
	ds_read_b128 v[164:167], v164 offset:3072
	ds_read_b128 v[176:179], v175
	ds_read_b128 v[180:183], v175 offset:1024
	ds_read_b128 v[184:187], v175 offset:2048
	ds_read_b128 v[192:195], v175 offset:3072
	s_add_u32 s18, s58, 0x40000
	s_addc_u32 s19, s59, 0
	s_mov_b32 m0, s66
	v_lshl_add_u64 v[232:233], s[18:19], 0, v[138:139]
	ds_read_b128 v[196:199], v173 offset:32768
	ds_read_b128 v[200:203], v173 offset:33792
	ds_read_b128 v[204:207], v173 offset:34816
	ds_read_b128 v[208:211], v173 offset:35840
	ds_read_b128 v[212:215], v173 offset:36864
	ds_read_b128 v[216:219], v173 offset:37888
	ds_read_b128 v[220:223], v173 offset:38912
	ds_read_b128 v[224:227], v173 offset:39936
	global_load_lds_dwordx4 v[232:233], off
	v_lshl_add_u64 v[232:233], s[18:19], 0, v[142:143]
	s_mov_b32 m0, s67
	s_nop 0
	global_load_lds_dwordx4 v[232:233], off
	s_waitcnt vmcnt(8)
	s_waitcnt lgkmcnt(0)
	s_barrier
	s_setprio 1
	s_waitcnt lgkmcnt(0)
	v_mfma_f32_16x16x32_bf16 v[126:129], v[130:133], v[196:199], v[126:129]
	v_mfma_f32_16x16x32_bf16 v[122:125], v[160:163], v[196:199], v[122:125]
	v_mfma_f32_16x16x32_bf16 v[110:113], v[130:133], v[204:207], v[110:113]
	v_mfma_f32_16x16x32_bf16 v[106:109], v[160:163], v[204:207], v[106:109]
	v_mfma_f32_16x16x32_bf16 v[94:97], v[130:133], v[212:215], v[94:97]
	v_mfma_f32_16x16x32_bf16 v[90:93], v[160:163], v[212:215], v[90:93]
	v_mfma_f32_16x16x32_bf16 v[78:81], v[130:133], v[220:223], v[78:81]
	v_mfma_f32_16x16x32_bf16 v[74:77], v[160:163], v[220:223], v[74:77]
	v_mfma_f32_16x16x32_bf16 v[126:129], v[134:137], v[200:203], v[126:129]
	v_mfma_f32_16x16x32_bf16 v[122:125], v[164:167], v[200:203], v[122:125]
	v_mfma_f32_16x16x32_bf16 v[110:113], v[134:137], v[208:211], v[110:113]
	v_mfma_f32_16x16x32_bf16 v[106:109], v[164:167], v[208:211], v[106:109]
	v_mfma_f32_16x16x32_bf16 v[94:97], v[134:137], v[216:219], v[94:97]
	v_mfma_f32_16x16x32_bf16 v[90:93], v[164:167], v[216:219], v[90:93]
	v_mfma_f32_16x16x32_bf16 v[78:81], v[134:137], v[224:227], v[78:81]
	v_mfma_f32_16x16x32_bf16 v[74:77], v[164:167], v[224:227], v[74:77]
	s_setprio 0
	s_setprio 1
	v_mfma_f32_16x16x32_bf16 v[118:121], v[176:179], v[196:199], v[118:121]
	v_mfma_f32_16x16x32_bf16 v[114:117], v[184:187], v[196:199], v[114:117]
	v_mfma_f32_16x16x32_bf16 v[102:105], v[176:179], v[204:207], v[102:105]
	v_mfma_f32_16x16x32_bf16 v[98:101], v[184:187], v[204:207], v[98:101]
	v_mfma_f32_16x16x32_bf16 v[86:89], v[176:179], v[212:215], v[86:89]
	v_mfma_f32_16x16x32_bf16 v[82:85], v[184:187], v[212:215], v[82:85]
	v_mfma_f32_16x16x32_bf16 v[70:73], v[176:179], v[220:223], v[70:73]
	v_mfma_f32_16x16x32_bf16 v[66:69], v[184:187], v[220:223], v[66:69]
	v_mfma_f32_16x16x32_bf16 v[118:121], v[180:183], v[200:203], v[118:121]
	v_mfma_f32_16x16x32_bf16 v[114:117], v[192:195], v[200:203], v[114:117]
	v_mfma_f32_16x16x32_bf16 v[102:105], v[180:183], v[208:211], v[102:105]
	v_mfma_f32_16x16x32_bf16 v[98:101], v[192:195], v[208:211], v[98:101]
	v_mfma_f32_16x16x32_bf16 v[86:89], v[180:183], v[216:219], v[86:89]
	v_mfma_f32_16x16x32_bf16 v[82:85], v[192:195], v[216:219], v[82:85]
	v_mfma_f32_16x16x32_bf16 v[70:73], v[180:183], v[224:227], v[70:73]
	v_mfma_f32_16x16x32_bf16 v[66:69], v[192:195], v[224:227], v[66:69]
	s_setprio 0
	s_barrier
; #define PG8_STAGE(bufoff, gbase, voff) do { _Pragma("unroll") for (int _i = 0; _i < 2; ++_i) \
;         __builtin_amdgcn_global_load_lds((const unsigned*)((const char*)(gbase) + (voff)[_i]), (PG8_LAS unsigned*)(lds + (bufoff) + ldsw + _i * 8192), 16, 0, 0); } while (0)
; #define PG8_LDA(dst, b, h) do { _Pragma("unroll") for (int m = 0; m < 4; ++m) _Pragma("unroll") for (int k = 0; k < 2; ++k) dst[m][k] = *(const PG8_LAS bf16x8*)(lds + PG8_SA(b, h) + aoff + m * 2048 + k * 1024); } while (0)
; #define PG8_MMA(ai, bj, At, Bt) do { __builtin_amdgcn_s_setprio(1); _Pragma("unroll") for (int m = 0; m < 4; ++m) _Pragma("unroll") for (int n = 0; n < 2; ++n) _Pragma("unroll") for (int k = 0; k < 2; ++k) \
;         acc[ai][bj][m][n] = __builtin_amdgcn_mfma_f32_16x16x32_bf16(Bt[n][k], At[m][k], acc[ai][bj][m][n], 0, 0, 0); __builtin_amdgcn_s_setprio(0); } while (0)
; #define PG8_WAIT_V(n) asm volatile("s_waitcnt vmcnt(" #n ")" ::: "memory")
; #define PG8_WAIT_L(n) asm volatile("s_waitcnt lgkmcnt(" #n ")" ::: "memory")
; #define PG8_BAR __builtin_amdgcn_s_barrier()
; #define PG8_SCHED __builtin_amdgcn_sched_barrier(0)
; template <class Epi, class Sched, bool ALIGN_EPI = false, bool SP2 = false>
; __device__ __forceinline__ void gemm_phase(PG8_LAS unsigned char* lds, const Gemm g, const Sched& S, const Epi& E, const int tid) {
;     ...
;         for (int t = 0; t < nt; t += 2) {
;             const bool last = (t == nt - 2);
;             const char* a1 = cA + (size_t)(t + 1) * kstep;
;             const char* a2 = last ? nA : cA + (size_t)(t + 2) * kstep; const char* b2 = last ? nB : cB + (size_t)(t + 2) * kstep;
;             const char* a3 = a2 + kstep; const char* b3 = b2 + kstep;
;     ...
;             PG8_LDA(At, 1, 1); PG8_STAGE(PG8_SB(1, 0), b3, voffB); PG8_STAGE(PG8_SB(1, 1), b3 + hstep, voffB); PG8_STAGE(PG8_SA(1, 0), a3, voffA);
;             PG8_WAIT_V(8); PG8_WAIT_L(0); PG8_BAR; PG8_MMA(1, 0, At, B0); PG8_MMA(1, 1, At, B1); PG8_BAR; PG8_SCHED;
	s_add_i32 s15, s15, s63
	v_lshl_add_u64 v[168:169], v[168:169], 0, s[42:43]
	s_mov_b32 m0, s15
	ds_read_b128 v[196:199], v173 offset:49152
	ds_read_b128 v[200:203], v173 offset:50176
	ds_read_b128 v[204:207], v173 offset:51200
	ds_read_b128 v[208:211], v173 offset:52224
	ds_read_b128 v[212:215], v173 offset:53248
	ds_read_b128 v[216:219], v173 offset:54272
	ds_read_b128 v[220:223], v173 offset:55296
	ds_read_b128 v[224:227], v173 offset:56320
	global_load_lds_dwordx4 v[168:169], off
	s_add_i32 m0, s15, 0x2000
	s_add_u32 s18, s56, 0x40080
	v_lshl_add_u64 v[168:169], v[188:189], 0, s[42:43]
	s_addc_u32 s19, s57, 0
	s_add_i32 s15, s60, s63
	global_load_lds_dwordx4 v[168:169], off
	v_lshl_add_u64 v[168:169], s[18:19], 0, v[140:141]
	s_mov_b32 m0, s15
	s_nop 0
	global_load_lds_dwordx4 v[168:169], off
	v_lshl_add_u64 v[168:169], s[18:19], 0, v[144:145]
	s_add_i32 m0, s15, 0x2000
	s_nop 0
	global_load_lds_dwordx4 v[168:169], off
	v_lshl_add_u64 v[168:169], v[228:229], 0, s[42:43]
	s_mov_b32 m0, s74
	s_nop 0
	global_load_lds_dwordx4 v[168:169], off
	v_lshl_add_u64 v[168:169], v[230:231], 0, s[42:43]
	s_mov_b32 m0, s75
	s_nop 0
	global_load_lds_dwordx4 v[168:169], off
	s_waitcnt vmcnt(8)
	s_waitcnt lgkmcnt(0)
	s_barrier
	s_setprio 1
	s_waitcnt lgkmcnt(0)
	v_mfma_f32_16x16x32_bf16 v[62:65], v[130:133], v[196:199], v[62:65]
	v_mfma_f32_16x16x32_bf16 v[58:61], v[160:163], v[196:199], v[58:61]
	v_mfma_f32_16x16x32_bf16 v[46:49], v[130:133], v[204:207], v[46:49]
	v_mfma_f32_16x16x32_bf16 v[42:45], v[160:163], v[204:207], v[42:45]
	v_mfma_f32_16x16x32_bf16 v[30:33], v[130:133], v[212:215], v[30:33]
	v_mfma_f32_16x16x32_bf16 v[26:29], v[160:163], v[212:215], v[26:29]
	v_mfma_f32_16x16x32_bf16 v[14:17], v[130:133], v[220:223], v[14:17]
	v_mfma_f32_16x16x32_bf16 v[10:13], v[160:163], v[220:223], v[10:13]
	v_mfma_f32_16x16x32_bf16 v[62:65], v[134:137], v[200:203], v[62:65]
	v_mfma_f32_16x16x32_bf16 v[58:61], v[164:167], v[200:203], v[58:61]
	v_mfma_f32_16x16x32_bf16 v[46:49], v[134:137], v[208:211], v[46:49]
	v_mfma_f32_16x16x32_bf16 v[42:45], v[164:167], v[208:211], v[42:45]
	v_mfma_f32_16x16x32_bf16 v[30:33], v[134:137], v[216:219], v[30:33]
	v_mfma_f32_16x16x32_bf16 v[26:29], v[164:167], v[216:219], v[26:29]
	v_mfma_f32_16x16x32_bf16 v[14:17], v[134:137], v[224:227], v[14:17]
	v_mfma_f32_16x16x32_bf16 v[10:13], v[164:167], v[224:227], v[10:13]
	s_setprio 0
	s_setprio 1
	v_mfma_f32_16x16x32_bf16 v[54:57], v[176:179], v[196:199], v[54:57]
	v_mfma_f32_16x16x32_bf16 v[50:53], v[184:187], v[196:199], v[50:53]
	v_mfma_f32_16x16x32_bf16 v[38:41], v[176:179], v[204:207], v[38:41]
	v_mfma_f32_16x16x32_bf16 v[34:37], v[184:187], v[204:207], v[34:37]
	v_mfma_f32_16x16x32_bf16 v[22:25], v[176:179], v[212:215], v[22:25]
	v_mfma_f32_16x16x32_bf16 v[18:21], v[184:187], v[212:215], v[18:21]
	v_mfma_f32_16x16x32_bf16 v[6:9], v[176:179], v[220:223], v[6:9]
	v_mfma_f32_16x16x32_bf16 v[2:5], v[184:187], v[220:223], v[2:5]
	v_mfma_f32_16x16x32_bf16 v[54:57], v[180:183], v[200:203], v[54:57]
	v_mfma_f32_16x16x32_bf16 v[50:53], v[192:195], v[200:203], v[50:53]
	v_mfma_f32_16x16x32_bf16 v[38:41], v[180:183], v[208:211], v[38:41]
	v_mfma_f32_16x16x32_bf16 v[34:37], v[192:195], v[208:211], v[34:37]
	v_mfma_f32_16x16x32_bf16 v[22:25], v[180:183], v[216:219], v[22:25]
	v_mfma_f32_16x16x32_bf16 v[18:21], v[192:195], v[216:219], v[18:21]
	v_mfma_f32_16x16x32_bf16 v[6:9], v[180:183], v[224:227], v[6:9]
	v_mfma_f32_16x16x32_bf16 v[2:5], v[192:195], v[224:227], v[2:5]
	s_setprio 0
	s_barrier
	s_add_i32 s49, s49, 2
	s_add_u32 s5, s5, 0x100
	s_addc_u32 s47, s47, 0
	s_add_u32 s54, s54, 0x100
	s_addc_u32 s55, s55, 0
